# PV3 deferred across barrier; setprio for waves 4-7 in diff-attn; 4 MFMAs ahead of K-loop barrier; rstd computed once per 4 lanes in SwiGLU/ProjGate epilogues (ds_bpermute share), ssq loads batched
# speedup vs baseline: 1.0609x; 1.0152x over previous
; #define PG8_STAGE(bufoff, gbase, voff) do { _Pragma("unroll") for (int _i = 0; _i < 2; ++_i) \
;         __builtin_amdgcn_global_load_lds((const unsigned*)((const char*)(gbase) + (voff)[_i]), (PG8_LAS unsigned*)(lds + (bufoff) + ldsw + _i * 8192), 16, 0, 0); } while (0)
; #define PG8_LDA(dst, b, h) do { _Pragma("unroll") for (int m = 0; m < 4; ++m) _Pragma("unroll") for (int k = 0; k < 2; ++k) dst[m][k] = *(const PG8_LAS bf16x8*)(lds + PG8_SA(b, h) + aoff + m * 2048 + k * 1024); } while (0)
; #define PG8_LDB(dst, b, h) do { _Pragma("unroll") for (int n = 0; n < 2; ++n) _Pragma("unroll") for (int k = 0; k < 2; ++k) dst[n][k] = *(const PG8_LAS bf16x8*)(lds + PG8_SB(b, h) + boff + n * 2048 + k * 1024); } while (0)
; #define PG8_MMA(ai, bj, At, Bt) do { __builtin_amdgcn_s_setprio(1); _Pragma("unroll") for (int m = 0; m < 4; ++m) _Pragma("unroll") for (int n = 0; n < 2; ++n) _Pragma("unroll") for (int k = 0; k < 2; ++k) \
;         acc[ai][bj][m][n] = __builtin_amdgcn_mfma_f32_16x16x32_bf16(Bt[n][k], At[m][k], acc[ai][bj][m][n], 0, 0, 0); __builtin_amdgcn_s_setprio(0); } while (0)
; #define PG8_WAIT_V(n) asm volatile("s_waitcnt vmcnt(" #n ")" ::: "memory")
; template <class Epi, class Sched, bool ALIGN_EPI = false, bool SP2 = false>
; __device__ __forceinline__ void gemm_phase(PG8_LAS unsigned char* lds, const Gemm g, const Sched& S, const Epi& E) {
;     ...
;             PG8_LDB(B0, 0, 0); PG8_LDB(B1, 0, 1); PG8_SCHED; PG8_LDA(At, 0, 0); PG8_STAGE(PG8_SA(1, 1), a1 + hstep, voffA);
;             PG8_WAIT_V(8); PG8_WAIT_L(0); PG8_BAR; PG8_MMA(0, 0, At, B0); PG8_MMA(0, 1, At, B1); PG8_BAR; PG8_SCHED;
;             PG8_LDA(At, 0, 1); PG8_STAGE(PG8_SB(0, 0), b2, voffB); PG8_STAGE(PG8_SB(0, 1), b2 + hstep, voffB); PG8_STAGE(PG8_SA(0, 0), a2, voffA);
;             PG8_WAIT_V(8); PG8_WAIT_L(0); PG8_BAR; PG8_MMA(1, 0, At, B0); PG8_MMA(1, 1, At, B1); PG8_BAR; PG8_SCHED;
;             PG8_LDB(B0, 1, 0); PG8_LDB(B1, 1, 1); PG8_SCHED; PG8_LDA(At, 1, 0); PG8_STAGE(PG8_SA(0, 1), a2 + hstep, voffA);
;             PG8_WAIT_V(8); PG8_WAIT_L(0); PG8_BAR; PG8_MMA(0, 0, At, B0); PG8_MMA(0, 1, At, B1); PG8_BAR; PG8_SCHED;
;             PG8_LDA(At, 1, 1); PG8_STAGE(PG8_SB(1, 0), b3, voffB); PG8_STAGE(PG8_SB(1, 1), b3 + hstep, voffB); PG8_STAGE(PG8_SA(1, 0), a3, voffA);
;             PG8_WAIT_V(8); PG8_WAIT_L(0); PG8_BAR; PG8_MMA(1, 0, At, B0); PG8_MMA(1, 1, At, B1); PG8_BAR; PG8_SCHED;
.LBB0_49:
	s_add_u32 s40, s0, 0xfffe0080
	s_addc_u32 s41, s1, -1
	s_add_i32 s65, 0, 0x10000
	s_cmp_eq_u32 s64, 4
	s_cselect_b32 s43, s19, s41
	s_cselect_b32 s42, s60, s40
	s_cselect_b32 s41, s17, s63
	s_cselect_b32 s40, s61, s62
	s_add_i32 s68, 0, 0x14000
	v_add_u32_e32 v144, s65, v248
	v_add_u32_e32 v160, s68, v248
	ds_read_b128 v[132:135], v144
	ds_read_b128 v[136:139], v144 offset:1024
	ds_read_b128 v[140:143], v144 offset:2048
	ds_read_b128 v[144:147], v144 offset:3072
	ds_read_b128 v[148:151], v160
	ds_read_b128 v[152:155], v160 offset:1024
	ds_read_b128 v[156:159], v160 offset:2048
	ds_read_b128 v[160:163], v160 offset:3072
	v_lshl_add_u64 v[210:211], s[0:1], 0, v[206:207]
	s_add_i32 m0, s51, 0xc000
	ds_read_b128 v[164:167], v250
	ds_read_b128 v[168:171], v250 offset:1024
	ds_read_b128 v[172:175], v250 offset:2048
	ds_read_b128 v[176:179], v250 offset:3072
	ds_read_b128 v[180:183], v250 offset:4096
	ds_read_b128 v[184:187], v250 offset:5120
	ds_read_b128 v[188:191], v250 offset:6144
	ds_read_b128 v[192:195], v250 offset:7168
	global_load_lds_dwordx4 v[210:211], off
	v_lshl_add_u64 v[210:211], s[0:1], 0, v[208:209]
	s_add_i32 m0, s51, 0xe000
	s_nop 0
	global_load_lds_dwordx4 v[210:211], off
	s_waitcnt vmcnt(8)
	s_waitcnt lgkmcnt(0)
	v_mfma_f32_16x16x32_bf16 v[128:131], v[132:135], v[164:167], v[128:131]
	v_mfma_f32_16x16x32_bf16 v[124:127], v[140:143], v[164:167], v[124:127]
	v_mfma_f32_16x16x32_bf16 v[116:119], v[132:135], v[172:175], v[116:119]
	v_mfma_f32_16x16x32_bf16 v[108:111], v[140:143], v[172:175], v[108:111]
	s_barrier
	s_setprio 1
	v_mfma_f32_16x16x32_bf16 v[100:103], v[132:135], v[180:183], v[100:103]
	v_mfma_f32_16x16x32_bf16 v[92:95], v[140:143], v[180:183], v[92:95]
	v_mfma_f32_16x16x32_bf16 v[84:87], v[132:135], v[188:191], v[84:87]
	v_mfma_f32_16x16x32_bf16 v[76:79], v[140:143], v[188:191], v[76:79]
	v_mfma_f32_16x16x32_bf16 v[128:131], v[136:139], v[168:171], v[128:131]
	v_mfma_f32_16x16x32_bf16 v[124:127], v[144:147], v[168:171], v[124:127]
	v_mfma_f32_16x16x32_bf16 v[116:119], v[136:139], v[176:179], v[116:119]
	v_mfma_f32_16x16x32_bf16 v[108:111], v[144:147], v[176:179], v[108:111]
	v_mfma_f32_16x16x32_bf16 v[100:103], v[136:139], v[184:187], v[100:103]
	v_mfma_f32_16x16x32_bf16 v[92:95], v[144:147], v[184:187], v[92:95]
	v_mfma_f32_16x16x32_bf16 v[84:87], v[136:139], v[192:195], v[84:87]
	v_mfma_f32_16x16x32_bf16 v[76:79], v[144:147], v[192:195], v[76:79]
	s_setprio 0
	s_setprio 1
	v_mfma_f32_16x16x32_bf16 v[120:123], v[148:151], v[164:167], v[120:123]
	v_mfma_f32_16x16x32_bf16 v[112:115], v[156:159], v[164:167], v[112:115]
	v_mfma_f32_16x16x32_bf16 v[104:107], v[148:151], v[172:175], v[104:107]
	v_mfma_f32_16x16x32_bf16 v[96:99], v[156:159], v[172:175], v[96:99]
	v_mfma_f32_16x16x32_bf16 v[88:91], v[148:151], v[180:183], v[88:91]
	v_mfma_f32_16x16x32_bf16 v[80:83], v[156:159], v[180:183], v[80:83]
	v_mfma_f32_16x16x32_bf16 v[72:75], v[148:151], v[188:191], v[72:75]
	v_mfma_f32_16x16x32_bf16 v[68:71], v[156:159], v[188:191], v[68:71]
	v_mfma_f32_16x16x32_bf16 v[120:123], v[152:155], v[168:171], v[120:123]
	v_mfma_f32_16x16x32_bf16 v[112:115], v[160:163], v[168:171], v[112:115]
	v_mfma_f32_16x16x32_bf16 v[104:107], v[152:155], v[176:179], v[104:107]
	v_mfma_f32_16x16x32_bf16 v[96:99], v[160:163], v[176:179], v[96:99]
	v_mfma_f32_16x16x32_bf16 v[88:91], v[152:155], v[184:187], v[88:91]
	v_mfma_f32_16x16x32_bf16 v[80:83], v[160:163], v[184:187], v[80:83]
	v_mfma_f32_16x16x32_bf16 v[72:75], v[152:155], v[192:195], v[72:75]
	v_mfma_f32_16x16x32_bf16 v[68:71], v[160:163], v[192:195], v[68:71]
	s_setprio 0
	s_barrier
	s_add_i32 s65, s65, s50
	v_lshl_add_u64 v[210:211], s[40:41], 0, v[196:197]
	s_mov_b32 m0, s65
	ds_read_b128 v[164:167], v250 offset:16384
	ds_read_b128 v[168:171], v250 offset:17408
	ds_read_b128 v[172:175], v250 offset:18432
	ds_read_b128 v[176:179], v250 offset:19456
	ds_read_b128 v[180:183], v250 offset:20480
	ds_read_b128 v[184:187], v250 offset:21504
	ds_read_b128 v[188:191], v250 offset:22528
	ds_read_b128 v[192:195], v250 offset:23552
	global_load_lds_dwordx4 v[210:211], off
	s_add_i32 m0, s65, 0x2000
	s_add_u32 s66, s40, 0x20000
	v_lshl_add_u64 v[212:213], s[40:41], 0, v[32:33]
	s_addc_u32 s67, s41, 0
	s_add_i32 s65, s68, s50
	global_load_lds_dwordx4 v[212:213], off
	v_lshl_add_u64 v[214:215], s[66:67], 0, v[196:197]
	s_mov_b32 m0, s65
	v_lshl_add_u64 v[216:217], s[42:43], 0, v[202:203]
	global_load_lds_dwordx4 v[214:215], off
	v_lshl_add_u64 v[214:215], s[66:67], 0, v[32:33]
	s_add_i32 m0, s65, 0x2000
	s_nop 0
	global_load_lds_dwordx4 v[214:215], off
	v_lshl_add_u64 v[214:215], s[42:43], 0, v[204:205]
	s_mov_b32 m0, s51
	s_nop 0
	global_load_lds_dwordx4 v[214:215], off
	s_mov_b32 m0, s52
	s_nop 0
	global_load_lds_dwordx4 v[216:217], off
	s_waitcnt vmcnt(8)
	s_waitcnt lgkmcnt(0)
	v_mfma_f32_16x16x32_bf16 v[64:67], v[132:135], v[164:167], v[64:67]
	v_mfma_f32_16x16x32_bf16 v[60:63], v[140:143], v[164:167], v[60:63]
	v_mfma_f32_16x16x32_bf16 v[52:55], v[132:135], v[172:175], v[52:55]
	v_mfma_f32_16x16x32_bf16 v[44:47], v[140:143], v[172:175], v[44:47]
	s_barrier
; #define PG8_STAGE(bufoff, gbase, voff) do { _Pragma("unroll") for (int _i = 0; _i < 2; ++_i) \
;         __builtin_amdgcn_global_load_lds((const unsigned*)((const char*)(gbase) + (voff)[_i]), (PG8_LAS unsigned*)(lds + (bufoff) + ldsw + _i * 8192), 16, 0, 0); } while (0)
; #define PG8_LDA(dst, b, h) do { _Pragma("unroll") for (int m = 0; m < 4; ++m) _Pragma("unroll") for (int k = 0; k < 2; ++k) dst[m][k] = *(const PG8_LAS bf16x8*)(lds + PG8_SA(b, h) + aoff + m * 2048 + k * 1024); } while (0)
; #define PG8_LDB(dst, b, h) do { _Pragma("unroll") for (int n = 0; n < 2; ++n) _Pragma("unroll") for (int k = 0; k < 2; ++k) dst[n][k] = *(const PG8_LAS bf16x8*)(lds + PG8_SB(b, h) + boff + n * 2048 + k * 1024); } while (0)
; #define PG8_MMA(ai, bj, At, Bt) do { __builtin_amdgcn_s_setprio(1); _Pragma("unroll") for (int m = 0; m < 4; ++m) _Pragma("unroll") for (int n = 0; n < 2; ++n) _Pragma("unroll") for (int k = 0; k < 2; ++k) \
;         acc[ai][bj][m][n] = __builtin_amdgcn_mfma_f32_16x16x32_bf16(Bt[n][k], At[m][k], acc[ai][bj][m][n], 0, 0, 0); __builtin_amdgcn_s_setprio(0); } while (0)
; #define PG8_WAIT_V(n) asm volatile("s_waitcnt vmcnt(" #n ")" ::: "memory")
; #define PG8_WAIT_L(n) asm volatile("s_waitcnt lgkmcnt(" #n ")" ::: "memory")
; #define PG8_BAR __builtin_amdgcn_s_barrier()
; #define PG8_SCHED __builtin_amdgcn_sched_barrier(0)
; template <class Epi, class Sched, bool ALIGN_EPI = false, bool SP2 = false>
; __device__ __forceinline__ void gemm_phase(PG8_LAS unsigned char* lds, const Gemm g, const Sched& S, const Epi& E) {
;     ...
;             PG8_WAIT_V(8); PG8_WAIT_L(0); PG8_BAR; PG8_MMA(1, 0, At, B0); PG8_MMA(1, 1, At, B1); PG8_BAR; PG8_SCHED;
;             PG8_LDB(B0, 1, 0); PG8_LDB(B1, 1, 1); PG8_SCHED; PG8_LDA(At, 1, 0); PG8_STAGE(PG8_SA(0, 1), a2 + hstep, voffA);
;             PG8_WAIT_V(8); PG8_WAIT_L(0); PG8_BAR; PG8_MMA(0, 0, At, B0); PG8_MMA(0, 1, At, B1); PG8_BAR; PG8_SCHED;
;             PG8_LDA(At, 1, 1); PG8_STAGE(PG8_SB(1, 0), b3, voffB); PG8_STAGE(PG8_SB(1, 1), b3 + hstep, voffB); PG8_STAGE(PG8_SA(1, 0), a3, voffA);
	s_setprio 1
	v_mfma_f32_16x16x32_bf16 v[36:39], v[132:135], v[180:183], v[36:39]
	v_mfma_f32_16x16x32_bf16 v[24:27], v[140:143], v[180:183], v[24:27]
	v_mfma_f32_16x16x32_bf16 v[16:19], v[132:135], v[188:191], v[16:19]
	v_mfma_f32_16x16x32_bf16 v[8:11], v[140:143], v[188:191], v[8:11]
	v_mfma_f32_16x16x32_bf16 v[64:67], v[136:139], v[168:171], v[64:67]
	v_mfma_f32_16x16x32_bf16 v[60:63], v[144:147], v[168:171], v[60:63]
	v_mfma_f32_16x16x32_bf16 v[52:55], v[136:139], v[176:179], v[52:55]
	v_mfma_f32_16x16x32_bf16 v[44:47], v[144:147], v[176:179], v[44:47]
	v_mfma_f32_16x16x32_bf16 v[36:39], v[136:139], v[184:187], v[36:39]
	v_mfma_f32_16x16x32_bf16 v[24:27], v[144:147], v[184:187], v[24:27]
	v_mfma_f32_16x16x32_bf16 v[16:19], v[136:139], v[192:195], v[16:19]
	v_mfma_f32_16x16x32_bf16 v[8:11], v[144:147], v[192:195], v[8:11]
	s_setprio 0
	s_setprio 1
	v_mfma_f32_16x16x32_bf16 v[56:59], v[148:151], v[164:167], v[56:59]
	v_mfma_f32_16x16x32_bf16 v[48:51], v[156:159], v[164:167], v[48:51]
	v_mfma_f32_16x16x32_bf16 v[40:43], v[148:151], v[172:175], v[40:43]
	v_mfma_f32_16x16x32_bf16 v[28:31], v[156:159], v[172:175], v[28:31]
	v_mfma_f32_16x16x32_bf16 v[20:23], v[148:151], v[180:183], v[20:23]
	v_mfma_f32_16x16x32_bf16 v[12:15], v[156:159], v[180:183], v[12:15]
	v_mfma_f32_16x16x32_bf16 v[4:7], v[148:151], v[188:191], v[4:7]
	v_mfma_f32_16x16x32_bf16 v[0:3], v[156:159], v[188:191], v[0:3]
	v_mfma_f32_16x16x32_bf16 v[56:59], v[152:155], v[168:171], v[56:59]
	v_mfma_f32_16x16x32_bf16 v[48:51], v[160:163], v[168:171], v[48:51]
	v_mfma_f32_16x16x32_bf16 v[40:43], v[152:155], v[176:179], v[40:43]
	v_mfma_f32_16x16x32_bf16 v[28:31], v[160:163], v[176:179], v[28:31]
	v_mfma_f32_16x16x32_bf16 v[20:23], v[152:155], v[184:187], v[20:23]
	v_mfma_f32_16x16x32_bf16 v[12:15], v[160:163], v[184:187], v[12:15]
	v_mfma_f32_16x16x32_bf16 v[4:7], v[152:155], v[192:195], v[4:7]
	v_mfma_f32_16x16x32_bf16 v[0:3], v[160:163], v[192:195], v[0:3]
	s_setprio 0
	s_barrier
	s_add_i32 s65, 0, 0x18000
	s_add_i32 s66, 0, 0x1c000
	v_add_u32_e32 v144, s65, v248
	v_add_u32_e32 v160, s66, v248
	ds_read_b128 v[132:135], v144
	ds_read_b128 v[136:139], v144 offset:1024
	ds_read_b128 v[140:143], v144 offset:2048
	ds_read_b128 v[144:147], v144 offset:3072
	ds_read_b128 v[148:151], v160
	ds_read_b128 v[152:155], v160 offset:1024
	ds_read_b128 v[156:159], v160 offset:2048
	ds_read_b128 v[160:163], v160 offset:3072
	s_add_u32 s42, s42, 0x20000
	s_addc_u32 s43, s43, 0
	s_mov_b32 m0, s53
	v_lshl_add_u64 v[218:219], s[42:43], 0, v[204:205]
	ds_read_b128 v[164:167], v250 offset:32768
	ds_read_b128 v[168:171], v250 offset:33792
	ds_read_b128 v[172:175], v250 offset:34816
	ds_read_b128 v[176:179], v250 offset:35840
	ds_read_b128 v[180:183], v250 offset:36864
	ds_read_b128 v[184:187], v250 offset:37888
	ds_read_b128 v[188:191], v250 offset:38912
	ds_read_b128 v[192:195], v250 offset:39936
	global_load_lds_dwordx4 v[218:219], off
	v_lshl_add_u64 v[218:219], s[42:43], 0, v[202:203]
	s_mov_b32 m0, s54
	s_nop 0
	global_load_lds_dwordx4 v[218:219], off
	s_waitcnt vmcnt(8)
	s_waitcnt lgkmcnt(0)
	v_mfma_f32_16x16x32_bf16 v[128:131], v[132:135], v[164:167], v[128:131]
	v_mfma_f32_16x16x32_bf16 v[124:127], v[140:143], v[164:167], v[124:127]
	v_mfma_f32_16x16x32_bf16 v[116:119], v[132:135], v[172:175], v[116:119]
	v_mfma_f32_16x16x32_bf16 v[108:111], v[140:143], v[172:175], v[108:111]
	s_barrier
	s_setprio 1
	v_mfma_f32_16x16x32_bf16 v[100:103], v[132:135], v[180:183], v[100:103]
	v_mfma_f32_16x16x32_bf16 v[92:95], v[140:143], v[180:183], v[92:95]
	v_mfma_f32_16x16x32_bf16 v[84:87], v[132:135], v[188:191], v[84:87]
	v_mfma_f32_16x16x32_bf16 v[76:79], v[140:143], v[188:191], v[76:79]
	v_mfma_f32_16x16x32_bf16 v[128:131], v[136:139], v[168:171], v[128:131]
	v_mfma_f32_16x16x32_bf16 v[124:127], v[144:147], v[168:171], v[124:127]
	v_mfma_f32_16x16x32_bf16 v[116:119], v[136:139], v[176:179], v[116:119]
	v_mfma_f32_16x16x32_bf16 v[108:111], v[144:147], v[176:179], v[108:111]
	v_mfma_f32_16x16x32_bf16 v[100:103], v[136:139], v[184:187], v[100:103]
	v_mfma_f32_16x16x32_bf16 v[92:95], v[144:147], v[184:187], v[92:95]
	v_mfma_f32_16x16x32_bf16 v[84:87], v[136:139], v[192:195], v[84:87]
	v_mfma_f32_16x16x32_bf16 v[76:79], v[144:147], v[192:195], v[76:79]
	s_setprio 0
	s_setprio 1
	v_mfma_f32_16x16x32_bf16 v[120:123], v[148:151], v[164:167], v[120:123]
	v_mfma_f32_16x16x32_bf16 v[112:115], v[156:159], v[164:167], v[112:115]
	v_mfma_f32_16x16x32_bf16 v[104:107], v[148:151], v[172:175], v[104:107]
	v_mfma_f32_16x16x32_bf16 v[96:99], v[156:159], v[172:175], v[96:99]
	v_mfma_f32_16x16x32_bf16 v[88:91], v[148:151], v[180:183], v[88:91]
	v_mfma_f32_16x16x32_bf16 v[80:83], v[156:159], v[180:183], v[80:83]
	v_mfma_f32_16x16x32_bf16 v[72:75], v[148:151], v[188:191], v[72:75]
	v_mfma_f32_16x16x32_bf16 v[68:71], v[156:159], v[188:191], v[68:71]
	v_mfma_f32_16x16x32_bf16 v[120:123], v[152:155], v[168:171], v[120:123]
	v_mfma_f32_16x16x32_bf16 v[112:115], v[160:163], v[168:171], v[112:115]
	v_mfma_f32_16x16x32_bf16 v[104:107], v[152:155], v[176:179], v[104:107]
	v_mfma_f32_16x16x32_bf16 v[96:99], v[160:163], v[176:179], v[96:99]
	v_mfma_f32_16x16x32_bf16 v[88:91], v[152:155], v[184:187], v[88:91]
	v_mfma_f32_16x16x32_bf16 v[80:83], v[160:163], v[184:187], v[80:83]
	v_mfma_f32_16x16x32_bf16 v[72:75], v[152:155], v[192:195], v[72:75]
	v_mfma_f32_16x16x32_bf16 v[68:71], v[160:163], v[192:195], v[68:71]
	s_setprio 0
	s_barrier
; #define PG8_STAGE(bufoff, gbase, voff) do { _Pragma("unroll") for (int _i = 0; _i < 2; ++_i) \
;         __builtin_amdgcn_global_load_lds((const unsigned*)((const char*)(gbase) + (voff)[_i]), (PG8_LAS unsigned*)(lds + (bufoff) + ldsw + _i * 8192), 16, 0, 0); } while (0)
; #define PG8_LDA(dst, b, h) do { _Pragma("unroll") for (int m = 0; m < 4; ++m) _Pragma("unroll") for (int k = 0; k < 2; ++k) dst[m][k] = *(const PG8_LAS bf16x8*)(lds + PG8_SA(b, h) + aoff + m * 2048 + k * 1024); } while (0)
; #define PG8_MMA(ai, bj, At, Bt) do { __builtin_amdgcn_s_setprio(1); _Pragma("unroll") for (int m = 0; m < 4; ++m) _Pragma("unroll") for (int n = 0; n < 2; ++n) _Pragma("unroll") for (int k = 0; k < 2; ++k) \
;         acc[ai][bj][m][n] = __builtin_amdgcn_mfma_f32_16x16x32_bf16(Bt[n][k], At[m][k], acc[ai][bj][m][n], 0, 0, 0); __builtin_amdgcn_s_setprio(0); } while (0)
; #define PG8_WAIT_V(n) asm volatile("s_waitcnt vmcnt(" #n ")" ::: "memory")
; #define PG8_WAIT_L(n) asm volatile("s_waitcnt lgkmcnt(" #n ")" ::: "memory")
; #define PG8_BAR __builtin_amdgcn_s_barrier()
; #define PG8_SCHED __builtin_amdgcn_sched_barrier(0)
; template <class Epi, class Sched, bool ALIGN_EPI = false, bool SP2 = false>
; __device__ __forceinline__ void gemm_phase(PG8_LAS unsigned char* lds, const Gemm g, const Sched& S, const Epi& E) {
;     ...
;             PG8_LDA(At, 1, 1); PG8_STAGE(PG8_SB(1, 0), b3, voffB); PG8_STAGE(PG8_SB(1, 1), b3 + hstep, voffB); PG8_STAGE(PG8_SA(1, 0), a3, voffA);
;             PG8_WAIT_V(8); PG8_WAIT_L(0); PG8_BAR; PG8_MMA(1, 0, At, B0); PG8_MMA(1, 1, At, B1); PG8_BAR; PG8_SCHED;
;     ...
;         }
;         if constexpr (ALIGN_EPI) { if (wr == 0) PG8_BAR; }
	s_add_i32 s42, s65, s50
	v_lshl_add_u64 v[210:211], v[210:211], 0, s[36:37]
	s_mov_b32 m0, s42
	ds_read_b128 v[164:167], v250 offset:49152
	ds_read_b128 v[168:171], v250 offset:50176
	ds_read_b128 v[172:175], v250 offset:51200
	ds_read_b128 v[176:179], v250 offset:52224
	ds_read_b128 v[180:183], v250 offset:53248
	ds_read_b128 v[184:187], v250 offset:54272
	ds_read_b128 v[188:191], v250 offset:55296
	ds_read_b128 v[192:195], v250 offset:56320
	global_load_lds_dwordx4 v[210:211], off
	s_add_i32 m0, s42, 0x2000
	s_add_u32 s40, s40, 0x20080
	v_lshl_add_u64 v[210:211], v[212:213], 0, s[36:37]
	s_addc_u32 s41, s41, 0
	s_add_i32 s42, s66, s50
	global_load_lds_dwordx4 v[210:211], off
	v_lshl_add_u64 v[210:211], s[40:41], 0, v[196:197]
	s_mov_b32 m0, s42
	s_nop 0
	global_load_lds_dwordx4 v[210:211], off
	v_lshl_add_u64 v[210:211], s[40:41], 0, v[32:33]
	s_add_i32 m0, s42, 0x2000
	s_nop 0
	global_load_lds_dwordx4 v[210:211], off
	v_lshl_add_u64 v[210:211], v[214:215], 0, s[36:37]
	s_mov_b32 m0, s56
	s_nop 0
	global_load_lds_dwordx4 v[210:211], off
	v_lshl_add_u64 v[210:211], v[216:217], 0, s[36:37]
	s_mov_b32 m0, s57
	s_nop 0
	global_load_lds_dwordx4 v[210:211], off
	s_waitcnt vmcnt(8)
	s_waitcnt lgkmcnt(0)
	v_mfma_f32_16x16x32_bf16 v[64:67], v[132:135], v[164:167], v[64:67]
	v_mfma_f32_16x16x32_bf16 v[60:63], v[140:143], v[164:167], v[60:63]
	v_mfma_f32_16x16x32_bf16 v[52:55], v[132:135], v[172:175], v[52:55]
	v_mfma_f32_16x16x32_bf16 v[44:47], v[140:143], v[172:175], v[44:47]
	s_barrier
	s_setprio 1
	v_mfma_f32_16x16x32_bf16 v[36:39], v[132:135], v[180:183], v[36:39]
	v_mfma_f32_16x16x32_bf16 v[24:27], v[140:143], v[180:183], v[24:27]
	v_mfma_f32_16x16x32_bf16 v[16:19], v[132:135], v[188:191], v[16:19]
	v_mfma_f32_16x16x32_bf16 v[8:11], v[140:143], v[188:191], v[8:11]
	v_mfma_f32_16x16x32_bf16 v[64:67], v[136:139], v[168:171], v[64:67]
	v_mfma_f32_16x16x32_bf16 v[60:63], v[144:147], v[168:171], v[60:63]
	v_mfma_f32_16x16x32_bf16 v[52:55], v[136:139], v[176:179], v[52:55]
	v_mfma_f32_16x16x32_bf16 v[44:47], v[144:147], v[176:179], v[44:47]
	v_mfma_f32_16x16x32_bf16 v[36:39], v[136:139], v[184:187], v[36:39]
	v_mfma_f32_16x16x32_bf16 v[24:27], v[144:147], v[184:187], v[24:27]
	v_mfma_f32_16x16x32_bf16 v[16:19], v[136:139], v[192:195], v[16:19]
	v_mfma_f32_16x16x32_bf16 v[8:11], v[144:147], v[192:195], v[8:11]
	s_setprio 0
	s_setprio 1
	v_mfma_f32_16x16x32_bf16 v[56:59], v[148:151], v[164:167], v[56:59]
	v_mfma_f32_16x16x32_bf16 v[48:51], v[156:159], v[164:167], v[48:51]
	v_mfma_f32_16x16x32_bf16 v[40:43], v[148:151], v[172:175], v[40:43]
	v_mfma_f32_16x16x32_bf16 v[28:31], v[156:159], v[172:175], v[28:31]
	v_mfma_f32_16x16x32_bf16 v[20:23], v[148:151], v[180:183], v[20:23]
	v_mfma_f32_16x16x32_bf16 v[12:15], v[156:159], v[180:183], v[12:15]
	v_mfma_f32_16x16x32_bf16 v[4:7], v[148:151], v[188:191], v[4:7]
	v_mfma_f32_16x16x32_bf16 v[0:3], v[156:159], v[188:191], v[0:3]
	v_mfma_f32_16x16x32_bf16 v[56:59], v[152:155], v[168:171], v[56:59]
	v_mfma_f32_16x16x32_bf16 v[48:51], v[160:163], v[168:171], v[48:51]
	v_mfma_f32_16x16x32_bf16 v[40:43], v[152:155], v[176:179], v[40:43]
	v_mfma_f32_16x16x32_bf16 v[28:31], v[160:163], v[176:179], v[28:31]
	v_mfma_f32_16x16x32_bf16 v[20:23], v[152:155], v[184:187], v[20:23]
	v_mfma_f32_16x16x32_bf16 v[12:15], v[160:163], v[184:187], v[12:15]
	v_mfma_f32_16x16x32_bf16 v[4:7], v[152:155], v[192:195], v[4:7]
	v_mfma_f32_16x16x32_bf16 v[0:3], v[160:163], v[192:195], v[0:3]
	s_setprio 0
	s_barrier
	s_add_i32 s64, s64, 2
	s_add_u32 s0, s0, 0x100
	s_addc_u32 s1, s1, 0
	s_add_u32 s62, s62, 0x100
	s_addc_u32 s63, s63, 0
	s_cmp_gt_u32 s64, 5
	s_cbranch_scc0 .LBB0_49
	s_and_b64 vcc, exec, s[12:13]
	s_cbranch_vccz .LBB0_52
	s_barrier

; template <int MODE, bool FROZEN = false>
; __device__ __forceinline__ bool attn_unit(LAS unsigned char* lds, const Params& p, int l, int ua, int ub) {
;     ...
;         const float* lq = p.diff_lambda + (size_t)l * 256;
;         const float s1 = wave_sum(lq[lane] * lq[64 + lane]), s2 = wave_sum(lq[128 + lane] * lq[192 + lane]);
;         lam_init = 0.8f - 0.6f * expf(-0.3f * (float)l);
;         lam = expf(s1) - expf(s2) + lam_init;
;     } else {
;         const int g = ua, qb = ub, hq = g * 4 + (wid >> 1); qtok0 = qb * 64 + (wid & 1) * 32; lut_sel = wid >> 1;
;         qcol = 3072 + hq * 64; kcol = 3584 + g * 64; vcol = 1024 + g * 64; ocol = hq * 64;
;         const int tlo = max(qb - 2, 0), thi = min(qb + 2, S / 64 - 1); kt0 = tlo * 64; NT = thi - tlo + 1; wt_hi = NT;
;         for (int i = tid; i < 4 * 449; i += 512) { const int hh = i / 449, rel = i % 449 - 224; lut[i] = (rel >= -128 && rel <= 128) ? p.rel_bias[t5_bucket(rel) * 12 + 4 + g * 4 + hh] * LOG2E : NEGBIG; }
;         m_run = p.gqa_sink[l * 8 + hq] * LOG2E; l_run = (hi == 0) ? 1.0f : 0.0f;
;     }
;     bf16x8 qf[4];
;     { const bf16_t* qp = proj + (size_t)(qtok0 + r32) * NPROJ + qcol + 8 * hi;
; #pragma unroll
;       for (int d0 = 0; d0 < 4; ++d0) qf[d0] = *(const bf16x8*)(qp + 16 * d0); }
;     f32x16 o[NB];
; #pragma unroll
;     for (int nb = 0; nb < NB; ++nb)
; #pragma unroll
;         for (int r = 0; r < 16; ++r) o[nb][r] = 0.f;
;     u32x4 kr[NKC], vr[NVC];
;     unsigned ksrc[NKC], vsrc[NVC]; int kdst[NKC], vdst[NVC];
;     const bf16_t* kvbase = proj + (size_t)kt0 * NPROJ;
; #pragma unroll
;     for (int i = 0; i < NKC; ++i) { const int cid = tid + 512 * i, row = cid / KCH, ch = cid % KCH; ksrc[i] = (unsigned)(row * NPROJ + kcol + ch * 8); kdst[i] = OFF_K + row * KPB + ch * 16; }
; #pragma unroll
;     for (int i = 0; i < NVC; ++i) { const int cid = tid + 512 * i, row = cid >> 3, ch = cid & 7; vsrc[i] = (unsigned)((vcol + row) * S + ch * 8); vdst[i] = OFF_V + row * VTP + (ch >> 1) * 32 + (ch & 1) * 8; }
;     const bf16_t* vtbase = vtg + kt0;
;     {
;         u32x4 k1[NKC];
; #pragma unroll
;         for (int i = 0; i < NKC; ++i) { kr[i] = *(const u32x4*)(kvbase + ksrc[i]); k1[i] = *(const u32x4*)(kvbase + (size_t)64 * NPROJ + ksrc[i]); }
; #pragma unroll
;         for (int i = 0; i < NVC; ++i) vr[i] = *(const u32x4*)(vtbase + vsrc[i]);
; #pragma unroll
.LBB0_116:
	v_mul_f32_e32 v55, 0x3fb8aa3b, v53
	s_mov_b32 s8, 0x3fb8aa3b
	v_fma_f32 v56, v53, s8, -v55
	v_fmac_f32_e32 v56, 0x32a5705f, v53
	v_rndne_f32_e32 v53, v55
	v_sub_f32_e32 v55, v55, v53
	v_add_f32_e32 v55, v55, v56
	v_mul_f32_e32 v56, 0x3fb8aa3b, v54
	v_fma_f32 v57, v54, s8, -v56
	v_fmac_f32_e32 v57, 0x32a5705f, v54
	v_rndne_f32_e32 v54, v56
	v_exp_f32_e32 v55, v55
	v_cvt_i32_f32_e32 v53, v53
	v_sub_f32_e32 v56, v56, v54
	v_add_f32_e32 v56, v56, v57
	v_exp_f32_e32 v56, v56
	v_cvt_i32_f32_e32 v54, v54
	v_ldexp_f32 v53, v55, v53
	v_cndmask_b32_e64 v53, 0, v53, s[40:41]
	v_mov_b32_e32 v55, 0x7f800000
	v_cndmask_b32_e64 v167, v55, v53, s[42:43]
	v_ldexp_f32 v53, v56, v54
	v_cndmask_b32_e64 v53, 0, v53, s[0:1]
	s_lshl_b32 s0, s51, 7
	s_and_b32 s0, s0, 0x2000
	s_lshl_b32 s1, s57, 7
	v_cndmask_b32_e64 v168, v55, v53, s[4:5]
	s_add_i32 s4, s0, s1
	s_or_b32 s4, s4, s58
	v_mul_u32_u24_e32 v53, 0x90, v52
	v_add_lshl_u32 v52, s4, v52, 2
	v_sub_u32_e32 v52, v32, v52
	s_or_b32 s1, s58, s1
	v_add3_u32 v101, 0, v53, v32
	v_add_u32_e32 v102, 0, v52
	s_add_i32 s1, s1, s0
	v_mov_b64_e32 v[98:99], v[50:51]
	v_mov_b64_e32 v[82:83], v[50:51]
	v_mov_b64_e32 v[66:67], v[50:51]
	s_add_i32 s8, s4, 0xffffff81
	s_sub_i32 s12, 33, s1
	s_mov_b32 s13, 0
	v_mov_b64_e32 v[96:97], v[48:49]
	v_mov_b64_e32 v[94:95], v[46:47]
	v_mov_b64_e32 v[92:93], v[44:45]
	v_mov_b64_e32 v[90:91], v[42:43]
	v_mov_b64_e32 v[88:89], v[40:41]
	v_mov_b64_e32 v[86:87], v[38:39]
	v_mov_b64_e32 v[84:85], v[36:37]
	v_mov_b64_e32 v[80:81], v[48:49]
	v_mov_b64_e32 v[78:79], v[46:47]
	v_mov_b64_e32 v[76:77], v[44:45]
	v_mov_b64_e32 v[74:75], v[42:43]
	v_mov_b64_e32 v[72:73], v[40:41]
	v_mov_b64_e32 v[70:71], v[38:39]
	v_mov_b64_e32 v[68:69], v[36:37]
	v_mov_b64_e32 v[64:65], v[48:49]
	v_mov_b64_e32 v[62:63], v[46:47]
	v_mov_b64_e32 v[60:61], v[44:45]
	v_mov_b64_e32 v[58:59], v[42:43]
	v_mov_b64_e32 v[56:57], v[40:41]
	v_mov_b64_e32 v[54:55], v[38:39]
	v_mov_b64_e32 v[52:53], v[36:37]
	v_mov_b64_e32 v[218:219], 0
	v_mov_b64_e32 v[220:221], 0
	v_mov_b64_e32 v[222:223], 0
	v_mov_b64_e32 v[224:225], 0
	v_mov_b64_e32 v[248:249], 0
	v_mov_b64_e32 v[250:251], 0
	v_mov_b64_e32 v[236:237], 0
	v_mov_b64_e32 v[238:239], 0
	v_mov_b64_e32 v[244:245], 0
	v_mov_b64_e32 v[246:247], 0
	v_readfirstlane_b32 s100, v228
	s_lshr_b32 s100, s100, 8
	s_cmp_eq_u32 s100, 0
	s_cbranch_scc1 .Lattn_prio_skip
	s_setprio 1
.Lattn_prio_skip:
	s_mov_b32 s4, 0
	s_barrier
	s_bitcmp1_b32 s4, 0
	s_cselect_b64 s[0:1], -1, 0
	s_cmpk_gt_u32 s4, 0xfd
	s_cbranch_scc1 .LBB0_118
.LBB0_117:
.LBB0_118:
	s_add_i32 s14, s4, 1
	s_bitcmp1_b32 s14, 0
	s_cselect_b32 s15, 0x4400, 0
	s_cselect_b32 s100, 0, 0x4800
	v_add_u32_e32 v194, s100, v101
	ds_read_b128 v[112:115], v194 offset:34816
	ds_read_b128 v[170:173], v194 offset:39424
	ds_read_b128 v[174:177], v194 offset:44032
	ds_read_b128 v[178:181], v194 offset:48640
	v_exp_f32_e32 v103, v16
	v_exp_f32_e32 v104, v17
	v_mfma_f32_32x32x16_bf16 v[52:67], v[236:239], v[244:247], v[52:67]
	v_exp_f32_e32 v105, v18
	v_exp_f32_e32 v106, v19
	v_cvt_pk_bf16_f32 v16, v103, v104
	v_mfma_f32_32x32x16_bf16 v[36:51], v[218:221], v[244:247], v[36:51]
	v_exp_f32_e32 v107, v20
	v_exp_f32_e32 v108, v21
	v_cvt_pk_bf16_f32 v17, v105, v106
	v_mfma_f32_32x32x16_bf16 v[84:99], v[222:225], v[244:247], v[84:99]
	v_exp_f32_e32 v109, v22
	v_exp_f32_e32 v110, v23
	v_cvt_pk_bf16_f32 v18, v107, v108
	v_mfma_f32_32x32x16_bf16 v[68:83], v[248:251], v[244:247], v[68:83]
	v_add_u32_e32 v195, s15, v166
	v_cvt_pk_bf16_f32 v19, v109, v110
	s_waitcnt lgkmcnt(3)
	s_nop 0
	v_mfma_f32_32x32x16_bf16 v[36:51], v[112:115], v[16:19], v[36:51]
	ds_read_b128 v[20:23], v194 offset:34848
	v_exp_f32_e32 v111, v24
	v_exp_f32_e32 v112, v25
	s_nop 0
	v_cvt_pk_bf16_f32 v24, v111, v112
	s_waitcnt lgkmcnt(3)
	v_mfma_f32_32x32x16_bf16 v[84:99], v[170:173], v[16:19], v[84:99]
	ds_read_b128 v[182:185], v194 offset:39456
	v_exp_f32_e32 v113, v26
	v_exp_f32_e32 v114, v27
	s_nop 0
	v_cvt_pk_bf16_f32 v25, v113, v114
	s_waitcnt lgkmcnt(3)
	v_mfma_f32_32x32x16_bf16 v[68:83], v[174:177], v[16:19], v[68:83]
	ds_read_b128 v[186:189], v194 offset:44064
	v_exp_f32_e32 v115, v28
	v_exp_f32_e32 v170, v29
	s_nop 0
	v_cvt_pk_bf16_f32 v26, v115, v170
	s_waitcnt lgkmcnt(3)
	v_mfma_f32_32x32x16_bf16 v[52:67], v[178:181], v[16:19], v[52:67]
	ds_read_b128 v[16:19], v194 offset:48672
	v_exp_f32_e32 v171, v30
	v_exp_f32_e32 v172, v31
	s_nop 0
	v_cvt_pk_bf16_f32 v27, v171, v172
	s_waitcnt lgkmcnt(3)
	s_nop 0
	v_mfma_f32_32x32x16_bf16 v[36:51], v[20:23], v[24:27], v[36:51]
	ds_read_b128 v[190:193], v194 offset:34880
	v_exp_f32_e32 v173, v0
	v_exp_f32_e32 v174, v1
	ds_read_b128 v[20:23], v195 offset:8736
	ds_read_b128 v[28:31], v195 offset:8800
	ds_read_b128 v[218:221], v195 offset:32
	v_cvt_pk_bf16_f32 v202, v173, v174
	s_waitcnt lgkmcnt(6)
	v_mfma_f32_32x32x16_bf16 v[84:99], v[182:185], v[24:27], v[84:99]
	ds_read_b128 v[206:209], v194 offset:39488
	v_exp_f32_e32 v175, v2
	v_exp_f32_e32 v176, v3
	ds_read_b128 v[0:3], v195 offset:8704
	ds_read_b128 v[222:225], v195 offset:64
	ds_read_b128 v[248:251], v195 offset:96
	v_cvt_pk_bf16_f32 v203, v175, v176
	s_waitcnt lgkmcnt(9)
	v_mfma_f32_32x32x16_bf16 v[68:83], v[186:189], v[24:27], v[68:83]
	ds_read_b128 v[210:213], v194 offset:44096
	v_exp_f32_e32 v177, v4
	v_exp_f32_e32 v178, v5
	s_nop 0
	v_cvt_pk_bf16_f32 v204, v177, v178
	s_waitcnt lgkmcnt(9)
	v_mfma_f32_32x32x16_bf16 v[52:67], v[16:19], v[24:27], v[52:67]
	ds_read_b128 v[16:19], v195
	ds_read_b128 v[24:27], v195 offset:8768
	ds_read_b128 v[214:217], v194 offset:48704
	v_exp_f32_e32 v179, v6
	v_exp_f32_e32 v180, v7
	s_nop 0
	v_cvt_pk_bf16_f32 v205, v179, v180
	ds_read_b128 v[236:239], v194 offset:48736
	v_exp_f32_e32 v181, v8
	v_exp_f32_e32 v182, v9
	s_waitcnt lgkmcnt(12)
; #define LAS __attribute__((address_space(3)))
; #define VLOAD(ks, DST) do { const LAS unsigned char* vp_ = Vb + (ks) * 32; \
;         _Pragma("unroll") for (int nb = 0; nb < NB; ++nb) DST[nb] = *(const LAS bf16x8*)(vp_ + nb * 32 * VTP); } while (0)
; #define SBAR_() __builtin_amdgcn_sched_barrier(0)
; template <int MODE, bool FROZEN = false>
; __device__ __forceinline__ bool attn_unit(LAS unsigned char* lds, const Params& p, int l, int ua, int ub) {
;     ...
;         VLOAD(0, va);
;         EXPCVT(0, pf0, ps0);
;         SBAR_();
;         VLOAD(1, vb); PVMMA(va, pf0); EXPCVT(1, pf1, ps1); _Pragma("unroll") for (int g_ = 0; g_ < NB; ++g_) { __builtin_amdgcn_sched_group_barrier(0x008, 1, 0); __builtin_amdgcn_sched_group_barrier(0x100, 1, 0); __builtin_amdgcn_sched_group_barrier(0x400, 8 / NB, 0); __builtin_amdgcn_sched_group_barrier(0x002, 12 / NB, 0); } SBAR_();
;         VLOAD(2, va);
; #pragma unroll
;         for (int d0 = 0; d0 < 4; ++d0) { kf0[d0] = *(const LAS bf16x8*)(Kb + d0 * 32); kf1[d0] = *(const LAS bf16x8*)(Kb + 32 * KPB + d0 * 32); }
;         PVMMA(vb, pf1); EXPCVT(2, pf0, ps2); _Pragma("unroll") for (int g_ = 0; g_ < NB; ++g_) { __builtin_amdgcn_sched_group_barrier(0x008, 1, 0); __builtin_amdgcn_sched_group_barrier(0x100, 1, 0); __builtin_amdgcn_sched_group_barrier(0x400, 8 / NB, 0); __builtin_amdgcn_sched_group_barrier(0x002, 12 / NB, 0); } SBAR_();
;         {
;             f32x16 z0, z1;
; #pragma unroll
;             for (int r = 0; r < 16; ++r) { z0[r] = 0.f; z1[r] = 0.f; }
; #pragma unroll
;             for (int d0 = 0; d0 < 4; ++d0) { z0 = __builtin_amdgcn_mfma_f32_32x32x16_bf16(kf0[d0], qf[d0], z0, 0, 0, 0); z1 = __builtin_amdgcn_mfma_f32_32x32x16_bf16(kf1[d0], qf[d0], z1, 0, 0, 0); }
;             sB0 = z0; sB1 = z1;
;         }
;         EXPCVT(3, pf1, ps3);
; #pragma unroll
;         for (int g_ = 0; g_ < 8; ++g_) { __builtin_amdgcn_sched_group_barrier(0x008, 1, 0); __builtin_amdgcn_sched_group_barrier(0x400, 1, 0); __builtin_amdgcn_sched_group_barrier(0x002, 2, 0); }
;         SBAR_();
;         float tmr;
;         VLOAD(3, vb); SBAR_();
;         PVMMA(va, pf0); if constexpr (!FROZEN) ATT_MAX3(tmr); else tmr = 0.f; PVMMA(vb, pf1);
;         const float ps = (ps0 + ps1) + (ps2 + ps3);
;     ...
;         l_run += ps;
;         if (t + 1 < NT) { ATT_BIAS(t + 1, tmr); ATT_UPD(tmr); }
	v_mfma_f32_32x32x16_bf16 v[36:51], v[190:193], v[202:205], v[36:51]
	v_exp_f32_e32 v183, v10
	v_exp_f32_e32 v184, v11
	v_cvt_pk_bf16_f32 v244, v181, v182
	s_sub_i32 s5, 0x4400, s15
	v_add_u32_e32 v190, s5, v33
	s_waitcnt lgkmcnt(8)
	v_mfma_f32_32x32x16_bf16 v[84:99], v[206:209], v[202:205], v[84:99]
	v_exp_f32_e32 v185, v12
	v_exp_f32_e32 v186, v13
	v_cvt_pk_bf16_f32 v245, v183, v184
	v_add_u32_e32 v191, s5, v165
	s_sub_i32 s101, 0xd000, s100
	s_waitcnt lgkmcnt(4)
	v_mfma_f32_32x32x16_bf16 v[68:83], v[210:213], v[202:205], v[68:83]
	v_exp_f32_e32 v187, v14
	v_exp_f32_e32 v188, v15
	v_cvt_pk_bf16_f32 v246, v185, v186
	v_add_u32_e32 v192, s101, v158
	s_waitcnt lgkmcnt(1)
	v_mfma_f32_32x32x16_bf16 v[52:67], v[214:217], v[202:205], v[52:67]
	v_add_u32_e32 v193, s101, v160
	v_cvt_pk_bf16_f32 v247, v187, v188
	s_min_i32 s5, s4, 0xfc
	s_mul_i32 s5, s5, 0x78000
	s_add_u32 s5, s34, s5
	s_addc_u32 s11, s35, 0
	s_add_u32 s10, s5, 0x168000
	s_addc_u32 s11, s11, 0
	v_mfma_f32_32x32x16_bf16 v[0:15], v[0:3], v[116:119], 0
	s_waitcnt vmcnt(3)
	ds_write_b128 v190, v[132:135]
	v_add_f32_e32 v105, v105, v106
	v_add_f32_e32 v106, v107, v108
	v_add_f32_e32 v107, v109, v110
	v_add_f32_e32 v103, v103, v104
	v_lshl_add_u64 v[202:203], v[196:197], 1, s[10:11]
	v_mfma_f32_32x32x16_bf16 v[0:15], v[20:23], v[120:123], v[0:15]
	s_waitcnt vmcnt(2)
	ds_write_b128 v191, v[140:143]
	v_add_f32_e32 v106, v106, v107
	v_add_f32_e32 v103, v103, v105
	v_add_f32_e32 v105, v115, v170
	v_add_f32_e32 v107, v171, v172
	v_lshl_add_u64 v[204:205], v[152:153], 1, s[10:11]
	s_min_i32 s4, s4, 0xfd
	s_lshl_b32 s4, s4, 7
	s_add_u32 s4, s6, s4
	s_addc_u32 s5, s7, 0
	v_mfma_f32_32x32x16_bf16 v[0:15], v[24:27], v[124:127], v[0:15]
	s_waitcnt vmcnt(1)
	ds_write2_b64 v192, v[136:137], v[138:139] offset1:2
	v_add_f32_e32 v104, v113, v114
	v_add_f32_e32 v105, v105, v107
	v_add_f32_e32 v107, v111, v112
	v_add_f32_e32 v104, v107, v104
	v_lshl_add_u64 v[206:207], v[154:155], 1, s[4:5]
	v_mfma_f32_32x32x16_bf16 v[0:15], v[28:31], v[128:131], v[0:15]
	s_waitcnt vmcnt(0)
	ds_write2_b64 v193, v[144:145], v[146:147] offset1:2
	v_add_f32_e32 v107, v177, v178
	v_add_f32_e32 v108, v179, v180
	v_add_f32_e32 v104, v104, v105
	v_add_f32_e32 v105, v175, v176
	v_lshl_add_u64 v[208:209], v[156:157], 1, s[4:5]
	v_mfma_f32_32x32x16_bf16 v[16:31], v[16:19], v[116:119], 0
	global_load_dwordx4 v[132:135], v[202:203], off
	v_add_f32_e32 v107, v107, v108
	v_add_f32_e32 v108, v173, v174
	v_add_f32_e32 v105, v108, v105
	v_add_f32_e32 v105, v105, v107
	s_cmpk_gt_i32 s12, 0x7f
	s_cselect_b64 s[0:1], -1, 0
	s_cmpk_gt_i32 s8, 0x7f
	s_cselect_b64 s[4:5], -1, 0
	s_or_b64 s[10:11], s[0:1], s[4:5]
	v_mfma_f32_32x32x16_bf16 v[16:31], v[218:221], v[120:123], v[16:31]
	ds_read_b128 v[218:221], v194 offset:34912
	global_load_dwordx4 v[140:143], v[204:205], off
	v_add_f32_e32 v107, v185, v186
	v_add_f32_e32 v108, v187, v188
	v_add_f32_e32 v103, v103, v106
	v_add_f32_e32 v106, v183, v184
	s_and_b64 vcc, exec, s[10:11]
	v_mfma_f32_32x32x16_bf16 v[16:31], v[222:225], v[124:127], v[16:31]
	ds_read_b128 v[222:225], v194 offset:39520
	global_load_dwordx4 v[136:139], v[206:207], off offset:256
	v_add_f32_e32 v107, v107, v108
	v_add_f32_e32 v108, v181, v182
	v_add_f32_e32 v106, v108, v106
	v_add_f32_e32 v106, v106, v107
	v_mfma_f32_32x32x16_bf16 v[16:31], v[248:251], v[128:131], v[16:31]
	ds_read_b128 v[248:251], v194 offset:44128
	global_load_dwordx4 v[144:147], v[208:209], off offset:256
	v_add_f32_e32 v103, v103, v104
	v_add_f32_e32 v104, v105, v106
	v_add_f32_e32 v103, v103, v104
	v_add_f32_e32 v100, v100, v103
	s_cbranch_vccnz .LBB0_120
	v_add_u32_e32 v189, s13, v102
	v_add_u32_e32 v190, 0x11c80, v189
	v_add_u32_e32 v192, 0x11c88, v189
	v_add_u32_e32 v194, 0x11ca0, v189
	v_add_u32_e32 v202, 0x11ca8, v189
	ds_read2_b32 v[190:191], v190 offset1:1
	ds_read2_b32 v[192:193], v192 offset1:1
	ds_read2_b32 v[194:195], v194 offset1:1
	ds_read2_b32 v[202:203], v202 offset1:1
	v_add_u32_e32 v204, 0x11cc0, v189
	v_add_u32_e32 v206, 0x11cc8, v189
	v_add_u32_e32 v208, 0x11ce0, v189
	v_add_u32_e32 v210, 0x11ce8, v189
	ds_read2_b32 v[204:205], v204 offset1:1
	ds_read2_b32 v[206:207], v206 offset1:1
	ds_read2_b32 v[208:209], v208 offset1:1
	ds_read2_b32 v[210:211], v210 offset1:1
	s_waitcnt lgkmcnt(7)
	v_sub_f32_e32 v191, v191, v169
	v_sub_f32_e32 v190, v190, v169
	s_waitcnt lgkmcnt(2)
	v_sub_f32_e32 v207, v207, v169
	v_sub_f32_e32 v205, v205, v169
	v_sub_f32_e32 v204, v204, v169
	v_sub_f32_e32 v206, v206, v169
	s_waitcnt lgkmcnt(1)
	v_sub_f32_e32 v209, v209, v169
	v_sub_f32_e32 v208, v208, v169
	s_waitcnt lgkmcnt(0)
	v_sub_f32_e32 v211, v211, v169
	v_sub_f32_e32 v210, v210, v169
	v_sub_f32_e32 v193, v193, v169
	v_sub_f32_e32 v192, v192, v169
	v_sub_f32_e32 v195, v195, v169
	v_sub_f32_e32 v194, v194, v169
	v_sub_f32_e32 v203, v203, v169
	v_sub_f32_e32 v202, v202, v169
	v_pk_add_f32 v[22:23], v[22:23], v[202:203]
	v_pk_add_f32 v[20:21], v[20:21], v[194:195]
	v_pk_add_f32 v[18:19], v[18:19], v[192:193]
	v_pk_add_f32 v[16:17], v[16:17], v[190:191]
	v_pk_add_f32 v[30:31], v[30:31], v[210:211]
	v_pk_add_f32 v[28:29], v[28:29], v[208:209]
	v_pk_add_f32 v[26:27], v[26:27], v[206:207]
	v_pk_add_f32 v[24:25], v[24:25], v[204:205]
	v_add_u32_e32 v190, 0x11d00, v189
	v_add_u32_e32 v192, 0x11d08, v189
	v_add_u32_e32 v194, 0x11d20, v189
	v_add_u32_e32 v202, 0x11d28, v189
	ds_read2_b32 v[190:191], v190 offset1:1
	ds_read2_b32 v[192:193], v192 offset1:1
	ds_read2_b32 v[194:195], v194 offset1:1
	ds_read2_b32 v[202:203], v202 offset1:1
	v_add_u32_e32 v204, 0x11d40, v189
	v_add_u32_e32 v206, 0x11d48, v189
	v_add_u32_e32 v208, 0x11d60, v189
	ds_read2_b32 v[204:205], v204 offset1:1
	v_add_u32_e32 v189, 0x11d68, v189
	ds_read2_b32 v[206:207], v206 offset1:1
	ds_read2_b32 v[208:209], v208 offset1:1
	ds_read2_b32 v[210:211], v189 offset1:1
	s_waitcnt lgkmcnt(7)
	v_sub_f32_e32 v191, v191, v169
	v_sub_f32_e32 v190, v190, v169
	s_waitcnt lgkmcnt(3)
	v_sub_f32_e32 v205, v205, v169
	v_sub_f32_e32 v204, v204, v169
	s_waitcnt lgkmcnt(2)
	v_sub_f32_e32 v207, v207, v169
	v_sub_f32_e32 v206, v206, v169
	s_waitcnt lgkmcnt(1)
	v_sub_f32_e32 v209, v209, v169
	v_sub_f32_e32 v208, v208, v169
	s_waitcnt lgkmcnt(0)
	v_sub_f32_e32 v211, v211, v169
	v_sub_f32_e32 v210, v210, v169
	v_sub_f32_e32 v193, v193, v169
	v_sub_f32_e32 v192, v192, v169
	v_sub_f32_e32 v195, v195, v169
	v_sub_f32_e32 v194, v194, v169
	v_sub_f32_e32 v203, v203, v169
	v_sub_f32_e32 v202, v202, v169
	v_pk_add_f32 v[6:7], v[6:7], v[202:203]
	v_pk_add_f32 v[4:5], v[4:5], v[194:195]
	v_pk_add_f32 v[2:3], v[2:3], v[192:193]
	v_pk_add_f32 v[0:1], v[0:1], v[190:191]
	v_pk_add_f32 v[14:15], v[14:15], v[210:211]
	v_pk_add_f32 v[12:13], v[12:13], v[208:209]
	v_pk_add_f32 v[10:11], v[10:11], v[206:207]
	v_pk_add_f32 v[8:9], v[8:9], v[204:205]
.LBB0_120:
	s_andn2_b64 vcc, exec, s[10:11]
	s_cbranch_vccnz .LBB0_123
	v_cndmask_b32_e64 v103, 0, v161, s[4:5]
	v_cndmask_b32_e64 v103, v103, v159, s[0:1]
	v_cmp_neq_f32_e32 vcc, v103, v169
	s_cbranch_vccz .LBB0_123
	v_sub_f32_e32 v104, v169, v103
	v_exp_f32_e32 v104, v104
	v_mov_b32_e32 v169, v103
	s_waitcnt lgkmcnt(0)
	v_mfma_f32_32x32x16_bf16 v[52:67], v[236:239], v[244:247], v[52:67]
	v_mfma_f32_32x32x16_bf16 v[36:51], v[218:221], v[244:247], v[36:51]
	v_mfma_f32_32x32x16_bf16 v[84:99], v[222:225], v[244:247], v[84:99]
	v_mfma_f32_32x32x16_bf16 v[68:83], v[248:251], v[244:247], v[68:83]
	v_mov_b32_e32 v244, 0
	v_mov_b32_e32 v245, 0
	v_mov_b32_e32 v246, 0
	v_mov_b32_e32 v247, 0
	s_nop 7
	s_nop 7
	v_pk_mul_f32 v[50:51], v[104:105], v[50:51] op_sel_hi:[0,1]
	v_pk_mul_f32 v[48:49], v[104:105], v[48:49] op_sel_hi:[0,1]
	v_pk_mul_f32 v[46:47], v[104:105], v[46:47] op_sel_hi:[0,1]
	v_pk_mul_f32 v[44:45], v[104:105], v[44:45] op_sel_hi:[0,1]
	v_pk_mul_f32 v[42:43], v[104:105], v[42:43] op_sel_hi:[0,1]
	v_pk_mul_f32 v[40:41], v[104:105], v[40:41] op_sel_hi:[0,1]
	v_pk_mul_f32 v[38:39], v[104:105], v[38:39] op_sel_hi:[0,1]
	v_pk_mul_f32 v[36:37], v[104:105], v[36:37] op_sel_hi:[0,1]
	v_pk_mul_f32 v[98:99], v[104:105], v[98:99] op_sel_hi:[0,1]
	v_pk_mul_f32 v[96:97], v[104:105], v[96:97] op_sel_hi:[0,1]
	v_pk_mul_f32 v[94:95], v[104:105], v[94:95] op_sel_hi:[0,1]
	v_pk_mul_f32 v[92:93], v[104:105], v[92:93] op_sel_hi:[0,1]
	v_pk_mul_f32 v[90:91], v[104:105], v[90:91] op_sel_hi:[0,1]
	v_pk_mul_f32 v[88:89], v[104:105], v[88:89] op_sel_hi:[0,1]
	v_pk_mul_f32 v[86:87], v[104:105], v[86:87] op_sel_hi:[0,1]
	v_pk_mul_f32 v[84:85], v[104:105], v[84:85] op_sel_hi:[0,1]
	v_pk_mul_f32 v[82:83], v[104:105], v[82:83] op_sel_hi:[0,1]
	v_pk_mul_f32 v[80:81], v[104:105], v[80:81] op_sel_hi:[0,1]
	v_pk_mul_f32 v[78:79], v[104:105], v[78:79] op_sel_hi:[0,1]
	v_pk_mul_f32 v[76:77], v[104:105], v[76:77] op_sel_hi:[0,1]
	v_pk_mul_f32 v[74:75], v[104:105], v[74:75] op_sel_hi:[0,1]
	v_pk_mul_f32 v[72:73], v[104:105], v[72:73] op_sel_hi:[0,1]
	v_pk_mul_f32 v[70:71], v[104:105], v[70:71] op_sel_hi:[0,1]
	v_pk_mul_f32 v[68:69], v[104:105], v[68:69] op_sel_hi:[0,1]
	v_pk_mul_f32 v[66:67], v[104:105], v[66:67] op_sel_hi:[0,1]
	v_pk_mul_f32 v[64:65], v[104:105], v[64:65] op_sel_hi:[0,1]
	v_pk_mul_f32 v[62:63], v[104:105], v[62:63] op_sel_hi:[0,1]
	v_pk_mul_f32 v[60:61], v[104:105], v[60:61] op_sel_hi:[0,1]
	v_pk_mul_f32 v[58:59], v[104:105], v[58:59] op_sel_hi:[0,1]
	v_pk_mul_f32 v[56:57], v[104:105], v[56:57] op_sel_hi:[0,1]
	v_pk_mul_f32 v[54:55], v[104:105], v[54:55] op_sel_hi:[0,1]
	v_pk_mul_f32 v[52:53], v[104:105], v[52:53] op_sel_hi:[0,1]
	v_mul_f32_e32 v100, v100, v104

; template <int MODE, bool FROZEN = false>
; __device__ __forceinline__ bool attn_unit(LAS unsigned char* lds, const Params& p, int l, int ua, int ub) {
;     ...
;         f32x16 sA0 = sB0, sA1 = sB1;
;         const float c2 = cbB - m_run;
;         const LAS unsigned char* Vb = lds + OFF_V + (t & 1) * VBUF + vlane_off;
;         const LAS unsigned char* Kb = lds + OFF_K + ((t + 1) & 1) * KBUF + klane_off;
;     ...
;         bf16x8 kf0[4], kf1[4], va[NB], vb[NB], pf0, pf1; float ps0, ps1, ps2, ps3;
;         VLOAD(0, va);
;         EXPCVT(0, pf0, ps0);
;         SBAR_();
;         VLOAD(1, vb); PVMMA(va, pf0); EXPCVT(1, pf1, ps1); _Pragma("unroll") for (int g_ = 0; g_ < NB; ++g_) { __builtin_amdgcn_sched_group_barrier(0x008, 1, 0); __builtin_amdgcn_sched_group_barrier(0x100, 1, 0); __builtin_amdgcn_sched_group_barrier(0x400, 8 / NB, 0); __builtin_amdgcn_sched_group_barrier(0x002, 12 / NB, 0); } SBAR_();
;         VLOAD(2, va);
; #pragma unroll
;         for (int d0 = 0; d0 < 4; ++d0) { kf0[d0] = *(const LAS bf16x8*)(Kb + d0 * 32); kf1[d0] = *(const LAS bf16x8*)(Kb + 32 * KPB + d0 * 32); }
;         PVMMA(vb, pf1); EXPCVT(2, pf0, ps2); _Pragma("unroll") for (int g_ = 0; g_ < NB; ++g_) { __builtin_amdgcn_sched_group_barrier(0x008, 1, 0); __builtin_amdgcn_sched_group_barrier(0x100, 1, 0); __builtin_amdgcn_sched_group_barrier(0x400, 8 / NB, 0); __builtin_amdgcn_sched_group_barrier(0x002, 12 / NB, 0); } SBAR_();
;         {
;             f32x16 z0, z1;
; #pragma unroll
;             for (int r = 0; r < 16; ++r) { z0[r] = 0.f; z1[r] = 0.f; }
; #pragma unroll
;             for (int d0 = 0; d0 < 4; ++d0) { z0 = __builtin_amdgcn_mfma_f32_32x32x16_bf16(kf0[d0], qf[d0], z0, 0, 0, 0); z1 = __builtin_amdgcn_mfma_f32_32x32x16_bf16(kf1[d0], qf[d0], z1, 0, 0, 0); }
;             sB0 = z0; sB1 = z1;
;         }
;         EXPCVT(3, pf1, ps3);
; #pragma unroll
;         for (int g_ = 0; g_ < 8; ++g_) { __builtin_amdgcn_sched_group_barrier(0x008, 1, 0); __builtin_amdgcn_sched_group_barrier(0x400, 1, 0); __builtin_amdgcn_sched_group_barrier(0x002, 2, 0); }
;         SBAR_();
;         float tmr;
;         VLOAD(3, vb); SBAR_();
;         PVMMA(va, pf0); if constexpr (!FROZEN) ATT_MAX3(tmr); else tmr = 0.f; PVMMA(vb, pf1);
;         const float ps = (ps0 + ps1) + (ps2 + ps3);
;     ...
;         l_run += ps;
;         if (t + 1 < NT) { ATT_BIAS(t + 1, tmr); ATT_UPD(tmr); }
.LBB0_125:
	s_setprio 0
	v_mfma_f32_32x32x16_bf16 v[52:67], v[236:239], v[244:247], v[52:67]
	v_mfma_f32_32x32x16_bf16 v[36:51], v[218:221], v[244:247], v[36:51]
	v_mfma_f32_32x32x16_bf16 v[84:99], v[222:225], v[244:247], v[84:99]
	v_mfma_f32_32x32x16_bf16 v[68:83], v[248:251], v[244:247], v[68:83]
	v_add_u32_e32 v33, 0x8800, v101
	ds_read_b128 v[104:107], v33 offset:32256
	ds_read_b128 v[108:111], v101 offset:62464
	ds_read_b128 v[112:115], v101 offset:57856
	ds_read_b128 v[116:119], v101 offset:53248
	v_exp_f32_e32 v125, v16
	v_exp_f32_e32 v127, v17
	v_exp_f32_e32 v129, v18
	v_exp_f32_e32 v131, v19
	v_exp_f32_e32 v103, v20
	v_exp_f32_e32 v21, v21
	v_exp_f32_e32 v17, v22
	v_exp_f32_e32 v19, v23
	v_cvt_pk_bf16_f32 v120, v125, v127
	v_cvt_pk_bf16_f32 v121, v129, v131
	v_cvt_pk_bf16_f32 v122, v103, v21
	v_cvt_pk_bf16_f32 v123, v17, v19
	s_waitcnt lgkmcnt(0)
	s_nop 0
	v_mfma_f32_32x32x16_bf16 v[36:51], v[116:119], v[120:123], v[36:51]
	ds_read_b128 v[116:119], v101 offset:53280
	s_waitcnt vmcnt(3)
	v_exp_f32_e32 v133, v24
	v_exp_f32_e32 v135, v25
	s_nop 0
	v_cvt_pk_bf16_f32 v22, v133, v135
	v_mfma_f32_32x32x16_bf16 v[84:99], v[112:115], v[120:123], v[84:99]
	ds_read_b128 v[112:115], v101 offset:57888
	s_waitcnt vmcnt(1)
	v_exp_f32_e32 v137, v26
	v_exp_f32_e32 v139, v27
	s_nop 0
	v_cvt_pk_bf16_f32 v23, v137, v139
	v_mfma_f32_32x32x16_bf16 v[68:83], v[108:111], v[120:123], v[68:83]
	ds_read_b128 v[108:111], v101 offset:62496
	v_exp_f32_e32 v141, v28
	v_exp_f32_e32 v143, v29
	s_nop 0
	v_cvt_pk_bf16_f32 v24, v141, v143
	v_mfma_f32_32x32x16_bf16 v[52:67], v[104:107], v[120:123], v[52:67]
	ds_read_b128 v[26:29], v33 offset:32288
	v_exp_f32_e32 v121, v30
	v_exp_f32_e32 v31, v31
	s_nop 0
	v_cvt_pk_bf16_f32 v25, v121, v31
	s_waitcnt lgkmcnt(3)
	s_nop 0
	v_mfma_f32_32x32x16_bf16 v[36:51], v[116:119], v[22:25], v[36:51]
	ds_read_b128 v[104:107], v101 offset:53312
	v_exp_f32_e32 v124, v0
	v_exp_f32_e32 v126, v1
	s_nop 0
	v_cvt_pk_bf16_f32 v0, v124, v126
	s_waitcnt lgkmcnt(3)
	v_mfma_f32_32x32x16_bf16 v[84:99], v[112:115], v[22:25], v[84:99]
	ds_read_b128 v[112:115], v101 offset:57920
	v_exp_f32_e32 v128, v2
	v_exp_f32_e32 v130, v3
	s_nop 0
	v_cvt_pk_bf16_f32 v1, v128, v130
	s_waitcnt lgkmcnt(3)
	v_mfma_f32_32x32x16_bf16 v[68:83], v[108:111], v[22:25], v[68:83]
	ds_read_b128 v[108:111], v101 offset:62528
	v_exp_f32_e32 v102, v4
	v_exp_f32_e32 v20, v5
	s_nop 0
	v_cvt_pk_bf16_f32 v2, v102, v20
	s_waitcnt lgkmcnt(3)
	v_mfma_f32_32x32x16_bf16 v[52:67], v[26:29], v[22:25], v[52:67]
	ds_read_b128 v[22:25], v33 offset:32320
	v_exp_f32_e32 v16, v6
	v_exp_f32_e32 v18, v7
	s_nop 0
	v_cvt_pk_bf16_f32 v3, v16, v18
	v_exp_f32_e32 v132, v8
	v_exp_f32_e32 v134, v9
	s_nop 0
	v_cvt_pk_bf16_f32 v4, v132, v134
	v_exp_f32_e32 v136, v10
	v_exp_f32_e32 v138, v11
	s_nop 0
	v_cvt_pk_bf16_f32 v5, v136, v138
	v_exp_f32_e32 v140, v12
	v_exp_f32_e32 v142, v13
	s_nop 0
	v_cvt_pk_bf16_f32 v6, v140, v142
	v_exp_f32_e32 v120, v14
	v_exp_f32_e32 v30, v15
	s_nop 0
	v_cvt_pk_bf16_f32 v7, v120, v30
	ds_read_b128 v[8:11], v101 offset:53344
	ds_read_b128 v[12:15], v101 offset:57952
	ds_read_b128 v[26:29], v101 offset:62560
	ds_read_b128 v[116:119], v33 offset:32352
	s_waitcnt lgkmcnt(7)
	v_mfma_f32_32x32x16_bf16 v[36:51], v[104:107], v[0:3], v[36:51]
	v_add_f32_e64 v16, v16, v18
	v_add_f32_e64 v17, v17, v19
	s_waitcnt lgkmcnt(0)
	s_barrier
	v_cmp_eq_u32_e32 vcc, 0, v148
	s_waitcnt lgkmcnt(0)
	s_barrier
	v_mfma_f32_32x32x16_bf16 v[84:99], v[112:115], v[0:3], v[84:99]
	v_mfma_f32_32x32x16_bf16 v[68:83], v[108:111], v[0:3], v[68:83]
	v_mfma_f32_32x32x16_bf16 v[52:67], v[22:25], v[0:3], v[52:67]
	v_add_f32_e64 v0, v124, v126
	v_add_f32_e64 v1, v125, v127
	v_add_f32_e64 v2, v128, v130
	v_add_f32_e64 v3, v129, v131
	v_add_f32_e64 v0, v0, v2
	v_add_f32_e64 v1, v1, v3
	v_pk_add_f32 v[2:3], v[102:103], v[20:21]
	s_nop 0
	v_pk_add_f32 v[2:3], v[2:3], v[16:17]
	v_mfma_f32_32x32x16_bf16 v[36:51], v[8:11], v[4:7], v[36:51]
	v_add_f32_e64 v0, v0, v2
	v_add_f32_e64 v1, v1, v3
	v_add_f32_e64 v2, v132, v134
	v_add_f32_e64 v3, v133, v135
	v_add_f32_e64 v8, v136, v138
	v_add_f32_e64 v9, v137, v139
	v_pk_add_f32 v[10:11], v[120:121], v[30:31]
	v_pk_add_f32 v[2:3], v[2:3], v[8:9]
	v_pk_add_f32 v[8:9], v[140:141], v[142:143]
	v_mfma_f32_32x32x16_bf16 v[84:99], v[12:15], v[4:7], v[84:99]
	v_add_f32_e64 v8, v8, v10
	v_add_f32_e64 v9, v9, v11
	v_add_f32_e64 v2, v2, v8
	v_add_f32_e64 v3, v3, v9
	v_add_f32_e64 v0, v0, v2
	v_add_f32_e64 v1, v1, v3
	v_add_f32_e32 v0, v0, v1
	v_mfma_f32_32x32x16_bf16 v[68:83], v[26:29], v[4:7], v[68:83]
	v_add_f32_e32 v0, v0, v100
	v_mov_b32_e32 v1, v0
	v_mov_b32_e32 v2, v0
	s_nop 1
	v_permlane32_swap_b32_e32 v1, v2
	v_mfma_f32_32x32x16_bf16 v[52:67], v[116:119], v[4:7], v[52:67]
	s_and_saveexec_b64 s[0:1], vcc
	s_cbranch_execz .LBB0_127
	v_readlane_b32 s4, v254, 47
	s_nop 1
	v_mov_b32_e32 v3, s4
	ds_write_b32 v3, v197

; #define PG8_STAGE(bufoff, gbase, voff) do { _Pragma("unroll") for (int _i = 0; _i < 2; ++_i) \
;         __builtin_amdgcn_global_load_lds((const unsigned*)((const char*)(gbase) + (voff)[_i]), (PG8_LAS unsigned*)(lds + (bufoff) + ldsw + _i * 8192), 16, 0, 0); } while (0)
; #define PG8_LDA(dst, b, h) do { _Pragma("unroll") for (int m = 0; m < 4; ++m) _Pragma("unroll") for (int k = 0; k < 2; ++k) dst[m][k] = *(const PG8_LAS bf16x8*)(lds + PG8_SA(b, h) + aoff + m * 2048 + k * 1024); } while (0)
; #define PG8_LDB(dst, b, h) do { _Pragma("unroll") for (int n = 0; n < 2; ++n) _Pragma("unroll") for (int k = 0; k < 2; ++k) dst[n][k] = *(const PG8_LAS bf16x8*)(lds + PG8_SB(b, h) + boff + n * 2048 + k * 1024); } while (0)
; #define PG8_MMA(ai, bj, At, Bt) do { __builtin_amdgcn_s_setprio(1); _Pragma("unroll") for (int m = 0; m < 4; ++m) _Pragma("unroll") for (int n = 0; n < 2; ++n) _Pragma("unroll") for (int k = 0; k < 2; ++k) \
;         acc[ai][bj][m][n] = __builtin_amdgcn_mfma_f32_16x16x32_bf16(Bt[n][k], At[m][k], acc[ai][bj][m][n], 0, 0, 0); __builtin_amdgcn_s_setprio(0); } while (0)
; #define PG8_WAIT_V(n) asm volatile("s_waitcnt vmcnt(" #n ")" ::: "memory")
; template <class Epi, class Sched, bool ALIGN_EPI = false, bool SP2 = false>
; __device__ __forceinline__ void gemm_phase(PG8_LAS unsigned char* lds, const Gemm g, const Sched& S, const Epi& E) {
;     ...
;             PG8_LDB(B0, 0, 0); PG8_LDB(B1, 0, 1); PG8_SCHED; PG8_LDA(At, 0, 0); PG8_STAGE(PG8_SA(1, 1), a1 + hstep, voffA);
;             PG8_WAIT_V(8); PG8_WAIT_L(0); PG8_BAR; PG8_MMA(0, 0, At, B0); PG8_MMA(0, 1, At, B1); PG8_BAR; PG8_SCHED;
;             PG8_LDA(At, 0, 1); PG8_STAGE(PG8_SB(0, 0), b2, voffB); PG8_STAGE(PG8_SB(0, 1), b2 + hstep, voffB); PG8_STAGE(PG8_SA(0, 0), a2, voffA);
;             PG8_WAIT_V(8); PG8_WAIT_L(0); PG8_BAR; PG8_MMA(1, 0, At, B0); PG8_MMA(1, 1, At, B1); PG8_BAR; PG8_SCHED;
;             PG8_LDB(B0, 1, 0); PG8_LDB(B1, 1, 1); PG8_SCHED; PG8_LDA(At, 1, 0); PG8_STAGE(PG8_SA(0, 1), a2 + hstep, voffA);
;             PG8_WAIT_V(8); PG8_WAIT_L(0); PG8_BAR; PG8_MMA(0, 0, At, B0); PG8_MMA(0, 1, At, B1); PG8_BAR; PG8_SCHED;
;             PG8_LDA(At, 1, 1); PG8_STAGE(PG8_SB(1, 0), b3, voffB); PG8_STAGE(PG8_SB(1, 1), b3 + hstep, voffB); PG8_STAGE(PG8_SA(1, 0), a3, voffA);
;             PG8_WAIT_V(8); PG8_WAIT_L(0); PG8_BAR; PG8_MMA(1, 0, At, B0); PG8_MMA(1, 1, At, B1); PG8_BAR; PG8_SCHED;
.LBB0_342:
	s_add_u32 s4, s0, 0xfffc0080
	s_addc_u32 s5, s1, -1
	s_add_i32 s60, 0, 0x10000
	s_cmp_eq_u32 s59, 12
	s_cselect_b32 s43, s21, s5
	s_cselect_b32 s42, s45, s4
	s_cselect_b32 s5, s19, s58
	s_cselect_b32 s4, s46, s47
	s_add_i32 s62, 0, 0x14000
	v_add_u32_e32 v144, s60, v170
	v_add_u32_e32 v174, s62, v170
	ds_read_b128 v[132:135], v144
	ds_read_b128 v[136:139], v144 offset:1024
	ds_read_b128 v[140:143], v144 offset:2048
	ds_read_b128 v[144:147], v144 offset:3072
	ds_read_b128 v[158:161], v174
	ds_read_b128 v[162:165], v174 offset:1024
	ds_read_b128 v[166:169], v174 offset:2048
	ds_read_b128 v[174:177], v174 offset:3072
	v_lshl_add_u64 v[194:195], s[0:1], 0, v[154:155]
	s_add_i32 m0, s50, 0xc000
	ds_read_b128 v[178:181], v173
	ds_read_b128 v[182:185], v173 offset:1024
	ds_read_b128 v[186:189], v173 offset:2048
	ds_read_b128 v[190:193], v173 offset:3072
	ds_read_b128 v[202:205], v173 offset:4096
	ds_read_b128 v[206:209], v173 offset:5120
	ds_read_b128 v[210:213], v173 offset:6144
	ds_read_b128 v[214:217], v173 offset:7168
	global_load_lds_dwordx4 v[194:195], off
	v_lshl_add_u64 v[194:195], s[0:1], 0, v[156:157]
	s_add_i32 m0, s50, 0xe000
	s_nop 0
	global_load_lds_dwordx4 v[194:195], off
	s_waitcnt vmcnt(8)
	s_waitcnt lgkmcnt(0)
	v_mfma_f32_16x16x32_bf16 v[128:131], v[132:135], v[178:181], v[128:131]
	v_mfma_f32_16x16x32_bf16 v[124:127], v[140:143], v[178:181], v[124:127]
	v_mfma_f32_16x16x32_bf16 v[112:115], v[132:135], v[186:189], v[112:115]
	v_mfma_f32_16x16x32_bf16 v[108:111], v[140:143], v[186:189], v[108:111]
	s_barrier
	s_setprio 1
	v_mfma_f32_16x16x32_bf16 v[96:99], v[132:135], v[202:205], v[96:99]
	v_mfma_f32_16x16x32_bf16 v[92:95], v[140:143], v[202:205], v[92:95]
	v_mfma_f32_16x16x32_bf16 v[80:83], v[132:135], v[210:213], v[80:83]
	v_mfma_f32_16x16x32_bf16 v[76:79], v[140:143], v[210:213], v[76:79]
	v_mfma_f32_16x16x32_bf16 v[128:131], v[136:139], v[182:185], v[128:131]
	v_mfma_f32_16x16x32_bf16 v[124:127], v[144:147], v[182:185], v[124:127]
	v_mfma_f32_16x16x32_bf16 v[112:115], v[136:139], v[190:193], v[112:115]
	v_mfma_f32_16x16x32_bf16 v[108:111], v[144:147], v[190:193], v[108:111]
	v_mfma_f32_16x16x32_bf16 v[96:99], v[136:139], v[206:209], v[96:99]
	v_mfma_f32_16x16x32_bf16 v[92:95], v[144:147], v[206:209], v[92:95]
	v_mfma_f32_16x16x32_bf16 v[80:83], v[136:139], v[214:217], v[80:83]
	v_mfma_f32_16x16x32_bf16 v[76:79], v[144:147], v[214:217], v[76:79]
	s_setprio 0
	s_setprio 1
	v_mfma_f32_16x16x32_bf16 v[120:123], v[158:161], v[178:181], v[120:123]
	v_mfma_f32_16x16x32_bf16 v[116:119], v[166:169], v[178:181], v[116:119]
	v_mfma_f32_16x16x32_bf16 v[104:107], v[158:161], v[186:189], v[104:107]
	v_mfma_f32_16x16x32_bf16 v[100:103], v[166:169], v[186:189], v[100:103]
	v_mfma_f32_16x16x32_bf16 v[88:91], v[158:161], v[202:205], v[88:91]
	v_mfma_f32_16x16x32_bf16 v[84:87], v[166:169], v[202:205], v[84:87]
	v_mfma_f32_16x16x32_bf16 v[72:75], v[158:161], v[210:213], v[72:75]
	v_mfma_f32_16x16x32_bf16 v[68:71], v[166:169], v[210:213], v[68:71]
	v_mfma_f32_16x16x32_bf16 v[120:123], v[162:165], v[182:185], v[120:123]
	v_mfma_f32_16x16x32_bf16 v[116:119], v[174:177], v[182:185], v[116:119]
	v_mfma_f32_16x16x32_bf16 v[104:107], v[162:165], v[190:193], v[104:107]
	v_mfma_f32_16x16x32_bf16 v[100:103], v[174:177], v[190:193], v[100:103]
	v_mfma_f32_16x16x32_bf16 v[88:91], v[162:165], v[206:209], v[88:91]
	v_mfma_f32_16x16x32_bf16 v[84:87], v[174:177], v[206:209], v[84:87]
	v_mfma_f32_16x16x32_bf16 v[72:75], v[162:165], v[214:217], v[72:75]
	v_mfma_f32_16x16x32_bf16 v[68:71], v[174:177], v[214:217], v[68:71]
	s_setprio 0
	s_barrier
	s_add_i32 s60, s60, s49
	v_lshl_add_u64 v[194:195], s[4:5], 0, v[150:151]
	s_mov_b32 m0, s60
	ds_read_b128 v[178:181], v173 offset:16384
	ds_read_b128 v[182:185], v173 offset:17408
	ds_read_b128 v[186:189], v173 offset:18432
	ds_read_b128 v[190:193], v173 offset:19456
	ds_read_b128 v[202:205], v173 offset:20480
	ds_read_b128 v[206:209], v173 offset:21504
	ds_read_b128 v[210:213], v173 offset:22528
	ds_read_b128 v[214:217], v173 offset:23552
	global_load_lds_dwordx4 v[194:195], off
	s_add_i32 m0, s60, 0x2000
	s_add_u32 s60, s4, 0x40000
	v_lshl_add_u64 v[218:219], s[4:5], 0, v[32:33]
	s_addc_u32 s61, s5, 0
	s_add_i32 s62, s62, s49
	global_load_lds_dwordx4 v[218:219], off
	v_lshl_add_u64 v[220:221], s[60:61], 0, v[150:151]
	s_mov_b32 m0, s62
	v_lshl_add_u64 v[222:223], s[42:43], 0, v[148:149]
	global_load_lds_dwordx4 v[220:221], off
	v_lshl_add_u64 v[220:221], s[60:61], 0, v[32:33]
	s_add_i32 m0, s62, 0x2000
	s_nop 0
	global_load_lds_dwordx4 v[220:221], off
	v_lshl_add_u64 v[220:221], s[42:43], 0, v[152:153]
	s_mov_b32 m0, s50
	s_nop 0
	global_load_lds_dwordx4 v[220:221], off
	s_mov_b32 m0, s51
	s_nop 0
	global_load_lds_dwordx4 v[222:223], off
	s_waitcnt vmcnt(8)
	s_waitcnt lgkmcnt(0)
	v_mfma_f32_16x16x32_bf16 v[64:67], v[132:135], v[178:181], v[64:67]
	v_mfma_f32_16x16x32_bf16 v[60:63], v[140:143], v[178:181], v[60:63]
	v_mfma_f32_16x16x32_bf16 v[48:51], v[132:135], v[186:189], v[48:51]
	v_mfma_f32_16x16x32_bf16 v[44:47], v[140:143], v[186:189], v[44:47]
	s_barrier
; #define PG8_STAGE(bufoff, gbase, voff) do { _Pragma("unroll") for (int _i = 0; _i < 2; ++_i) \
;         __builtin_amdgcn_global_load_lds((const unsigned*)((const char*)(gbase) + (voff)[_i]), (PG8_LAS unsigned*)(lds + (bufoff) + ldsw + _i * 8192), 16, 0, 0); } while (0)
; #define PG8_LDA(dst, b, h) do { _Pragma("unroll") for (int m = 0; m < 4; ++m) _Pragma("unroll") for (int k = 0; k < 2; ++k) dst[m][k] = *(const PG8_LAS bf16x8*)(lds + PG8_SA(b, h) + aoff + m * 2048 + k * 1024); } while (0)
; #define PG8_LDB(dst, b, h) do { _Pragma("unroll") for (int n = 0; n < 2; ++n) _Pragma("unroll") for (int k = 0; k < 2; ++k) dst[n][k] = *(const PG8_LAS bf16x8*)(lds + PG8_SB(b, h) + boff + n * 2048 + k * 1024); } while (0)
; #define PG8_MMA(ai, bj, At, Bt) do { __builtin_amdgcn_s_setprio(1); _Pragma("unroll") for (int m = 0; m < 4; ++m) _Pragma("unroll") for (int n = 0; n < 2; ++n) _Pragma("unroll") for (int k = 0; k < 2; ++k) \
;         acc[ai][bj][m][n] = __builtin_amdgcn_mfma_f32_16x16x32_bf16(Bt[n][k], At[m][k], acc[ai][bj][m][n], 0, 0, 0); __builtin_amdgcn_s_setprio(0); } while (0)
; #define PG8_WAIT_V(n) asm volatile("s_waitcnt vmcnt(" #n ")" ::: "memory")
; #define PG8_WAIT_L(n) asm volatile("s_waitcnt lgkmcnt(" #n ")" ::: "memory")
; #define PG8_BAR __builtin_amdgcn_s_barrier()
; #define PG8_SCHED __builtin_amdgcn_sched_barrier(0)
; template <class Epi, class Sched, bool ALIGN_EPI = false, bool SP2 = false>
; __device__ __forceinline__ void gemm_phase(PG8_LAS unsigned char* lds, const Gemm g, const Sched& S, const Epi& E) {
;     ...
;             PG8_WAIT_V(8); PG8_WAIT_L(0); PG8_BAR; PG8_MMA(1, 0, At, B0); PG8_MMA(1, 1, At, B1); PG8_BAR; PG8_SCHED;
;             PG8_LDB(B0, 1, 0); PG8_LDB(B1, 1, 1); PG8_SCHED; PG8_LDA(At, 1, 0); PG8_STAGE(PG8_SA(0, 1), a2 + hstep, voffA);
;             PG8_WAIT_V(8); PG8_WAIT_L(0); PG8_BAR; PG8_MMA(0, 0, At, B0); PG8_MMA(0, 1, At, B1); PG8_BAR; PG8_SCHED;
;             PG8_LDA(At, 1, 1); PG8_STAGE(PG8_SB(1, 0), b3, voffB); PG8_STAGE(PG8_SB(1, 1), b3 + hstep, voffB); PG8_STAGE(PG8_SA(1, 0), a3, voffA);
	s_setprio 1
	v_mfma_f32_16x16x32_bf16 v[28:31], v[132:135], v[202:205], v[28:31]
	v_mfma_f32_16x16x32_bf16 v[24:27], v[140:143], v[202:205], v[24:27]
	v_mfma_f32_16x16x32_bf16 v[12:15], v[132:135], v[210:213], v[12:15]
	v_mfma_f32_16x16x32_bf16 v[8:11], v[140:143], v[210:213], v[8:11]
	v_mfma_f32_16x16x32_bf16 v[64:67], v[136:139], v[182:185], v[64:67]
	v_mfma_f32_16x16x32_bf16 v[60:63], v[144:147], v[182:185], v[60:63]
	v_mfma_f32_16x16x32_bf16 v[48:51], v[136:139], v[190:193], v[48:51]
	v_mfma_f32_16x16x32_bf16 v[44:47], v[144:147], v[190:193], v[44:47]
	v_mfma_f32_16x16x32_bf16 v[28:31], v[136:139], v[206:209], v[28:31]
	v_mfma_f32_16x16x32_bf16 v[24:27], v[144:147], v[206:209], v[24:27]
	v_mfma_f32_16x16x32_bf16 v[12:15], v[136:139], v[214:217], v[12:15]
	v_mfma_f32_16x16x32_bf16 v[8:11], v[144:147], v[214:217], v[8:11]
	s_setprio 0
	s_setprio 1
	v_mfma_f32_16x16x32_bf16 v[56:59], v[158:161], v[178:181], v[56:59]
	v_mfma_f32_16x16x32_bf16 v[52:55], v[166:169], v[178:181], v[52:55]
	v_mfma_f32_16x16x32_bf16 v[40:43], v[158:161], v[186:189], v[40:43]
	v_mfma_f32_16x16x32_bf16 v[36:39], v[166:169], v[186:189], v[36:39]
	v_mfma_f32_16x16x32_bf16 v[20:23], v[158:161], v[202:205], v[20:23]
	v_mfma_f32_16x16x32_bf16 v[16:19], v[166:169], v[202:205], v[16:19]
	v_mfma_f32_16x16x32_bf16 v[4:7], v[158:161], v[210:213], v[4:7]
	v_mfma_f32_16x16x32_bf16 v[0:3], v[166:169], v[210:213], v[0:3]
	v_mfma_f32_16x16x32_bf16 v[56:59], v[162:165], v[182:185], v[56:59]
	v_mfma_f32_16x16x32_bf16 v[52:55], v[174:177], v[182:185], v[52:55]
	v_mfma_f32_16x16x32_bf16 v[40:43], v[162:165], v[190:193], v[40:43]
	v_mfma_f32_16x16x32_bf16 v[36:39], v[174:177], v[190:193], v[36:39]
	v_mfma_f32_16x16x32_bf16 v[20:23], v[162:165], v[206:209], v[20:23]
	v_mfma_f32_16x16x32_bf16 v[16:19], v[174:177], v[206:209], v[16:19]
	v_mfma_f32_16x16x32_bf16 v[4:7], v[162:165], v[214:217], v[4:7]
	v_mfma_f32_16x16x32_bf16 v[0:3], v[174:177], v[214:217], v[0:3]
	s_setprio 0
	s_barrier
	s_add_i32 s60, 0, 0x18000
	s_add_i32 s61, 0, 0x1c000
	v_add_u32_e32 v144, s60, v170
	v_add_u32_e32 v174, s61, v170
	ds_read_b128 v[132:135], v144
	ds_read_b128 v[136:139], v144 offset:1024
	ds_read_b128 v[140:143], v144 offset:2048
	ds_read_b128 v[144:147], v144 offset:3072
	ds_read_b128 v[158:161], v174
	ds_read_b128 v[162:165], v174 offset:1024
	ds_read_b128 v[166:169], v174 offset:2048
	ds_read_b128 v[174:177], v174 offset:3072
	s_add_u32 s42, s42, 0x40000
	s_addc_u32 s43, s43, 0
	s_mov_b32 m0, s52
	v_lshl_add_u64 v[224:225], s[42:43], 0, v[152:153]
	ds_read_b128 v[178:181], v173 offset:32768
	ds_read_b128 v[182:185], v173 offset:33792
	ds_read_b128 v[186:189], v173 offset:34816
	ds_read_b128 v[190:193], v173 offset:35840
	ds_read_b128 v[202:205], v173 offset:36864
	ds_read_b128 v[206:209], v173 offset:37888
	ds_read_b128 v[210:213], v173 offset:38912
	ds_read_b128 v[214:217], v173 offset:39936
	global_load_lds_dwordx4 v[224:225], off
	v_lshl_add_u64 v[224:225], s[42:43], 0, v[148:149]
	s_mov_b32 m0, s53
	s_nop 0
	global_load_lds_dwordx4 v[224:225], off
	s_waitcnt vmcnt(8)
	s_waitcnt lgkmcnt(0)
	v_mfma_f32_16x16x32_bf16 v[128:131], v[132:135], v[178:181], v[128:131]
	v_mfma_f32_16x16x32_bf16 v[124:127], v[140:143], v[178:181], v[124:127]
	v_mfma_f32_16x16x32_bf16 v[112:115], v[132:135], v[186:189], v[112:115]
	v_mfma_f32_16x16x32_bf16 v[108:111], v[140:143], v[186:189], v[108:111]
	s_barrier
	s_setprio 1
	v_mfma_f32_16x16x32_bf16 v[96:99], v[132:135], v[202:205], v[96:99]
	v_mfma_f32_16x16x32_bf16 v[92:95], v[140:143], v[202:205], v[92:95]
	v_mfma_f32_16x16x32_bf16 v[80:83], v[132:135], v[210:213], v[80:83]
	v_mfma_f32_16x16x32_bf16 v[76:79], v[140:143], v[210:213], v[76:79]
	v_mfma_f32_16x16x32_bf16 v[128:131], v[136:139], v[182:185], v[128:131]
	v_mfma_f32_16x16x32_bf16 v[124:127], v[144:147], v[182:185], v[124:127]
	v_mfma_f32_16x16x32_bf16 v[112:115], v[136:139], v[190:193], v[112:115]
	v_mfma_f32_16x16x32_bf16 v[108:111], v[144:147], v[190:193], v[108:111]
	v_mfma_f32_16x16x32_bf16 v[96:99], v[136:139], v[206:209], v[96:99]
	v_mfma_f32_16x16x32_bf16 v[92:95], v[144:147], v[206:209], v[92:95]
	v_mfma_f32_16x16x32_bf16 v[80:83], v[136:139], v[214:217], v[80:83]
	v_mfma_f32_16x16x32_bf16 v[76:79], v[144:147], v[214:217], v[76:79]
	s_setprio 0
	s_setprio 1
	v_mfma_f32_16x16x32_bf16 v[120:123], v[158:161], v[178:181], v[120:123]
	v_mfma_f32_16x16x32_bf16 v[116:119], v[166:169], v[178:181], v[116:119]
	v_mfma_f32_16x16x32_bf16 v[104:107], v[158:161], v[186:189], v[104:107]
	v_mfma_f32_16x16x32_bf16 v[100:103], v[166:169], v[186:189], v[100:103]
	v_mfma_f32_16x16x32_bf16 v[88:91], v[158:161], v[202:205], v[88:91]
	v_mfma_f32_16x16x32_bf16 v[84:87], v[166:169], v[202:205], v[84:87]
	v_mfma_f32_16x16x32_bf16 v[72:75], v[158:161], v[210:213], v[72:75]
	v_mfma_f32_16x16x32_bf16 v[68:71], v[166:169], v[210:213], v[68:71]
	v_mfma_f32_16x16x32_bf16 v[120:123], v[162:165], v[182:185], v[120:123]
	v_mfma_f32_16x16x32_bf16 v[116:119], v[174:177], v[182:185], v[116:119]
	v_mfma_f32_16x16x32_bf16 v[104:107], v[162:165], v[190:193], v[104:107]
	v_mfma_f32_16x16x32_bf16 v[100:103], v[174:177], v[190:193], v[100:103]
	v_mfma_f32_16x16x32_bf16 v[88:91], v[162:165], v[206:209], v[88:91]
	v_mfma_f32_16x16x32_bf16 v[84:87], v[174:177], v[206:209], v[84:87]
	v_mfma_f32_16x16x32_bf16 v[72:75], v[162:165], v[214:217], v[72:75]
	v_mfma_f32_16x16x32_bf16 v[68:71], v[174:177], v[214:217], v[68:71]
	s_setprio 0
	s_barrier
; #define PG8_STAGE(bufoff, gbase, voff) do { _Pragma("unroll") for (int _i = 0; _i < 2; ++_i) \
;         __builtin_amdgcn_global_load_lds((const unsigned*)((const char*)(gbase) + (voff)[_i]), (PG8_LAS unsigned*)(lds + (bufoff) + ldsw + _i * 8192), 16, 0, 0); } while (0)
; #define PG8_LDA(dst, b, h) do { _Pragma("unroll") for (int m = 0; m < 4; ++m) _Pragma("unroll") for (int k = 0; k < 2; ++k) dst[m][k] = *(const PG8_LAS bf16x8*)(lds + PG8_SA(b, h) + aoff + m * 2048 + k * 1024); } while (0)
; #define PG8_MMA(ai, bj, At, Bt) do { __builtin_amdgcn_s_setprio(1); _Pragma("unroll") for (int m = 0; m < 4; ++m) _Pragma("unroll") for (int n = 0; n < 2; ++n) _Pragma("unroll") for (int k = 0; k < 2; ++k) \
;         acc[ai][bj][m][n] = __builtin_amdgcn_mfma_f32_16x16x32_bf16(Bt[n][k], At[m][k], acc[ai][bj][m][n], 0, 0, 0); __builtin_amdgcn_s_setprio(0); } while (0)
; #define PG8_WAIT_V(n) asm volatile("s_waitcnt vmcnt(" #n ")" ::: "memory")
; #define PG8_WAIT_L(n) asm volatile("s_waitcnt lgkmcnt(" #n ")" ::: "memory")
; #define PG8_BAR __builtin_amdgcn_s_barrier()
; #define PG8_SCHED __builtin_amdgcn_sched_barrier(0)
; template <class Epi, class Sched, bool ALIGN_EPI = false, bool SP2 = false>
; __device__ __forceinline__ void gemm_phase(PG8_LAS unsigned char* lds, const Gemm g, const Sched& S, const Epi& E) {
;     ...
;             PG8_LDA(At, 1, 1); PG8_STAGE(PG8_SB(1, 0), b3, voffB); PG8_STAGE(PG8_SB(1, 1), b3 + hstep, voffB); PG8_STAGE(PG8_SA(1, 0), a3, voffA);
;             PG8_WAIT_V(8); PG8_WAIT_L(0); PG8_BAR; PG8_MMA(1, 0, At, B0); PG8_MMA(1, 1, At, B1); PG8_BAR; PG8_SCHED;
; __device__ __forceinline__ float rstd_of(const float* ssq, int row) {
;     const f32x4* q = (const f32x4*)(ssq + (size_t)row * 16); const f32x4 a = q[0], b = q[1], c = q[2], d = q[3];
;     const float t = (((a.x + a.y) + (a.z + a.w)) + ((b.x + b.y) + (b.z + b.w))) + (((c.x + c.y) + (c.z + c.w)) + ((d.x + d.y) + (d.z + d.w)));
;     return 1.0f / sqrtf(t * (1.0f / DM) + 1e-6f); }
	s_add_i32 s42, s60, s49
	v_lshl_add_u64 v[194:195], v[194:195], 0, s[36:37]
	s_mov_b32 m0, s42
	ds_read_b128 v[178:181], v173 offset:49152
	ds_read_b128 v[182:185], v173 offset:50176
	ds_read_b128 v[186:189], v173 offset:51200
	ds_read_b128 v[190:193], v173 offset:52224
	ds_read_b128 v[202:205], v173 offset:53248
	ds_read_b128 v[206:209], v173 offset:54272
	ds_read_b128 v[210:213], v173 offset:55296
	ds_read_b128 v[214:217], v173 offset:56320
	global_load_lds_dwordx4 v[194:195], off
	s_add_i32 m0, s42, 0x2000
	s_add_u32 s4, s4, 0x40080
	v_lshl_add_u64 v[194:195], v[218:219], 0, s[36:37]
	s_addc_u32 s5, s5, 0
	s_add_i32 s42, s61, s49
	global_load_lds_dwordx4 v[194:195], off
	v_lshl_add_u64 v[194:195], s[4:5], 0, v[150:151]
	s_mov_b32 m0, s42
	s_nop 0
	global_load_lds_dwordx4 v[194:195], off
	v_lshl_add_u64 v[194:195], s[4:5], 0, v[32:33]
	s_add_i32 m0, s42, 0x2000
	s_nop 0
	global_load_lds_dwordx4 v[194:195], off
	v_lshl_add_u64 v[194:195], v[220:221], 0, s[36:37]
	s_mov_b32 m0, s54
	s_nop 0
	global_load_lds_dwordx4 v[194:195], off
	v_lshl_add_u64 v[194:195], v[222:223], 0, s[36:37]
	s_mov_b32 m0, s55
	s_nop 0
	global_load_lds_dwordx4 v[194:195], off
	s_waitcnt vmcnt(8)
	s_waitcnt lgkmcnt(0)
	v_mfma_f32_16x16x32_bf16 v[64:67], v[132:135], v[178:181], v[64:67]
	v_mfma_f32_16x16x32_bf16 v[60:63], v[140:143], v[178:181], v[60:63]
	v_mfma_f32_16x16x32_bf16 v[48:51], v[132:135], v[186:189], v[48:51]
	v_mfma_f32_16x16x32_bf16 v[44:47], v[140:143], v[186:189], v[44:47]
	s_barrier
	s_setprio 1
	v_mfma_f32_16x16x32_bf16 v[28:31], v[132:135], v[202:205], v[28:31]
	v_mfma_f32_16x16x32_bf16 v[24:27], v[140:143], v[202:205], v[24:27]
	v_mfma_f32_16x16x32_bf16 v[12:15], v[132:135], v[210:213], v[12:15]
	v_mfma_f32_16x16x32_bf16 v[8:11], v[140:143], v[210:213], v[8:11]
	v_mfma_f32_16x16x32_bf16 v[64:67], v[136:139], v[182:185], v[64:67]
	v_mfma_f32_16x16x32_bf16 v[60:63], v[144:147], v[182:185], v[60:63]
	v_mfma_f32_16x16x32_bf16 v[48:51], v[136:139], v[190:193], v[48:51]
	v_mfma_f32_16x16x32_bf16 v[44:47], v[144:147], v[190:193], v[44:47]
	v_mfma_f32_16x16x32_bf16 v[28:31], v[136:139], v[206:209], v[28:31]
	v_mfma_f32_16x16x32_bf16 v[24:27], v[144:147], v[206:209], v[24:27]
	v_mfma_f32_16x16x32_bf16 v[12:15], v[136:139], v[214:217], v[12:15]
	v_mfma_f32_16x16x32_bf16 v[8:11], v[144:147], v[214:217], v[8:11]
	s_setprio 0
	s_setprio 1
	v_mfma_f32_16x16x32_bf16 v[56:59], v[158:161], v[178:181], v[56:59]
	v_mfma_f32_16x16x32_bf16 v[52:55], v[166:169], v[178:181], v[52:55]
	v_mfma_f32_16x16x32_bf16 v[40:43], v[158:161], v[186:189], v[40:43]
	v_mfma_f32_16x16x32_bf16 v[36:39], v[166:169], v[186:189], v[36:39]
	v_mfma_f32_16x16x32_bf16 v[20:23], v[158:161], v[202:205], v[20:23]
	v_mfma_f32_16x16x32_bf16 v[16:19], v[166:169], v[202:205], v[16:19]
	v_mfma_f32_16x16x32_bf16 v[4:7], v[158:161], v[210:213], v[4:7]
	v_mfma_f32_16x16x32_bf16 v[0:3], v[166:169], v[210:213], v[0:3]
	v_mfma_f32_16x16x32_bf16 v[56:59], v[162:165], v[182:185], v[56:59]
	v_mfma_f32_16x16x32_bf16 v[52:55], v[174:177], v[182:185], v[52:55]
	v_mfma_f32_16x16x32_bf16 v[40:43], v[162:165], v[190:193], v[40:43]
	v_mfma_f32_16x16x32_bf16 v[36:39], v[174:177], v[190:193], v[36:39]
	v_mfma_f32_16x16x32_bf16 v[20:23], v[162:165], v[206:209], v[20:23]
	v_mfma_f32_16x16x32_bf16 v[16:19], v[174:177], v[206:209], v[16:19]
	v_mfma_f32_16x16x32_bf16 v[4:7], v[162:165], v[214:217], v[4:7]
	v_mfma_f32_16x16x32_bf16 v[0:3], v[174:177], v[214:217], v[0:3]
	s_setprio 0
	s_barrier
	s_add_i32 s59, s59, 2
	s_add_u32 s0, s0, 0x100
	s_addc_u32 s1, s1, 0
	s_add_u32 s47, s47, 0x100
	s_addc_u32 s58, s58, 0
	s_cmp_gt_u32 s59, 13
	s_cbranch_scc0 .LBB0_342
	s_and_b64 vcc, exec, s[16:17]
	s_cbranch_vccz .LBB0_345
	s_barrier
.LBB0_345:
	v_lshl_add_u32 v158, s44, 8, v35
	v_mbcnt_lo_u32_b32 v210, -1, 0
	v_mbcnt_hi_u32_b32 v210, -1, v210
	v_lshrrev_b32_e32 v211, 4, v210
	v_and_b32_e32 v212, 1, v211
	v_lshrrev_b32_e32 v211, 1, v211
	v_lshlrev_b32_e32 v212, 5, v212
	v_lshl_add_u32 v212, v211, 7, v212
	v_add_u32_e32 v212, v212, v158
	v_mov_b32_e32 v213, 0
	v_lshlrev_b64 v[212:213], 6, v[212:213]
	v_lshl_add_u64 v[212:213], s[14:15], 0, v[212:213]
	global_load_dwordx4 v[132:135], v[212:213], off
	global_load_dwordx4 v[136:139], v[212:213], off offset:16
	global_load_dwordx4 v[140:143], v[212:213], off offset:32
	global_load_dwordx4 v[144:147], v[212:213], off offset:48
	global_load_dwordx4 v[174:177], v[212:213], off offset:1024
	global_load_dwordx4 v[178:181], v[212:213], off offset:1040
	global_load_dwordx4 v[182:185], v[212:213], off offset:1056
	global_load_dwordx4 v[186:189], v[212:213], off offset:1072
	v_and_b32_e32 v214, 15, v210
	v_lshlrev_b32_e32 v214, 2, v214
	v_add_u32_e32 v215, 64, v214
	v_add_u32_e32 v216, 0x80, v214
	v_add_u32_e32 v217, 0xc0, v214
	s_waitcnt vmcnt(4)
	v_add_f32_e32 v132, v132, v133
	v_add_f32_e32 v134, v134, v135
	v_add_f32_e32 v132, v132, v134
	v_add_f32_e32 v136, v136, v137
	v_add_f32_e32 v138, v138, v139
	v_add_f32_e32 v136, v136, v138
	v_add_f32_e32 v140, v140, v141
	v_add_f32_e32 v142, v142, v143
	v_add_f32_e32 v140, v140, v142
	v_add_f32_e32 v144, v144, v145
	v_add_f32_e32 v146, v146, v147
	v_add_f32_e32 v144, v144, v146
	v_add_f32_e32 v132, v132, v136
	v_add_f32_e32 v140, v140, v144
	v_add_f32_e32 v132, v132, v140
	v_fmamk_f32 v132, v132, 0x3a800000, v229
	v_cmp_gt_f32_e32 vcc, 0xf800000, v132
	v_mul_f32_e32 v137, 0x4f800000, v132
	s_nop 0
	v_cndmask_b32_e32 v132, v132, v137, vcc
	v_sqrt_f32_e32 v137, v132
	s_nop 0
	v_add_u32_e32 v138, -1, v137
	v_fma_f32 v139, -v138, v137, v132
	v_cmp_ge_f32_e64 s[100:101], 0, v139
	v_add_u32_e32 v139, 1, v137
	s_nop 0
	v_cndmask_b32_e64 v138, v137, v138, s[100:101]
	v_fma_f32 v137, -v139, v137, v132
	v_cmp_lt_f32_e64 s[100:101], 0, v137
	s_nop 1
	v_cndmask_b32_e64 v137, v138, v139, s[100:101]
	v_mul_f32_e32 v138, 0x37800000, v137
	v_cndmask_b32_e32 v137, v137, v138, vcc
	v_cmp_class_f32_e32 vcc, v132, v230
	s_nop 1
	v_cndmask_b32_e32 v132, v137, v132, vcc
	v_div_scale_f32 v137, s[100:101], v132, v132, 1.0
	v_rcp_f32_e32 v138, v137
	s_nop 0
	v_fma_f32 v139, -v137, v138, 1.0
	v_fmac_f32_e32 v138, v139, v138
	v_div_scale_f32 v139, vcc, 1.0, v132, 1.0
	v_mul_f32_e32 v141, v139, v138
	v_fma_f32 v142, -v137, v141, v139
	v_fmac_f32_e32 v141, v142, v138
	v_fma_f32 v137, -v137, v141, v139
	v_div_fmas_f32 v137, v137, v138, v141
	v_div_fixup_f32 v218, v137, v132, 1.0
	s_waitcnt vmcnt(0)
; __device__ __forceinline__ unsigned pk2(float lo, float hi) { return pg8::cvt_pk_bf16(lo, hi); }
; __device__ __forceinline__ float fast_exp2(float x) { return __builtin_amdgcn_exp2f(x); }
; __device__ __forceinline__ float fast_rcp(float x) { return __builtin_amdgcn_rcpf(x); }
; __device__ __forceinline__ float rstd_of(const float* ssq, int row) {
;     const f32x4* q = (const f32x4*)(ssq + (size_t)row * 16); const f32x4 a = q[0], b = q[1], c = q[2], d = q[3];
;     const float t = (((a.x + a.y) + (a.z + a.w)) + ((b.x + b.y) + (b.z + b.w))) + (((c.x + c.y) + (c.z + c.w)) + ((d.x + d.y) + (d.z + d.w)));
;     return 1.0f / sqrtf(t * (1.0f / DM) + 1e-6f); }
;     __device__ __forceinline__ void operator()(const pg8::f32x4 (&acc)[2][2][4][2], const pg8::Unit& u, int wr, int wc, int fr, int fq) const {
;     ...
;             const int col0 = (u.pn - 15) * 256 + wc * 32 + 8 * fq;
;             f32x4 bb[2][2];
; #pragma unroll
;             for (int bj = 0; bj < 2; ++bj) { bb[bj][0] = *(const f32x4*)(bg + col0 + bj * 128); bb[bj][1] = *(const f32x4*)(bg + col0 + bj * 128 + 4); }
; #pragma unroll
;             for (int ai = 0; ai < 2; ++ai)
; #pragma unroll
;                 for (int m = 0; m < 4; ++m) {
;                     const int row = row0 + ai * 128 + m * 16; const float rs = rstd_of(ssq, row);
; #pragma unroll
;                     for (int bj = 0; bj < 2; ++bj) {
;                         float v[8];
; #pragma unroll
;                         for (int j = 0; j < 4; ++j) { v[j] = fast_rcp(1.0f + fast_exp2(-(acc[ai][bj][m][0][j] * rs + bb[bj][0][j]) * LOG2E)); v[4 + j] = fast_rcp(1.0f + fast_exp2(-(acc[ai][bj][m][1][j] * rs + bb[bj][1][j]) * LOG2E)); }
;                         u32x4 w; w.x = pk2(v[0], v[1]); w.y = pk2(v[2], v[3]); w.z = pk2(v[4], v[5]); w.w = pk2(v[6], v[7]);
;                         *(u32x4*)(G + (size_t)row * NGATE + col0 + bj * 128) = w;
;                     }
	v_add_f32_e32 v174, v174, v175
	v_add_f32_e32 v176, v176, v177
	v_add_f32_e32 v174, v174, v176
	v_add_f32_e32 v178, v178, v179
	v_add_f32_e32 v180, v180, v181
	v_add_f32_e32 v178, v178, v180
	v_add_f32_e32 v182, v182, v183
	v_add_f32_e32 v184, v184, v185
	v_add_f32_e32 v182, v182, v184
	v_add_f32_e32 v186, v186, v187
	v_add_f32_e32 v188, v188, v189
	v_add_f32_e32 v186, v186, v188
	v_add_f32_e32 v174, v174, v178
	v_add_f32_e32 v182, v182, v186
	v_add_f32_e32 v174, v174, v182
	v_fmamk_f32 v174, v174, 0x3a800000, v229
	v_cmp_gt_f32_e32 vcc, 0xf800000, v174
	v_mul_f32_e32 v179, 0x4f800000, v174
	s_nop 0
	v_cndmask_b32_e32 v174, v174, v179, vcc
	v_sqrt_f32_e32 v179, v174
	s_nop 0
	v_add_u32_e32 v180, -1, v179
	v_fma_f32 v181, -v180, v179, v174
	v_cmp_ge_f32_e64 s[100:101], 0, v181
	v_add_u32_e32 v181, 1, v179
	s_nop 0
	v_cndmask_b32_e64 v180, v179, v180, s[100:101]
	v_fma_f32 v179, -v181, v179, v174
	v_cmp_lt_f32_e64 s[100:101], 0, v179
	s_nop 1
	v_cndmask_b32_e64 v179, v180, v181, s[100:101]
	v_mul_f32_e32 v180, 0x37800000, v179
	v_cndmask_b32_e32 v179, v179, v180, vcc
	v_cmp_class_f32_e32 vcc, v174, v230
	s_nop 1
	v_cndmask_b32_e32 v174, v179, v174, vcc
	v_div_scale_f32 v179, s[100:101], v174, v174, 1.0
	v_rcp_f32_e32 v180, v179
	s_nop 0
	v_fma_f32 v181, -v179, v180, 1.0
	v_fmac_f32_e32 v180, v181, v180
	v_div_scale_f32 v181, vcc, 1.0, v174, 1.0
	v_mul_f32_e32 v183, v181, v180
	v_fma_f32 v184, -v179, v183, v181
	v_fmac_f32_e32 v183, v184, v180
	v_fma_f32 v179, -v179, v183, v181
	v_div_fmas_f32 v179, v179, v180, v183
	v_div_fixup_f32 v219, v179, v174, 1.0
	ds_bpermute_b32 v202, v214, v218
	ds_bpermute_b32 v203, v214, v219
	ds_bpermute_b32 v204, v215, v218
	ds_bpermute_b32 v205, v215, v219
	ds_bpermute_b32 v206, v216, v218
	ds_bpermute_b32 v207, v216, v219
	ds_bpermute_b32 v208, v217, v218
	ds_bpermute_b32 v209, v217, v219
	s_waitcnt lgkmcnt(0)
	v_or_b32_e32 v164, 16, v158
	v_or_b32_e32 v162, 32, v158
	s_mov_b64 s[0:1], -1
	s_cmp_gt_i32 s57, 14
	v_ashrrev_i32_e32 v159, 31, v158
	v_ashrrev_i32_e32 v165, 31, v164
	v_ashrrev_i32_e32 v163, 31, v162
	v_or_b32_e32 v160, 48, v158
	s_cbranch_scc0 .LBB0_347
	v_lshl_add_u32 v196, s57, 8, v172
	v_lshl_add_u64 v[132:133], v[196:197], 2, s[12:13]
	global_load_dwordx4 v[144:147], v[132:133], off
	global_load_dwordx4 v[140:143], v[132:133], off offset:16
	global_load_dwordx4 v[136:139], v[132:133], off offset:512
	s_nop 0
	global_load_dwordx4 v[132:135], v[132:133], off offset:528
	s_mov_b32 s4, 0xf800000
	v_readlane_b32 s0, v252, 4
	v_readlane_b32 s1, v252, 5
	s_waitcnt vmcnt(0)
	s_nop 0
	v_mov_b64_e32 v[166:167], s[0:1]
	v_mad_i64_i32 v[174:175], s[0:1], v158, s31, v[166:167]
	s_nop 1
	v_lshlrev_b64 v[168:169], 1, v[196:197]
	s_nop 1
	v_lshl_add_u64 v[178:179], v[174:175], 0, v[168:169]
	s_nop 0
	v_mov_b32_e32 v161, v202
	v_fma_f32 v174, v128, v161, v144
	v_fma_f32 v175, v124, v161, v140
	v_fma_f32 v176, v129, v161, v145
	v_fma_f32 v177, v125, v161, v141
	v_fma_f32 v180, v130, v161, v146
	v_fma_f32 v181, v126, v161, v142
	v_fma_f32 v182, v131, v161, v147
	v_fma_f32 v183, v127, v161, v143
	v_mul_f32_e32 v174, 0xbfb8aa3b, v174
	v_mul_f32_e32 v175, 0xbfb8aa3b, v175
	v_mul_f32_e32 v176, 0xbfb8aa3b, v176
	v_mul_f32_e32 v177, 0xbfb8aa3b, v177
	v_mul_f32_e32 v180, 0xbfb8aa3b, v180
	v_mul_f32_e32 v181, 0xbfb8aa3b, v181
	v_mul_f32_e32 v182, 0xbfb8aa3b, v182
	v_mul_f32_e32 v183, 0xbfb8aa3b, v183
	v_exp_f32_e32 v174, v174
	v_exp_f32_e32 v175, v175
	v_exp_f32_e32 v176, v176
	v_exp_f32_e32 v177, v177
	v_exp_f32_e32 v180, v180
	v_exp_f32_e32 v181, v181
	v_exp_f32_e32 v182, v182
	v_exp_f32_e32 v183, v183
	v_add_f32_e32 v174, 1.0, v174
	v_add_f32_e32 v175, 1.0, v175
	v_add_f32_e32 v176, 1.0, v176
	v_add_f32_e32 v177, 1.0, v177
	v_add_f32_e32 v180, 1.0, v180
	v_add_f32_e32 v181, 1.0, v181
	v_add_f32_e32 v182, 1.0, v182
	v_add_f32_e32 v183, 1.0, v183
	v_rcp_f32_e32 v174, v174
	v_rcp_f32_e32 v188, v175
	v_rcp_f32_e32 v175, v176
	v_rcp_f32_e32 v176, v177
	v_rcp_f32_e32 v177, v180
	v_rcp_f32_e32 v180, v181
	v_rcp_f32_e32 v181, v182
	v_rcp_f32_e32 v182, v183
	v_fma_f32 v187, v117, v161, v133
	v_cvt_pk_bf16_f32 v174, v174, v175
	v_cvt_pk_bf16_f32 v175, v177, v181
	v_cvt_pk_bf16_f32 v176, v188, v176
	v_cvt_pk_bf16_f32 v177, v180, v182
	v_mul_f32_e32 v187, 0xbfb8aa3b, v187
	global_store_dwordx4 v[178:179], v[174:177], off
	v_fma_f32 v180, v118, v161, v134
	v_mul_f32_e32 v180, 0xbfb8aa3b, v180
	v_fma_f32 v177, v122, v161, v138
	v_exp_f32_e32 v174, v187
	v_mul_f32_e32 v177, 0xbfb8aa3b, v177
	v_exp_f32_e32 v177, v177
	v_exp_f32_e32 v180, v180
	v_add_f32_e32 v174, 1.0, v174
	v_rcp_f32_e32 v181, v174
	v_add_f32_e32 v174, 1.0, v177
	v_fma_f32 v184, v120, v161, v136
	v_fma_f32 v185, v116, v161, v132
	v_fma_f32 v186, v121, v161, v137
	v_rcp_f32_e32 v177, v174
	v_add_f32_e32 v174, 1.0, v180
	v_fma_f32 v180, v123, v161, v139
	v_fma_f32 v161, v119, v161, v135
	v_mul_f32_e32 v184, 0xbfb8aa3b, v184
	v_mul_f32_e32 v185, 0xbfb8aa3b, v185
	v_mul_f32_e32 v186, 0xbfb8aa3b, v186
	v_mul_f32_e32 v180, 0xbfb8aa3b, v180
	v_mul_f32_e32 v161, 0xbfb8aa3b, v161
	v_exp_f32_e32 v184, v184
	v_exp_f32_e32 v185, v185
	v_exp_f32_e32 v186, v186
	v_exp_f32_e32 v180, v180
	v_exp_f32_e32 v161, v161
	v_add_f32_e32 v184, 1.0, v184
	v_add_f32_e32 v185, 1.0, v185
	v_add_f32_e32 v175, 1.0, v186
	v_rcp_f32_e32 v182, v174
	v_add_f32_e32 v174, 1.0, v180
	v_add_f32_e32 v161, 1.0, v161
	v_rcp_f32_e32 v183, v184
	v_rcp_f32_e32 v176, v185
	v_rcp_f32_e32 v175, v175
	v_rcp_f32_e32 v180, v174
	v_rcp_f32_e32 v161, v161
	v_cvt_pk_bf16_f32 v176, v176, v181
	v_cvt_pk_bf16_f32 v174, v183, v175
	v_cvt_pk_bf16_f32 v175, v177, v180
	v_cvt_pk_bf16_f32 v177, v182, v161
; __device__ __forceinline__ unsigned pk2(float lo, float hi) { return pg8::cvt_pk_bf16(lo, hi); }
; __device__ __forceinline__ float fast_exp2(float x) { return __builtin_amdgcn_exp2f(x); }
; __device__ __forceinline__ float fast_rcp(float x) { return __builtin_amdgcn_rcpf(x); }
;     __device__ __forceinline__ void operator()(const pg8::f32x4 (&acc)[2][2][4][2], const pg8::Unit& u, int wr, int wc, int fr, int fq) const {
;     ...
;                     const int row = row0 + ai * 128 + m * 16; const float rs = rstd_of(ssq, row);
; #pragma unroll
;                     for (int bj = 0; bj < 2; ++bj) {
;                         float v[8];
; #pragma unroll
;                         for (int j = 0; j < 4; ++j) { v[j] = fast_rcp(1.0f + fast_exp2(-(acc[ai][bj][m][0][j] * rs + bb[bj][0][j]) * LOG2E)); v[4 + j] = fast_rcp(1.0f + fast_exp2(-(acc[ai][bj][m][1][j] * rs + bb[bj][1][j]) * LOG2E)); }
;                         u32x4 w; w.x = pk2(v[0], v[1]); w.y = pk2(v[2], v[3]); w.z = pk2(v[4], v[5]); w.w = pk2(v[6], v[7]);
;                         *(u32x4*)(G + (size_t)row * NGATE + col0 + bj * 128) = w;
	global_store_dwordx4 v[178:179], v[174:177], off offset:256
	s_nop 1
	v_mov_b32_e32 v161, v203
	v_fma_f32 v175, v108, v161, v140
	v_fma_f32 v176, v113, v161, v145
	v_fma_f32 v177, v109, v161, v141
	v_fma_f32 v178, v114, v161, v146
	v_mul_f32_e32 v175, 0xbfb8aa3b, v175
	v_mul_f32_e32 v176, 0xbfb8aa3b, v176
	v_mul_f32_e32 v177, 0xbfb8aa3b, v177
	v_mul_f32_e32 v178, 0xbfb8aa3b, v178
	v_exp_f32_e32 v175, v175
	v_exp_f32_e32 v176, v176
	v_exp_f32_e32 v177, v177
	v_exp_f32_e32 v178, v178
	v_add_f32_e32 v175, 1.0, v175
	v_add_f32_e32 v176, 1.0, v176
	v_add_f32_e32 v177, 1.0, v177
	v_add_f32_e32 v178, 1.0, v178
	v_fma_f32 v174, v112, v161, v144
	v_fma_f32 v179, v110, v161, v142
	v_fma_f32 v180, v115, v161, v147
	v_rcp_f32_e32 v181, v175
	v_rcp_f32_e32 v175, v176
	v_rcp_f32_e32 v176, v177
	v_rcp_f32_e32 v177, v178
	v_fma_f32 v178, v111, v161, v143
	v_mul_f32_e32 v174, 0xbfb8aa3b, v174
	v_mul_f32_e32 v179, 0xbfb8aa3b, v179
	v_mul_f32_e32 v180, 0xbfb8aa3b, v180
	v_mul_f32_e32 v178, 0xbfb8aa3b, v178
	v_exp_f32_e32 v174, v174
	v_exp_f32_e32 v179, v179
	v_exp_f32_e32 v180, v180
	v_exp_f32_e32 v178, v178
	v_add_f32_e32 v174, 1.0, v174
	v_add_f32_e32 v179, 1.0, v179
	v_add_f32_e32 v180, 1.0, v180
	v_add_f32_e32 v178, 1.0, v178
	v_rcp_f32_e32 v174, v174
	v_rcp_f32_e32 v179, v179
	v_rcp_f32_e32 v180, v180
	v_rcp_f32_e32 v178, v178
	v_cvt_pk_bf16_f32 v174, v174, v175
	v_cvt_pk_bf16_f32 v176, v181, v176
	v_cvt_pk_bf16_f32 v175, v177, v180
	v_cvt_pk_bf16_f32 v177, v179, v178
	v_mad_i64_i32 v[178:179], s[0:1], v164, s31, v[166:167]
	v_lshl_add_u64 v[178:179], v[178:179], 0, v[168:169]
	v_fma_f32 v181, v100, v161, v132
	v_fma_f32 v180, v104, v161, v136
	v_mul_f32_e32 v181, 0xbfb8aa3b, v181
	global_store_dwordx4 v[178:179], v[174:177], off
	v_mul_f32_e32 v180, 0xbfb8aa3b, v180
	v_exp_f32_e32 v181, v181
	v_fma_f32 v176, v105, v161, v137
	v_fma_f32 v177, v101, v161, v133
	v_mul_f32_e32 v176, 0xbfb8aa3b, v176
	v_mul_f32_e32 v177, 0xbfb8aa3b, v177
	v_exp_f32_e32 v180, v180
	v_exp_f32_e32 v176, v176
	v_exp_f32_e32 v177, v177
	v_add_f32_e32 v175, 1.0, v181
	v_add_f32_e32 v174, 1.0, v180
	v_rcp_f32_e32 v180, v175
	v_add_f32_e32 v175, 1.0, v176
	v_add_f32_e32 v176, 1.0, v177
	v_fma_f32 v177, v106, v161, v138
	v_fma_f32 v181, v102, v161, v134
	v_fma_f32 v182, v107, v161, v139
	v_fma_f32 v161, v103, v161, v135
	v_mul_f32_e32 v177, 0xbfb8aa3b, v177
	v_mul_f32_e32 v181, 0xbfb8aa3b, v181
	v_mul_f32_e32 v182, 0xbfb8aa3b, v182
	v_mul_f32_e32 v161, 0xbfb8aa3b, v161
	v_exp_f32_e32 v177, v177
	v_exp_f32_e32 v181, v181
	v_exp_f32_e32 v182, v182
	v_exp_f32_e32 v161, v161
	v_add_f32_e32 v177, 1.0, v177
	v_add_f32_e32 v181, 1.0, v181
	v_add_f32_e32 v182, 1.0, v182
	v_add_f32_e32 v161, 1.0, v161
	v_rcp_f32_e32 v174, v174
	v_rcp_f32_e32 v175, v175
	v_rcp_f32_e32 v176, v176
	v_rcp_f32_e32 v177, v177
	v_rcp_f32_e32 v181, v181
	v_rcp_f32_e32 v182, v182
	v_rcp_f32_e32 v161, v161
	v_cvt_pk_bf16_f32 v174, v174, v175
	v_cvt_pk_bf16_f32 v176, v180, v176
	v_cvt_pk_bf16_f32 v175, v177, v182
	v_cvt_pk_bf16_f32 v177, v181, v161
	global_store_dwordx4 v[178:179], v[174:177], off offset:256
	s_nop 1
	v_mov_b32_e32 v161, v204
	v_fma_f32 v175, v92, v161, v140
	v_mul_f32_e32 v175, 0xbfb8aa3b, v175
	v_fma_f32 v176, v97, v161, v145
	v_fma_f32 v177, v93, v161, v141
	v_exp_f32_e32 v175, v175
	v_mul_f32_e32 v176, 0xbfb8aa3b, v176
	v_mul_f32_e32 v177, 0xbfb8aa3b, v177
	v_exp_f32_e32 v176, v176
	v_exp_f32_e32 v177, v177
	v_add_f32_e32 v175, 1.0, v175
	v_fma_f32 v174, v96, v161, v144
	v_rcp_f32_e32 v178, v175
	v_add_f32_e32 v175, 1.0, v176
	v_add_f32_e32 v176, 1.0, v177
	v_fma_f32 v177, v98, v161, v146
	v_fma_f32 v179, v94, v161, v142
	v_fma_f32 v180, v99, v161, v147
	v_fma_f32 v181, v95, v161, v143
	v_mul_f32_e32 v174, 0xbfb8aa3b, v174
	v_mul_f32_e32 v177, 0xbfb8aa3b, v177
	v_mul_f32_e32 v179, 0xbfb8aa3b, v179
	v_mul_f32_e32 v180, 0xbfb8aa3b, v180
	v_mul_f32_e32 v181, 0xbfb8aa3b, v181
	v_exp_f32_e32 v174, v174
	v_exp_f32_e32 v177, v177
	v_exp_f32_e32 v179, v179
	v_exp_f32_e32 v180, v180
	v_exp_f32_e32 v181, v181
	v_add_f32_e32 v174, 1.0, v174
	v_add_f32_e32 v177, 1.0, v177
	v_add_f32_e32 v179, 1.0, v179
	v_add_f32_e32 v180, 1.0, v180
	v_add_f32_e32 v181, 1.0, v181
	v_rcp_f32_e32 v174, v174
	v_rcp_f32_e32 v175, v175
	v_rcp_f32_e32 v176, v176
	v_rcp_f32_e32 v177, v177
	v_rcp_f32_e32 v179, v179
	v_rcp_f32_e32 v180, v180
	v_rcp_f32_e32 v181, v181
	v_cvt_pk_bf16_f32 v174, v174, v175
	v_cvt_pk_bf16_f32 v176, v178, v176
	v_cvt_pk_bf16_f32 v175, v177, v180
	v_cvt_pk_bf16_f32 v177, v179, v181
	v_mad_i64_i32 v[178:179], s[0:1], v162, s31, v[166:167]
	v_lshl_add_u64 v[178:179], v[178:179], 0, v[168:169]
	v_fma_f32 v181, v84, v161, v132
	v_fma_f32 v180, v88, v161, v136
	v_mul_f32_e32 v181, 0xbfb8aa3b, v181
	global_store_dwordx4 v[178:179], v[174:177], off
	v_mul_f32_e32 v180, 0xbfb8aa3b, v180
	v_exp_f32_e32 v181, v181
	v_fma_f32 v176, v89, v161, v137
	v_fma_f32 v177, v85, v161, v133
	v_mul_f32_e32 v176, 0xbfb8aa3b, v176
	v_mul_f32_e32 v177, 0xbfb8aa3b, v177
	v_exp_f32_e32 v180, v180
	v_exp_f32_e32 v176, v176
	v_exp_f32_e32 v177, v177
	v_add_f32_e32 v175, 1.0, v181
	v_add_f32_e32 v174, 1.0, v180
	v_rcp_f32_e32 v180, v175
	v_add_f32_e32 v175, 1.0, v176
	v_add_f32_e32 v176, 1.0, v177
	v_fma_f32 v177, v90, v161, v138
	v_fma_f32 v181, v86, v161, v134
	v_fma_f32 v182, v91, v161, v139
	v_fma_f32 v161, v87, v161, v135
	v_mul_f32_e32 v177, 0xbfb8aa3b, v177
	v_mul_f32_e32 v181, 0xbfb8aa3b, v181
	v_mul_f32_e32 v182, 0xbfb8aa3b, v182
	v_mul_f32_e32 v161, 0xbfb8aa3b, v161
	v_exp_f32_e32 v177, v177
	v_exp_f32_e32 v181, v181
	v_exp_f32_e32 v182, v182
	v_exp_f32_e32 v161, v161
	v_add_f32_e32 v177, 1.0, v177
	v_add_f32_e32 v181, 1.0, v181
; __device__ __forceinline__ unsigned pk2(float lo, float hi) { return pg8::cvt_pk_bf16(lo, hi); }
; __device__ __forceinline__ float fast_exp2(float x) { return __builtin_amdgcn_exp2f(x); }
; __device__ __forceinline__ float fast_rcp(float x) { return __builtin_amdgcn_rcpf(x); }
;     __device__ __forceinline__ void operator()(const pg8::f32x4 (&acc)[2][2][4][2], const pg8::Unit& u, int wr, int wc, int fr, int fq) const {
;     ...
;                     const int row = row0 + ai * 128 + m * 16; const float rs = rstd_of(ssq, row);
; #pragma unroll
;                     for (int bj = 0; bj < 2; ++bj) {
;                         float v[8];
; #pragma unroll
;                         for (int j = 0; j < 4; ++j) { v[j] = fast_rcp(1.0f + fast_exp2(-(acc[ai][bj][m][0][j] * rs + bb[bj][0][j]) * LOG2E)); v[4 + j] = fast_rcp(1.0f + fast_exp2(-(acc[ai][bj][m][1][j] * rs + bb[bj][1][j]) * LOG2E)); }
;                         u32x4 w; w.x = pk2(v[0], v[1]); w.y = pk2(v[2], v[3]); w.z = pk2(v[4], v[5]); w.w = pk2(v[6], v[7]);
;                         *(u32x4*)(G + (size_t)row * NGATE + col0 + bj * 128) = w;
	v_add_f32_e32 v182, 1.0, v182
	v_add_f32_e32 v161, 1.0, v161
	v_rcp_f32_e32 v174, v174
	v_rcp_f32_e32 v175, v175
	v_rcp_f32_e32 v176, v176
	v_rcp_f32_e32 v177, v177
	v_rcp_f32_e32 v181, v181
	v_rcp_f32_e32 v182, v182
	v_rcp_f32_e32 v161, v161
	v_cvt_pk_bf16_f32 v174, v174, v175
	v_cvt_pk_bf16_f32 v176, v180, v176
	v_cvt_pk_bf16_f32 v175, v177, v182
	v_cvt_pk_bf16_f32 v177, v181, v161
	global_store_dwordx4 v[178:179], v[174:177], off offset:256
	s_nop 1
	v_add_u32_e32 v190, 0x80, v158
	v_ashrrev_i32_e32 v191, 31, v190
	s_nop 1
	v_mov_b32_e32 v161, v205
	v_fma_f32 v175, v76, v161, v140
	v_mul_f32_e32 v175, 0xbfb8aa3b, v175
	v_fma_f32 v176, v81, v161, v145
	v_fma_f32 v177, v77, v161, v141
	v_exp_f32_e32 v175, v175
	v_mul_f32_e32 v176, 0xbfb8aa3b, v176
	v_mul_f32_e32 v177, 0xbfb8aa3b, v177
	v_exp_f32_e32 v176, v176
	v_exp_f32_e32 v177, v177
	v_add_f32_e32 v175, 1.0, v175
	v_fma_f32 v174, v80, v161, v144
	v_rcp_f32_e32 v178, v175
	v_add_f32_e32 v175, 1.0, v176
	v_add_f32_e32 v176, 1.0, v177
	v_fma_f32 v177, v82, v161, v146
	v_fma_f32 v179, v78, v161, v142
	v_fma_f32 v180, v83, v161, v147
	v_fma_f32 v181, v79, v161, v143
	v_mul_f32_e32 v174, 0xbfb8aa3b, v174
	v_mul_f32_e32 v177, 0xbfb8aa3b, v177
	v_mul_f32_e32 v179, 0xbfb8aa3b, v179
	v_mul_f32_e32 v180, 0xbfb8aa3b, v180
	v_mul_f32_e32 v181, 0xbfb8aa3b, v181
	v_exp_f32_e32 v174, v174
	v_exp_f32_e32 v177, v177
	v_exp_f32_e32 v179, v179
	v_exp_f32_e32 v180, v180
	v_exp_f32_e32 v181, v181
	v_add_f32_e32 v174, 1.0, v174
	v_add_f32_e32 v177, 1.0, v177
	v_add_f32_e32 v179, 1.0, v179
	v_add_f32_e32 v180, 1.0, v180
	v_add_f32_e32 v181, 1.0, v181
	v_rcp_f32_e32 v174, v174
	v_rcp_f32_e32 v175, v175
	v_rcp_f32_e32 v176, v176
	v_rcp_f32_e32 v177, v177
	v_rcp_f32_e32 v179, v179
	v_rcp_f32_e32 v180, v180
	v_rcp_f32_e32 v181, v181
	v_cvt_pk_bf16_f32 v174, v174, v175
	v_cvt_pk_bf16_f32 v176, v178, v176
	v_cvt_pk_bf16_f32 v175, v177, v180
	v_cvt_pk_bf16_f32 v177, v179, v181
	v_mad_i64_i32 v[178:179], s[0:1], v160, s31, v[166:167]
	v_lshl_add_u64 v[178:179], v[178:179], 0, v[168:169]
	v_fma_f32 v181, v68, v161, v132
	v_fma_f32 v180, v72, v161, v136
	v_mul_f32_e32 v181, 0xbfb8aa3b, v181
	global_store_dwordx4 v[178:179], v[174:177], off
	v_mul_f32_e32 v180, 0xbfb8aa3b, v180
	v_exp_f32_e32 v181, v181
	v_fma_f32 v176, v73, v161, v137
	v_fma_f32 v177, v69, v161, v133
	v_mul_f32_e32 v176, 0xbfb8aa3b, v176
	v_mul_f32_e32 v177, 0xbfb8aa3b, v177
	v_exp_f32_e32 v180, v180
	v_exp_f32_e32 v176, v176
	v_exp_f32_e32 v177, v177
	v_add_f32_e32 v175, 1.0, v181
	v_add_f32_e32 v174, 1.0, v180
	v_rcp_f32_e32 v180, v175
	v_add_f32_e32 v175, 1.0, v176
	v_add_f32_e32 v176, 1.0, v177
	v_fma_f32 v177, v74, v161, v138
	v_fma_f32 v181, v70, v161, v134
	v_fma_f32 v182, v75, v161, v139
	v_fma_f32 v161, v71, v161, v135
	v_mul_f32_e32 v177, 0xbfb8aa3b, v177
	v_mul_f32_e32 v181, 0xbfb8aa3b, v181
	v_mul_f32_e32 v182, 0xbfb8aa3b, v182
	v_mul_f32_e32 v161, 0xbfb8aa3b, v161
	v_exp_f32_e32 v177, v177
	v_exp_f32_e32 v181, v181
	v_exp_f32_e32 v182, v182
	v_exp_f32_e32 v161, v161
	v_add_f32_e32 v177, 1.0, v177
	v_add_f32_e32 v181, 1.0, v181
	v_add_f32_e32 v182, 1.0, v182
	v_add_f32_e32 v161, 1.0, v161
	v_rcp_f32_e32 v174, v174
	v_rcp_f32_e32 v175, v175
	v_rcp_f32_e32 v176, v176
	v_rcp_f32_e32 v177, v177
	v_rcp_f32_e32 v181, v181
	v_rcp_f32_e32 v182, v182
	v_rcp_f32_e32 v161, v161
	v_cvt_pk_bf16_f32 v174, v174, v175
	v_cvt_pk_bf16_f32 v176, v180, v176
	v_cvt_pk_bf16_f32 v175, v177, v182
	v_cvt_pk_bf16_f32 v177, v181, v161
	global_store_dwordx4 v[178:179], v[174:177], off offset:256
	s_nop 1
	v_mov_b32_e32 v161, v206
	v_fma_f32 v175, v60, v161, v140
	v_mul_f32_e32 v175, 0xbfb8aa3b, v175
	v_fma_f32 v176, v65, v161, v145
	v_fma_f32 v177, v61, v161, v141
	v_exp_f32_e32 v175, v175
	v_mul_f32_e32 v176, 0xbfb8aa3b, v176
	v_mul_f32_e32 v177, 0xbfb8aa3b, v177
	v_exp_f32_e32 v176, v176
	v_exp_f32_e32 v177, v177
	v_add_f32_e32 v175, 1.0, v175
	v_fma_f32 v174, v64, v161, v144
	v_rcp_f32_e32 v178, v175
	v_add_f32_e32 v175, 1.0, v176
	v_add_f32_e32 v176, 1.0, v177
	v_fma_f32 v177, v66, v161, v146
	v_fma_f32 v179, v62, v161, v142
	v_fma_f32 v180, v67, v161, v147
	v_fma_f32 v181, v63, v161, v143
	v_mul_f32_e32 v174, 0xbfb8aa3b, v174
	v_mul_f32_e32 v177, 0xbfb8aa3b, v177
	v_mul_f32_e32 v179, 0xbfb8aa3b, v179
	v_mul_f32_e32 v180, 0xbfb8aa3b, v180
	v_mul_f32_e32 v181, 0xbfb8aa3b, v181
	v_exp_f32_e32 v174, v174
	v_exp_f32_e32 v177, v177
	v_exp_f32_e32 v179, v179
	v_exp_f32_e32 v180, v180
	v_exp_f32_e32 v181, v181
	v_add_f32_e32 v174, 1.0, v174
	v_add_f32_e32 v177, 1.0, v177
	v_add_f32_e32 v179, 1.0, v179
	v_add_f32_e32 v180, 1.0, v180
	v_add_f32_e32 v181, 1.0, v181
	v_rcp_f32_e32 v174, v174
	v_rcp_f32_e32 v175, v175
	v_rcp_f32_e32 v176, v176
	v_rcp_f32_e32 v177, v177
	v_rcp_f32_e32 v179, v179
	v_rcp_f32_e32 v180, v180
	v_rcp_f32_e32 v181, v181
	v_cvt_pk_bf16_f32 v174, v174, v175
	v_cvt_pk_bf16_f32 v176, v178, v176
	v_cvt_pk_bf16_f32 v175, v177, v180
	v_cvt_pk_bf16_f32 v177, v179, v181
	v_mad_i64_i32 v[178:179], s[0:1], v190, s31, v[166:167]
	v_lshl_add_u64 v[178:179], v[178:179], 0, v[168:169]
	v_fma_f32 v181, v52, v161, v132
	v_fma_f32 v180, v56, v161, v136
	v_mul_f32_e32 v181, 0xbfb8aa3b, v181
	global_store_dwordx4 v[178:179], v[174:177], off
	v_mul_f32_e32 v180, 0xbfb8aa3b, v180
	v_exp_f32_e32 v181, v181
	v_fma_f32 v176, v57, v161, v137
	v_fma_f32 v177, v53, v161, v133
	v_mul_f32_e32 v176, 0xbfb8aa3b, v176
	v_mul_f32_e32 v177, 0xbfb8aa3b, v177
	v_exp_f32_e32 v180, v180
	v_exp_f32_e32 v176, v176
	v_exp_f32_e32 v177, v177
	v_add_f32_e32 v175, 1.0, v181
	v_add_f32_e32 v174, 1.0, v180
	v_rcp_f32_e32 v180, v175
	v_add_f32_e32 v175, 1.0, v176
	v_add_f32_e32 v176, 1.0, v177
; __device__ __forceinline__ unsigned pk2(float lo, float hi) { return pg8::cvt_pk_bf16(lo, hi); }
; __device__ __forceinline__ float fast_exp2(float x) { return __builtin_amdgcn_exp2f(x); }
; __device__ __forceinline__ float fast_rcp(float x) { return __builtin_amdgcn_rcpf(x); }
;     __device__ __forceinline__ void operator()(const pg8::f32x4 (&acc)[2][2][4][2], const pg8::Unit& u, int wr, int wc, int fr, int fq) const {
;     ...
;                     const int row = row0 + ai * 128 + m * 16; const float rs = rstd_of(ssq, row);
; #pragma unroll
;                     for (int bj = 0; bj < 2; ++bj) {
;                         float v[8];
; #pragma unroll
;                         for (int j = 0; j < 4; ++j) { v[j] = fast_rcp(1.0f + fast_exp2(-(acc[ai][bj][m][0][j] * rs + bb[bj][0][j]) * LOG2E)); v[4 + j] = fast_rcp(1.0f + fast_exp2(-(acc[ai][bj][m][1][j] * rs + bb[bj][1][j]) * LOG2E)); }
;                         u32x4 w; w.x = pk2(v[0], v[1]); w.y = pk2(v[2], v[3]); w.z = pk2(v[4], v[5]); w.w = pk2(v[6], v[7]);
;                         *(u32x4*)(G + (size_t)row * NGATE + col0 + bj * 128) = w;
	v_fma_f32 v177, v58, v161, v138
	v_fma_f32 v181, v54, v161, v134
	v_fma_f32 v182, v59, v161, v139
	v_fma_f32 v161, v55, v161, v135
	v_mul_f32_e32 v177, 0xbfb8aa3b, v177
	v_mul_f32_e32 v181, 0xbfb8aa3b, v181
	v_mul_f32_e32 v182, 0xbfb8aa3b, v182
	v_mul_f32_e32 v161, 0xbfb8aa3b, v161
	v_exp_f32_e32 v177, v177
	v_exp_f32_e32 v181, v181
	v_exp_f32_e32 v182, v182
	v_exp_f32_e32 v161, v161
	v_add_f32_e32 v177, 1.0, v177
	v_add_f32_e32 v181, 1.0, v181
	v_add_f32_e32 v182, 1.0, v182
	v_add_f32_e32 v161, 1.0, v161
	v_rcp_f32_e32 v174, v174
	v_rcp_f32_e32 v175, v175
	v_rcp_f32_e32 v176, v176
	v_rcp_f32_e32 v177, v177
	v_rcp_f32_e32 v181, v181
	v_rcp_f32_e32 v182, v182
	v_rcp_f32_e32 v161, v161
	v_add_u32_e32 v190, 0x90, v158
	v_cvt_pk_bf16_f32 v174, v174, v175
	v_cvt_pk_bf16_f32 v175, v177, v182
	v_cvt_pk_bf16_f32 v176, v180, v176
	v_cvt_pk_bf16_f32 v177, v181, v161
	global_store_dwordx4 v[178:179], v[174:177], off offset:256
	s_nop 1
	v_mov_b32_e32 v161, v207
	v_fma_f32 v175, v44, v161, v140
	v_mul_f32_e32 v175, 0xbfb8aa3b, v175
	v_fma_f32 v176, v49, v161, v145
	v_fma_f32 v177, v45, v161, v141
	v_exp_f32_e32 v175, v175
	v_mul_f32_e32 v176, 0xbfb8aa3b, v176
	v_mul_f32_e32 v177, 0xbfb8aa3b, v177
	v_exp_f32_e32 v176, v176
	v_exp_f32_e32 v177, v177
	v_add_f32_e32 v175, 1.0, v175
	v_fma_f32 v174, v48, v161, v144
	v_rcp_f32_e32 v178, v175
	v_add_f32_e32 v175, 1.0, v176
	v_add_f32_e32 v176, 1.0, v177
	v_fma_f32 v177, v50, v161, v146
	v_fma_f32 v179, v46, v161, v142
	v_fma_f32 v180, v51, v161, v147
	v_fma_f32 v181, v47, v161, v143
	v_mul_f32_e32 v174, 0xbfb8aa3b, v174
	v_mul_f32_e32 v177, 0xbfb8aa3b, v177
	v_mul_f32_e32 v179, 0xbfb8aa3b, v179
	v_mul_f32_e32 v180, 0xbfb8aa3b, v180
	v_mul_f32_e32 v181, 0xbfb8aa3b, v181
	v_exp_f32_e32 v174, v174
	v_exp_f32_e32 v177, v177
	v_exp_f32_e32 v179, v179
	v_exp_f32_e32 v180, v180
	v_exp_f32_e32 v181, v181
	v_add_f32_e32 v174, 1.0, v174
	v_add_f32_e32 v177, 1.0, v177
	v_add_f32_e32 v179, 1.0, v179
	v_add_f32_e32 v180, 1.0, v180
	v_add_f32_e32 v181, 1.0, v181
	v_rcp_f32_e32 v174, v174
	v_rcp_f32_e32 v175, v175
	v_rcp_f32_e32 v176, v176
	v_rcp_f32_e32 v177, v177
	v_rcp_f32_e32 v179, v179
	v_rcp_f32_e32 v180, v180
	v_rcp_f32_e32 v181, v181
	v_cvt_pk_bf16_f32 v174, v174, v175
	v_cvt_pk_bf16_f32 v176, v178, v176
	v_cvt_pk_bf16_f32 v175, v177, v180
	v_cvt_pk_bf16_f32 v177, v179, v181
	v_mad_i64_i32 v[178:179], s[0:1], v190, s31, v[166:167]
	v_lshl_add_u64 v[178:179], v[178:179], 0, v[168:169]
	v_fma_f32 v181, v36, v161, v132
	v_fma_f32 v180, v40, v161, v136
	v_mul_f32_e32 v181, 0xbfb8aa3b, v181
	global_store_dwordx4 v[178:179], v[174:177], off
	v_mul_f32_e32 v180, 0xbfb8aa3b, v180
	v_exp_f32_e32 v181, v181
	v_fma_f32 v176, v41, v161, v137
	v_fma_f32 v177, v37, v161, v133
	v_mul_f32_e32 v176, 0xbfb8aa3b, v176
	v_mul_f32_e32 v177, 0xbfb8aa3b, v177
	v_exp_f32_e32 v180, v180
	v_exp_f32_e32 v176, v176
	v_exp_f32_e32 v177, v177
	v_add_f32_e32 v175, 1.0, v181
	v_add_f32_e32 v174, 1.0, v180
	v_rcp_f32_e32 v180, v175
	v_add_f32_e32 v175, 1.0, v176
	v_add_f32_e32 v176, 1.0, v177
	v_fma_f32 v177, v42, v161, v138
	v_fma_f32 v181, v38, v161, v134
	v_fma_f32 v182, v43, v161, v139
	v_fma_f32 v161, v39, v161, v135
	v_mul_f32_e32 v177, 0xbfb8aa3b, v177
	v_mul_f32_e32 v181, 0xbfb8aa3b, v181
	v_mul_f32_e32 v182, 0xbfb8aa3b, v182
	v_mul_f32_e32 v161, 0xbfb8aa3b, v161
	v_exp_f32_e32 v177, v177
	v_exp_f32_e32 v181, v181
	v_exp_f32_e32 v182, v182
	v_exp_f32_e32 v161, v161
	v_add_f32_e32 v177, 1.0, v177
	v_add_f32_e32 v181, 1.0, v181
	v_add_f32_e32 v182, 1.0, v182
	v_add_f32_e32 v161, 1.0, v161
	v_rcp_f32_e32 v174, v174
	v_rcp_f32_e32 v175, v175
	v_rcp_f32_e32 v176, v176
	v_rcp_f32_e32 v177, v177
	v_rcp_f32_e32 v181, v181
	v_rcp_f32_e32 v182, v182
	v_rcp_f32_e32 v161, v161
	v_add_u32_e32 v190, 0xa0, v158
	v_cvt_pk_bf16_f32 v174, v174, v175
	v_cvt_pk_bf16_f32 v175, v177, v182
	v_cvt_pk_bf16_f32 v176, v180, v176
	v_cvt_pk_bf16_f32 v177, v181, v161
	global_store_dwordx4 v[178:179], v[174:177], off offset:256
	s_nop 1
	v_mov_b32_e32 v161, v208
	v_fma_f32 v175, v24, v161, v140
	v_mul_f32_e32 v175, 0xbfb8aa3b, v175
	v_fma_f32 v176, v29, v161, v145
	v_fma_f32 v177, v25, v161, v141
	v_exp_f32_e32 v175, v175
	v_mul_f32_e32 v176, 0xbfb8aa3b, v176
	v_mul_f32_e32 v177, 0xbfb8aa3b, v177
	v_exp_f32_e32 v176, v176
	v_exp_f32_e32 v177, v177
	v_add_f32_e32 v175, 1.0, v175
	v_fma_f32 v174, v28, v161, v144
	v_rcp_f32_e32 v178, v175
	v_add_f32_e32 v175, 1.0, v176
	v_add_f32_e32 v176, 1.0, v177
	v_fma_f32 v177, v30, v161, v146
	v_fma_f32 v179, v26, v161, v142
	v_fma_f32 v180, v31, v161, v147
	v_fma_f32 v181, v27, v161, v143
	v_mul_f32_e32 v174, 0xbfb8aa3b, v174
	v_mul_f32_e32 v177, 0xbfb8aa3b, v177
	v_mul_f32_e32 v179, 0xbfb8aa3b, v179
	v_mul_f32_e32 v180, 0xbfb8aa3b, v180
	v_mul_f32_e32 v181, 0xbfb8aa3b, v181
	v_exp_f32_e32 v174, v174
	v_exp_f32_e32 v177, v177
	v_exp_f32_e32 v179, v179
	v_exp_f32_e32 v180, v180
	v_exp_f32_e32 v181, v181
	v_add_f32_e32 v174, 1.0, v174
	v_add_f32_e32 v177, 1.0, v177
	v_add_f32_e32 v179, 1.0, v179
	v_add_f32_e32 v180, 1.0, v180
	v_add_f32_e32 v181, 1.0, v181
	v_rcp_f32_e32 v174, v174
	v_rcp_f32_e32 v175, v175
	v_rcp_f32_e32 v176, v176
	v_rcp_f32_e32 v177, v177
	v_rcp_f32_e32 v179, v179
	v_rcp_f32_e32 v180, v180
	v_rcp_f32_e32 v181, v181
	v_cvt_pk_bf16_f32 v174, v174, v175
	v_cvt_pk_bf16_f32 v176, v178, v176
; __device__ __forceinline__ unsigned pk2(float lo, float hi) { return pg8::cvt_pk_bf16(lo, hi); }
; __device__ __forceinline__ float fast_exp2(float x) { return __builtin_amdgcn_exp2f(x); }
; __device__ __forceinline__ float fast_rcp(float x) { return __builtin_amdgcn_rcpf(x); }
;     __device__ __forceinline__ void operator()(const pg8::f32x4 (&acc)[2][2][4][2], const pg8::Unit& u, int wr, int wc, int fr, int fq) const {
;     ...
;                     const int row = row0 + ai * 128 + m * 16; const float rs = rstd_of(ssq, row) * sc;
; #pragma unroll
;                     for (int bj = 0; bj < 2; ++bj) {
;                         const pg8::f32x4 v0 = acc[ai][bj][m][0] * rs, v1 = acc[ai][bj][m][1] * rs;
;     ...
;                     const int row = row0 + ai * 128 + m * 16; const float rs = rstd_of(ssq, row);
; #pragma unroll
;                     for (int bj = 0; bj < 2; ++bj) {
;                         float v[8];
; #pragma unroll
;                         for (int j = 0; j < 4; ++j) { v[j] = fast_rcp(1.0f + fast_exp2(-(acc[ai][bj][m][0][j] * rs + bb[bj][0][j]) * LOG2E)); v[4 + j] = fast_rcp(1.0f + fast_exp2(-(acc[ai][bj][m][1][j] * rs + bb[bj][1][j]) * LOG2E)); }
;                         u32x4 w; w.x = pk2(v[0], v[1]); w.y = pk2(v[2], v[3]); w.z = pk2(v[4], v[5]); w.w = pk2(v[6], v[7]);
;                         *(u32x4*)(G + (size_t)row * NGATE + col0 + bj * 128) = w;
;                     }
	v_cvt_pk_bf16_f32 v175, v177, v180
	v_cvt_pk_bf16_f32 v177, v179, v181
	v_mad_i64_i32 v[178:179], s[0:1], v190, s31, v[166:167]
	v_lshl_add_u64 v[178:179], v[178:179], 0, v[168:169]
	v_fma_f32 v181, v16, v161, v132
	v_fma_f32 v180, v20, v161, v136
	v_mul_f32_e32 v181, 0xbfb8aa3b, v181
	global_store_dwordx4 v[178:179], v[174:177], off
	v_mul_f32_e32 v180, 0xbfb8aa3b, v180
	v_exp_f32_e32 v181, v181
	v_fma_f32 v176, v21, v161, v137
	v_fma_f32 v177, v17, v161, v133
	v_mul_f32_e32 v176, 0xbfb8aa3b, v176
	v_mul_f32_e32 v177, 0xbfb8aa3b, v177
	v_exp_f32_e32 v180, v180
	v_exp_f32_e32 v176, v176
	v_exp_f32_e32 v177, v177
	v_add_f32_e32 v175, 1.0, v181
	v_add_f32_e32 v174, 1.0, v180
	v_rcp_f32_e32 v180, v175
	v_add_f32_e32 v175, 1.0, v176
	v_add_f32_e32 v176, 1.0, v177
	v_fma_f32 v177, v22, v161, v138
	v_fma_f32 v181, v18, v161, v134
	v_fma_f32 v182, v23, v161, v139
	v_fma_f32 v161, v19, v161, v135
	v_mul_f32_e32 v177, 0xbfb8aa3b, v177
	v_mul_f32_e32 v181, 0xbfb8aa3b, v181
	v_mul_f32_e32 v182, 0xbfb8aa3b, v182
	v_mul_f32_e32 v161, 0xbfb8aa3b, v161
	v_exp_f32_e32 v177, v177
	v_exp_f32_e32 v181, v181
	v_exp_f32_e32 v182, v182
	v_exp_f32_e32 v161, v161
	v_add_f32_e32 v177, 1.0, v177
	v_add_f32_e32 v181, 1.0, v181
	v_add_f32_e32 v182, 1.0, v182
	v_add_f32_e32 v161, 1.0, v161
	v_rcp_f32_e32 v174, v174
	v_rcp_f32_e32 v175, v175
	v_rcp_f32_e32 v176, v176
	v_rcp_f32_e32 v177, v177
	v_rcp_f32_e32 v181, v181
	v_rcp_f32_e32 v182, v182
	v_rcp_f32_e32 v161, v161
	v_add_u32_e32 v190, 0xb0, v158
	v_cvt_pk_bf16_f32 v174, v174, v175
	v_cvt_pk_bf16_f32 v175, v177, v182
	v_cvt_pk_bf16_f32 v176, v180, v176
	v_cvt_pk_bf16_f32 v177, v181, v161
	global_store_dwordx4 v[178:179], v[174:177], off offset:256
	s_nop 1
	v_mov_b32_e32 v161, v209
	v_fma_f32 v140, v8, v161, v140
	v_mul_f32_e32 v140, 0xbfb8aa3b, v140
	v_fma_f32 v145, v13, v161, v145
	v_exp_f32_e32 v140, v140
	v_mul_f32_e32 v145, 0xbfb8aa3b, v145
	v_exp_f32_e32 v145, v145
	v_fma_f32 v141, v9, v161, v141
	v_add_f32_e32 v140, 1.0, v140
	v_mul_f32_e32 v141, 0xbfb8aa3b, v141
	v_rcp_f32_e32 v174, v140
	v_add_f32_e32 v140, 1.0, v145
	v_fma_f32 v145, v14, v161, v146
	v_exp_f32_e32 v141, v141
	v_mul_f32_e32 v145, 0xbfb8aa3b, v145
	v_exp_f32_e32 v145, v145
	v_fma_f32 v144, v12, v161, v144
	v_fma_f32 v142, v10, v161, v142
	v_mul_f32_e32 v144, 0xbfb8aa3b, v144
	v_add_f32_e32 v141, 1.0, v141
	v_mul_f32_e32 v142, 0xbfb8aa3b, v142
	v_fmac_f32_e32 v147, v15, v161
	v_fmac_f32_e32 v143, v11, v161
	v_exp_f32_e32 v144, v144
	v_exp_f32_e32 v142, v142
	v_rcp_f32_e32 v146, v141
	v_add_f32_e32 v141, 1.0, v145
	v_mul_f32_e32 v145, 0xbfb8aa3b, v147
	v_mul_f32_e32 v143, 0xbfb8aa3b, v143
	v_exp_f32_e32 v145, v145
	v_exp_f32_e32 v143, v143
	v_add_f32_e32 v144, 1.0, v144
	v_add_f32_e32 v142, 1.0, v142
	v_fma_f32 v132, v0, v161, v132
	v_rcp_f32_e32 v144, v144
	v_rcp_f32_e32 v140, v140
	v_rcp_f32_e32 v147, v142
	v_add_f32_e32 v142, 1.0, v145
	v_add_f32_e32 v143, 1.0, v143
	v_mul_f32_e32 v132, 0xbfb8aa3b, v132
	v_fma_f32 v137, v5, v161, v137
	v_rcp_f32_e32 v141, v141
	v_rcp_f32_e32 v142, v142
	v_rcp_f32_e32 v143, v143
	v_exp_f32_e32 v132, v132
	v_mul_f32_e32 v137, 0xbfb8aa3b, v137
	v_exp_f32_e32 v137, v137
	v_cvt_pk_bf16_f32 v140, v144, v140
	v_mad_i64_i32 v[144:145], s[0:1], v190, s31, v[166:167]
	v_cvt_pk_bf16_f32 v141, v141, v142
	v_cvt_pk_bf16_f32 v142, v174, v146
	v_cvt_pk_bf16_f32 v143, v147, v143
	v_lshl_add_u64 v[144:145], v[144:145], 0, v[168:169]
	v_add_f32_e32 v132, 1.0, v132
	v_fma_f32 v133, v1, v161, v133
	global_store_dwordx4 v[144:145], v[140:143], off
	v_mul_f32_e32 v133, 0xbfb8aa3b, v133
	v_exp_f32_e32 v133, v133
	v_rcp_f32_e32 v140, v132
	v_add_f32_e32 v132, 1.0, v137
	v_fma_f32 v137, v6, v161, v138
	v_mul_f32_e32 v137, 0xbfb8aa3b, v137
	v_exp_f32_e32 v137, v137
	v_fma_f32 v134, v2, v161, v134
	v_fma_f32 v136, v4, v161, v136
	v_add_f32_e32 v133, 1.0, v133
	v_mul_f32_e32 v134, 0xbfb8aa3b, v134
	v_fmac_f32_e32 v139, v7, v161
	v_fmac_f32_e32 v135, v3, v161
	v_mul_f32_e32 v136, 0xbfb8aa3b, v136
	v_exp_f32_e32 v134, v134
	v_rcp_f32_e32 v138, v133
	v_add_f32_e32 v133, 1.0, v137
	v_mul_f32_e32 v137, 0xbfb8aa3b, v139
	v_mul_f32_e32 v135, 0xbfb8aa3b, v135
	v_exp_f32_e32 v136, v136
	v_exp_f32_e32 v137, v137
	v_exp_f32_e32 v135, v135
	v_add_f32_e32 v134, 1.0, v134
	v_add_f32_e32 v136, 1.0, v136
	v_rcp_f32_e32 v139, v134
	v_add_f32_e32 v134, 1.0, v137
	v_add_f32_e32 v135, 1.0, v135
	v_rcp_f32_e32 v136, v136
	v_rcp_f32_e32 v132, v132
	v_rcp_f32_e32 v133, v133
	v_rcp_f32_e32 v134, v134
	v_rcp_f32_e32 v135, v135
	v_cvt_pk_bf16_f32 v132, v136, v132
	s_mov_b64 s[0:1], 0
	v_cvt_pk_bf16_f32 v133, v133, v134
	v_cvt_pk_bf16_f32 v134, v140, v138
	v_cvt_pk_bf16_f32 v135, v139, v135
	global_store_dwordx4 v[144:145], v[132:135], off offset:256
.LBB0_347:
	s_andn2_b64 vcc, exec, s[0:1]
	s_cbranch_vccnz .LBB0_485
	s_nop 0
	s_mul_hi_i32 s0, s57, 0x2aaaaaab
	s_lshr_b32 s1, s0, 31
	s_add_i32 s0, s0, s1
	s_mul_i32 s0, s0, 6
	s_sub_i32 s0, s57, s0
	s_cmp_lt_i32 s0, 2
	s_cselect_b64 s[0:1], -1, 0
	s_lshl_b32 s19, s57, 8
	s_add_i32 s4, s19, 0xfffffc00
	s_add_i32 s5, s19, 0xfffff800
	s_cmp_lt_u32 s57, 12
	s_cselect_b32 s5, s5, 0x380
	s_cmp_lt_i32 s57, 6
	s_nop 0
	s_cselect_b32 s21, s4, s5
	s_cmp_lt_i32 s57, 10
	s_nop 1
	s_cbranch_scc1 .LBB0_350
	s_cmp_gt_i32 s57, 11
	s_mov_b64 s[4:5], -1
	s_cselect_b64 s[42:43], -1, 0
	s_cbranch_execz .LBB0_351
	s_branch .LBB0_352

; __device__ __forceinline__ unsigned pk2(float lo, float hi) { return pg8::cvt_pk_bf16(lo, hi); }
;     __device__ __forceinline__ void operator()(const pg8::f32x4 (&acc)[2][2][4][2], const pg8::Unit& u, int wr, int wc, int fr, int fq) const {
;     ...
;                     const int row = row0 + ai * 128 + m * 16; const float rs = rstd_of(ssq, row) * sc;
; #pragma unroll
;                     for (int bj = 0; bj < 2; ++bj) {
;                         const pg8::f32x4 v0 = acc[ai][bj][m][0] * rs, v1 = acc[ai][bj][m][1] * rs;
;                         u32x4 w; w.x = pk2(v0[0], v0[1]); w.y = pk2(v0[2], v0[3]); w.z = pk2(v1[0], v1[1]); w.w = pk2(v1[2], v1[3]);
;                         if (vt_all || (vt_half && bj == 1)) {
;                             bf16_t* vp = vt + (size_t)(vrow0 + bj * 128) * S + row;
;                             vp[0 * (size_t)S] = (bf16_t)(w.x & 0xffffu); vp[1 * (size_t)S] = (bf16_t)(w.x >> 16); vp[2 * (size_t)S] = (bf16_t)(w.y & 0xffffu); vp[3 * (size_t)S] = (bf16_t)(w.y >> 16);
;                             vp[4 * (size_t)S] = (bf16_t)(w.z & 0xffffu); vp[5 * (size_t)S] = (bf16_t)(w.z >> 16); vp[6 * (size_t)S] = (bf16_t)(w.w & 0xffffu); vp[7 * (size_t)S] = (bf16_t)(w.w >> 16);
;                         } else {
;                             *(u32x4*)(proj + (size_t)row * NPROJ + col0 + bj * 128) = w;
.LBB0_352:
	v_mov_b32_e32 v132, 0x3e38aa3b
	v_cndmask_b32_e64 v138, 1.0, v132, s[0:1]
	v_mov_b32_e32 v134, v202
	v_mul_f32_e32 v136, v138, v134
	v_or_b32_e32 v132, s19, v171
	s_movk_i32 s0, 0x1e00
	v_pk_mul_f32 v[130:131], v[130:131], v[136:137] op_sel_hi:[1,0]
	v_pk_mul_f32 v[128:129], v[128:129], v[136:137] op_sel_hi:[1,0]
	v_pk_mul_f32 v[140:141], v[126:127], v[136:137] op_sel_hi:[1,0]
	v_pk_mul_f32 v[126:127], v[124:125], v[136:137] op_sel_hi:[1,0]
	v_ashrrev_i32_e32 v133, 31, v132
	v_mad_i64_i32 v[134:135], s[0:1], v158, s0, 0
	v_cvt_pk_bf16_f32 v124, v128, v129
	v_cvt_pk_bf16_f32 v125, v130, v131
	v_cvt_pk_bf16_f32 v126, v126, v127
	s_andn2_b64 vcc, exec, s[42:43]
	v_cvt_pk_bf16_f32 v127, v140, v141
	s_cbranch_vccnz .LBB0_354
	v_lshl_add_u64 v[128:129], s[34:35], 0, v[134:135]
	v_lshl_add_u64 v[128:129], v[132:133], 1, v[128:129]
	global_store_dwordx4 v[128:129], v[124:127], off
	s_mov_b64 s[4:5], 0

;     __device__ __forceinline__ void operator()(const pg8::f32x4 (&acc)[2][2][4][2], const pg8::Unit& u, int wr, int wc, int fr, int fq) const {
;     ...
;                     const int row = row0 + ai * 128 + m * 16; const float rs = rstd_of(ssq, row) * sc;
.LBB0_365:
	s_cmp_lt_i32 s57, 10
	s_nop 1
	s_cbranch_scc1 .LBB0_367
	s_cmp_gt_i32 s57, 11
	s_mov_b64 s[0:1], -1
	s_cselect_b64 s[44:45], -1, 0
	s_cbranch_execz .LBB0_368
	s_branch .LBB0_369

; __device__ __forceinline__ unsigned pk2(float lo, float hi) { return pg8::cvt_pk_bf16(lo, hi); }
;     __device__ __forceinline__ void operator()(const pg8::f32x4 (&acc)[2][2][4][2], const pg8::Unit& u, int wr, int wc, int fr, int fq) const {
;     ...
;                     const int row = row0 + ai * 128 + m * 16; const float rs = rstd_of(ssq, row) * sc;
; #pragma unroll
;                     for (int bj = 0; bj < 2; ++bj) {
;                         const pg8::f32x4 v0 = acc[ai][bj][m][0] * rs, v1 = acc[ai][bj][m][1] * rs;
;                         u32x4 w; w.x = pk2(v0[0], v0[1]); w.y = pk2(v0[2], v0[3]); w.z = pk2(v1[0], v1[1]); w.w = pk2(v1[2], v1[3]);
;                         if (vt_all || (vt_half && bj == 1)) {
;                             bf16_t* vp = vt + (size_t)(vrow0 + bj * 128) * S + row;
;                             vp[0 * (size_t)S] = (bf16_t)(w.x & 0xffffu); vp[1 * (size_t)S] = (bf16_t)(w.x >> 16); vp[2 * (size_t)S] = (bf16_t)(w.y & 0xffffu); vp[3 * (size_t)S] = (bf16_t)(w.y >> 16);
;                             vp[4 * (size_t)S] = (bf16_t)(w.z & 0xffffu); vp[5 * (size_t)S] = (bf16_t)(w.z >> 16); vp[6 * (size_t)S] = (bf16_t)(w.w & 0xffffu); vp[7 * (size_t)S] = (bf16_t)(w.w >> 16);
;                         } else {
;                             *(u32x4*)(proj + (size_t)row * NPROJ + col0 + bj * 128) = w;
.LBB0_369:
	v_mov_b32_e32 v116, v203
	v_mul_f32_e32 v118, v138, v116
	s_movk_i32 s19, 0x1e00
	v_pk_mul_f32 v[114:115], v[114:115], v[118:119] op_sel_hi:[1,0]
	v_pk_mul_f32 v[112:113], v[112:113], v[118:119] op_sel_hi:[1,0]
	v_pk_mul_f32 v[120:121], v[110:111], v[118:119] op_sel_hi:[1,0]
	v_pk_mul_f32 v[110:111], v[108:109], v[118:119] op_sel_hi:[1,0]
	v_mad_i64_i32 v[116:117], s[46:47], v164, s19, 0
	v_cvt_pk_bf16_f32 v108, v112, v113
	v_cvt_pk_bf16_f32 v109, v114, v115
	v_cvt_pk_bf16_f32 v110, v110, v111
	s_andn2_b64 vcc, exec, s[44:45]
	v_cvt_pk_bf16_f32 v111, v120, v121
	s_cbranch_vccz .LBB0_373
	s_andn2_b64 vcc, exec, s[0:1]
	s_cbranch_vccz .LBB0_374

;     __device__ __forceinline__ void operator()(const pg8::f32x4 (&acc)[2][2][4][2], const pg8::Unit& u, int wr, int wc, int fr, int fq) const {
;     ...
;                     const int row = row0 + ai * 128 + m * 16; const float rs = rstd_of(ssq, row) * sc;
.LBB0_382:
	s_nop 0
	s_cmp_lt_i32 s57, 10
	s_nop 1
	s_cbranch_scc1 .LBB0_384
	s_cmp_gt_i32 s57, 11
	s_mov_b64 s[0:1], -1
	s_cselect_b64 s[44:45], -1, 0
	s_cbranch_execz .LBB0_385
	s_branch .LBB0_386

; __device__ __forceinline__ unsigned pk2(float lo, float hi) { return pg8::cvt_pk_bf16(lo, hi); }
;     __device__ __forceinline__ void operator()(const pg8::f32x4 (&acc)[2][2][4][2], const pg8::Unit& u, int wr, int wc, int fr, int fq) const {
;     ...
;                     const int row = row0 + ai * 128 + m * 16; const float rs = rstd_of(ssq, row) * sc;
; #pragma unroll
;                     for (int bj = 0; bj < 2; ++bj) {
;                         const pg8::f32x4 v0 = acc[ai][bj][m][0] * rs, v1 = acc[ai][bj][m][1] * rs;
;                         u32x4 w; w.x = pk2(v0[0], v0[1]); w.y = pk2(v0[2], v0[3]); w.z = pk2(v1[0], v1[1]); w.w = pk2(v1[2], v1[3]);
;                         if (vt_all || (vt_half && bj == 1)) {
;                             bf16_t* vp = vt + (size_t)(vrow0 + bj * 128) * S + row;
;                             vp[0 * (size_t)S] = (bf16_t)(w.x & 0xffffu); vp[1 * (size_t)S] = (bf16_t)(w.x >> 16); vp[2 * (size_t)S] = (bf16_t)(w.y & 0xffffu); vp[3 * (size_t)S] = (bf16_t)(w.y >> 16);
;                             vp[4 * (size_t)S] = (bf16_t)(w.z & 0xffffu); vp[5 * (size_t)S] = (bf16_t)(w.z >> 16); vp[6 * (size_t)S] = (bf16_t)(w.w & 0xffffu); vp[7 * (size_t)S] = (bf16_t)(w.w >> 16);
;                         } else {
;                             *(u32x4*)(proj + (size_t)row * NPROJ + col0 + bj * 128) = w;
.LBB0_386:
	v_mov_b32_e32 v100, v204
	v_mul_f32_e32 v102, v138, v100
	s_movk_i32 s19, 0x1e00
	v_pk_mul_f32 v[98:99], v[98:99], v[102:103] op_sel_hi:[1,0]
	v_pk_mul_f32 v[96:97], v[96:97], v[102:103] op_sel_hi:[1,0]
	v_pk_mul_f32 v[104:105], v[94:95], v[102:103] op_sel_hi:[1,0]
	v_pk_mul_f32 v[94:95], v[92:93], v[102:103] op_sel_hi:[1,0]
	v_mad_i64_i32 v[100:101], s[46:47], v162, s19, 0
	v_cvt_pk_bf16_f32 v92, v96, v97
	v_cvt_pk_bf16_f32 v93, v98, v99
	v_cvt_pk_bf16_f32 v94, v94, v95
	s_andn2_b64 vcc, exec, s[44:45]
	v_cvt_pk_bf16_f32 v95, v104, v105
	s_cbranch_vccz .LBB0_390
	s_andn2_b64 vcc, exec, s[0:1]
	s_cbranch_vccz .LBB0_391

; __device__ __forceinline__ unsigned pk2(float lo, float hi) { return pg8::cvt_pk_bf16(lo, hi); }
;     __device__ __forceinline__ void operator()(const pg8::f32x4 (&acc)[2][2][4][2], const pg8::Unit& u, int wr, int wc, int fr, int fq) const {
;     ...
;                     const int row = row0 + ai * 128 + m * 16; const float rs = rstd_of(ssq, row) * sc;
; #pragma unroll
;                     for (int bj = 0; bj < 2; ++bj) {
;                         const pg8::f32x4 v0 = acc[ai][bj][m][0] * rs, v1 = acc[ai][bj][m][1] * rs;
;                         u32x4 w; w.x = pk2(v0[0], v0[1]); w.y = pk2(v0[2], v0[3]); w.z = pk2(v1[0], v1[1]); w.w = pk2(v1[2], v1[3]);
;                         if (vt_all || (vt_half && bj == 1)) {
;                             bf16_t* vp = vt + (size_t)(vrow0 + bj * 128) * S + row;
;                             vp[0 * (size_t)S] = (bf16_t)(w.x & 0xffffu); vp[1 * (size_t)S] = (bf16_t)(w.x >> 16); vp[2 * (size_t)S] = (bf16_t)(w.y & 0xffffu); vp[3 * (size_t)S] = (bf16_t)(w.y >> 16);
;                             vp[4 * (size_t)S] = (bf16_t)(w.z & 0xffffu); vp[5 * (size_t)S] = (bf16_t)(w.z >> 16); vp[6 * (size_t)S] = (bf16_t)(w.w & 0xffffu); vp[7 * (size_t)S] = (bf16_t)(w.w >> 16);
;                         } else {
;                             *(u32x4*)(proj + (size_t)row * NPROJ + col0 + bj * 128) = w;
.LBB0_403:
	v_mov_b32_e32 v84, v205
	v_mul_f32_e32 v86, v138, v84
	s_movk_i32 s19, 0x1e00
	v_pk_mul_f32 v[82:83], v[82:83], v[86:87] op_sel_hi:[1,0]
	v_pk_mul_f32 v[80:81], v[80:81], v[86:87] op_sel_hi:[1,0]
	v_pk_mul_f32 v[88:89], v[78:79], v[86:87] op_sel_hi:[1,0]
	v_pk_mul_f32 v[78:79], v[76:77], v[86:87] op_sel_hi:[1,0]
	v_mad_i64_i32 v[84:85], s[46:47], v160, s19, 0
	v_cvt_pk_bf16_f32 v76, v80, v81
	v_cvt_pk_bf16_f32 v77, v82, v83
	v_cvt_pk_bf16_f32 v78, v78, v79
	s_andn2_b64 vcc, exec, s[44:45]
	v_cvt_pk_bf16_f32 v79, v88, v89
	s_cbranch_vccz .LBB0_407
	s_andn2_b64 vcc, exec, s[0:1]
	s_cbranch_vccz .LBB0_408

;     __device__ __forceinline__ void operator()(const pg8::f32x4 (&acc)[2][2][4][2], const pg8::Unit& u, int wr, int wc, int fr, int fq) const {
;     ...
;                     const int row = row0 + ai * 128 + m * 16; const float rs = rstd_of(ssq, row) * sc;
.LBB0_416:
	v_add_u32_e32 v68, 0x80, v158
	s_nop 0
	s_cmp_lt_i32 s57, 10
	s_nop 1
	s_cbranch_scc1 .LBB0_418
	s_cmp_gt_i32 s57, 11
	s_mov_b64 s[0:1], -1
	s_cselect_b64 s[44:45], -1, 0
	s_cbranch_execz .LBB0_419
	s_branch .LBB0_420

; __device__ __forceinline__ unsigned pk2(float lo, float hi) { return pg8::cvt_pk_bf16(lo, hi); }
;     __device__ __forceinline__ void operator()(const pg8::f32x4 (&acc)[2][2][4][2], const pg8::Unit& u, int wr, int wc, int fr, int fq) const {
;     ...
;                     const int row = row0 + ai * 128 + m * 16; const float rs = rstd_of(ssq, row) * sc;
; #pragma unroll
;                     for (int bj = 0; bj < 2; ++bj) {
;                         const pg8::f32x4 v0 = acc[ai][bj][m][0] * rs, v1 = acc[ai][bj][m][1] * rs;
;                         u32x4 w; w.x = pk2(v0[0], v0[1]); w.y = pk2(v0[2], v0[3]); w.z = pk2(v1[0], v1[1]); w.w = pk2(v1[2], v1[3]);
;                         if (vt_all || (vt_half && bj == 1)) {
.LBB0_420:
	v_mov_b32_e32 v69, v206
	v_mul_f32_e32 v70, v138, v69
	s_movk_i32 s19, 0x1e00
	v_pk_mul_f32 v[66:67], v[66:67], v[70:71] op_sel_hi:[1,0]
	v_pk_mul_f32 v[64:65], v[64:65], v[70:71] op_sel_hi:[1,0]
	v_pk_mul_f32 v[72:73], v[62:63], v[70:71] op_sel_hi:[1,0]
	v_pk_mul_f32 v[62:63], v[60:61], v[70:71] op_sel_hi:[1,0]
	v_mad_i64_i32 v[68:69], s[46:47], v68, s19, 0
	v_cvt_pk_bf16_f32 v60, v64, v65
	v_cvt_pk_bf16_f32 v61, v66, v67
	v_cvt_pk_bf16_f32 v62, v62, v63
	s_andn2_b64 vcc, exec, s[44:45]
	v_cvt_pk_bf16_f32 v63, v72, v73
	s_cbranch_vccz .LBB0_424
	s_andn2_b64 vcc, exec, s[0:1]
	s_cbranch_vccz .LBB0_425

; __device__ __forceinline__ float rstd_of(const float* ssq, int row) {
;     const f32x4* q = (const f32x4*)(ssq + (size_t)row * 16); const f32x4 a = q[0], b = q[1], c = q[2], d = q[3];
;     const float t = (((a.x + a.y) + (a.z + a.w)) + ((b.x + b.y) + (b.z + b.w))) + (((c.x + c.y) + (c.z + c.w)) + ((d.x + d.y) + (d.z + d.w)));
;     return 1.0f / sqrtf(t * (1.0f / DM) + 1e-6f); }
;     __device__ __forceinline__ void operator()(const pg8::f32x4 (&acc)[2][2][4][2], const pg8::Unit& u, int wr, int wc, int fr, int fq) const {
;     ...
;                     const int row = row0 + ai * 128 + m * 16; const float rs = rstd_of(ssq, row) * sc;
.LBB0_433:
	v_add_u32_e32 v52, 0x90, v158
	s_nop 0
	s_cmp_lt_i32 s57, 10
	s_nop 1
	s_cbranch_scc1 .LBB0_435
	s_cmp_gt_i32 s57, 11
	s_mov_b64 s[0:1], -1
	s_cselect_b64 s[44:45], -1, 0
	s_cbranch_execz .LBB0_436
	s_branch .LBB0_437

; __device__ __forceinline__ unsigned pk2(float lo, float hi) { return pg8::cvt_pk_bf16(lo, hi); }
;     __device__ __forceinline__ void operator()(const pg8::f32x4 (&acc)[2][2][4][2], const pg8::Unit& u, int wr, int wc, int fr, int fq) const {
;     ...
;                     const int row = row0 + ai * 128 + m * 16; const float rs = rstd_of(ssq, row) * sc;
; #pragma unroll
;                     for (int bj = 0; bj < 2; ++bj) {
;                         const pg8::f32x4 v0 = acc[ai][bj][m][0] * rs, v1 = acc[ai][bj][m][1] * rs;
;                         u32x4 w; w.x = pk2(v0[0], v0[1]); w.y = pk2(v0[2], v0[3]); w.z = pk2(v1[0], v1[1]); w.w = pk2(v1[2], v1[3]);
;                         if (vt_all || (vt_half && bj == 1)) {
.LBB0_437:
	v_mov_b32_e32 v53, v207
	v_mul_f32_e32 v54, v138, v53
	s_movk_i32 s19, 0x1e00
	v_pk_mul_f32 v[50:51], v[50:51], v[54:55] op_sel_hi:[1,0]
	v_pk_mul_f32 v[48:49], v[48:49], v[54:55] op_sel_hi:[1,0]
	v_pk_mul_f32 v[56:57], v[46:47], v[54:55] op_sel_hi:[1,0]
	v_pk_mul_f32 v[46:47], v[44:45], v[54:55] op_sel_hi:[1,0]
	v_mad_i64_i32 v[52:53], s[46:47], v52, s19, 0
	v_cvt_pk_bf16_f32 v44, v48, v49
	v_cvt_pk_bf16_f32 v45, v50, v51
	v_cvt_pk_bf16_f32 v46, v46, v47
	s_andn2_b64 vcc, exec, s[44:45]
	v_cvt_pk_bf16_f32 v47, v56, v57
	s_cbranch_vccz .LBB0_441
	s_andn2_b64 vcc, exec, s[0:1]
	s_cbranch_vccz .LBB0_442

; __device__ __forceinline__ float rstd_of(const float* ssq, int row) {
;     const f32x4* q = (const f32x4*)(ssq + (size_t)row * 16); const f32x4 a = q[0], b = q[1], c = q[2], d = q[3];
;     const float t = (((a.x + a.y) + (a.z + a.w)) + ((b.x + b.y) + (b.z + b.w))) + (((c.x + c.y) + (c.z + c.w)) + ((d.x + d.y) + (d.z + d.w)));
;     return 1.0f / sqrtf(t * (1.0f / DM) + 1e-6f); }
;     __device__ __forceinline__ void operator()(const pg8::f32x4 (&acc)[2][2][4][2], const pg8::Unit& u, int wr, int wc, int fr, int fq) const {
;     ...
;                     const int row = row0 + ai * 128 + m * 16; const float rs = rstd_of(ssq, row) * sc;
.LBB0_450:
	v_add_u32_e32 v36, 0xa0, v158
	s_nop 0
	s_cmp_lt_i32 s57, 10
	s_nop 1
	s_cbranch_scc1 .LBB0_452
	s_cmp_gt_i32 s57, 11
	s_mov_b64 s[0:1], -1
	s_cselect_b64 s[44:45], -1, 0
	s_cbranch_execz .LBB0_453
	s_branch .LBB0_454

; __device__ __forceinline__ unsigned pk2(float lo, float hi) { return pg8::cvt_pk_bf16(lo, hi); }
;     __device__ __forceinline__ void operator()(const pg8::f32x4 (&acc)[2][2][4][2], const pg8::Unit& u, int wr, int wc, int fr, int fq) const {
;     ...
;                     const int row = row0 + ai * 128 + m * 16; const float rs = rstd_of(ssq, row) * sc;
; #pragma unroll
;                     for (int bj = 0; bj < 2; ++bj) {
;                         const pg8::f32x4 v0 = acc[ai][bj][m][0] * rs, v1 = acc[ai][bj][m][1] * rs;
;                         u32x4 w; w.x = pk2(v0[0], v0[1]); w.y = pk2(v0[2], v0[3]); w.z = pk2(v1[0], v1[1]); w.w = pk2(v1[2], v1[3]);
;                         if (vt_all || (vt_half && bj == 1)) {
.LBB0_454:
	v_mov_b32_e32 v37, v208
	v_mul_f32_e32 v38, v138, v37
	s_movk_i32 s19, 0x1e00
	v_pk_mul_f32 v[30:31], v[30:31], v[38:39] op_sel_hi:[1,0]
	v_pk_mul_f32 v[28:29], v[28:29], v[38:39] op_sel_hi:[1,0]
	v_pk_mul_f32 v[40:41], v[26:27], v[38:39] op_sel_hi:[1,0]
	v_pk_mul_f32 v[26:27], v[24:25], v[38:39] op_sel_hi:[1,0]
	v_mad_i64_i32 v[36:37], s[46:47], v36, s19, 0
	v_cvt_pk_bf16_f32 v24, v28, v29
	v_cvt_pk_bf16_f32 v25, v30, v31
	v_cvt_pk_bf16_f32 v26, v26, v27
	s_andn2_b64 vcc, exec, s[44:45]
	v_cvt_pk_bf16_f32 v27, v40, v41
	s_cbranch_vccz .LBB0_458
	s_andn2_b64 vcc, exec, s[0:1]
	s_cbranch_vccz .LBB0_459

; __device__ __forceinline__ float rstd_of(const float* ssq, int row) {
;     const f32x4* q = (const f32x4*)(ssq + (size_t)row * 16); const f32x4 a = q[0], b = q[1], c = q[2], d = q[3];
;     const float t = (((a.x + a.y) + (a.z + a.w)) + ((b.x + b.y) + (b.z + b.w))) + (((c.x + c.y) + (c.z + c.w)) + ((d.x + d.y) + (d.z + d.w)));
;     return 1.0f / sqrtf(t * (1.0f / DM) + 1e-6f); }
;     __device__ __forceinline__ void operator()(const pg8::f32x4 (&acc)[2][2][4][2], const pg8::Unit& u, int wr, int wc, int fr, int fq) const {
;     ...
;                     const int row = row0 + ai * 128 + m * 16; const float rs = rstd_of(ssq, row) * sc;
.LBB0_467:
	v_add_u32_e32 v16, 0xb0, v158
	s_cmp_lt_i32 s57, 10
	s_nop 1
	s_cbranch_scc1 .LBB0_469
	s_cmp_gt_i32 s57, 11
	s_mov_b64 s[0:1], -1
	s_cselect_b64 s[44:45], -1, 0
	s_cbranch_execz .LBB0_470
	s_branch .LBB0_471

; __device__ __forceinline__ unsigned pk2(float lo, float hi) { return pg8::cvt_pk_bf16(lo, hi); }
;     __device__ __forceinline__ void operator()(const pg8::f32x4 (&acc)[2][2][4][2], const pg8::Unit& u, int wr, int wc, int fr, int fq) const {
;     ...
;                     const int row = row0 + ai * 128 + m * 16; const float rs = rstd_of(ssq, row) * sc;
; #pragma unroll
;                     for (int bj = 0; bj < 2; ++bj) {
;                         const pg8::f32x4 v0 = acc[ai][bj][m][0] * rs, v1 = acc[ai][bj][m][1] * rs;
;                         u32x4 w; w.x = pk2(v0[0], v0[1]); w.y = pk2(v0[2], v0[3]); w.z = pk2(v1[0], v1[1]); w.w = pk2(v1[2], v1[3]);
;                         if (vt_all || (vt_half && bj == 1)) {
.LBB0_471:
	v_mov_b32_e32 v17, v209
	v_mul_f32_e32 v18, v138, v17
	s_movk_i32 s19, 0x1e00
	v_pk_mul_f32 v[14:15], v[14:15], v[18:19] op_sel_hi:[1,0]
	v_pk_mul_f32 v[12:13], v[12:13], v[18:19] op_sel_hi:[1,0]
	v_pk_mul_f32 v[20:21], v[10:11], v[18:19] op_sel_hi:[1,0]
	v_pk_mul_f32 v[10:11], v[8:9], v[18:19] op_sel_hi:[1,0]
	v_mad_i64_i32 v[16:17], s[46:47], v16, s19, 0
	v_cvt_pk_bf16_f32 v8, v12, v13
	v_cvt_pk_bf16_f32 v9, v14, v15
	v_cvt_pk_bf16_f32 v10, v10, v11
	s_andn2_b64 vcc, exec, s[44:45]
	v_cvt_pk_bf16_f32 v11, v20, v21
	s_cbranch_vccz .LBB0_475
	s_andn2_b64 vcc, exec, s[0:1]
	s_cbranch_vccz .LBB0_476

; #define PG8_STAGE(bufoff, gbase, voff) do { _Pragma("unroll") for (int _i = 0; _i < 2; ++_i) \
;         __builtin_amdgcn_global_load_lds((const unsigned*)((const char*)(gbase) + (voff)[_i]), (PG8_LAS unsigned*)(lds + (bufoff) + ldsw + _i * 8192), 16, 0, 0); } while (0)
; #define PG8_LDA(dst, b, h) do { _Pragma("unroll") for (int m = 0; m < 4; ++m) _Pragma("unroll") for (int k = 0; k < 2; ++k) dst[m][k] = *(const PG8_LAS bf16x8*)(lds + PG8_SA(b, h) + aoff + m * 2048 + k * 1024); } while (0)
; #define PG8_LDB(dst, b, h) do { _Pragma("unroll") for (int n = 0; n < 2; ++n) _Pragma("unroll") for (int k = 0; k < 2; ++k) dst[n][k] = *(const PG8_LAS bf16x8*)(lds + PG8_SB(b, h) + boff + n * 2048 + k * 1024); } while (0)
; #define PG8_MMA(ai, bj, At, Bt) do { __builtin_amdgcn_s_setprio(1); _Pragma("unroll") for (int m = 0; m < 4; ++m) _Pragma("unroll") for (int n = 0; n < 2; ++n) _Pragma("unroll") for (int k = 0; k < 2; ++k) \
;         acc[ai][bj][m][n] = __builtin_amdgcn_mfma_f32_16x16x32_bf16(Bt[n][k], At[m][k], acc[ai][bj][m][n], 0, 0, 0); __builtin_amdgcn_s_setprio(0); } while (0)
; #define PG8_WAIT_V(n) asm volatile("s_waitcnt vmcnt(" #n ")" ::: "memory")
; template <class Epi, class Sched, bool ALIGN_EPI = false, bool SP2 = false>
; __device__ __forceinline__ void gemm_phase(PG8_LAS unsigned char* lds, const Gemm g, const Sched& S, const Epi& E) {
;     ...
;             PG8_LDB(B0, 0, 0); PG8_LDB(B1, 0, 1); PG8_SCHED; PG8_LDA(At, 0, 0); PG8_STAGE(PG8_SA(1, 1), a1 + hstep, voffA);
;             PG8_WAIT_V(8); PG8_WAIT_L(0); PG8_BAR; PG8_MMA(0, 0, At, B0); PG8_MMA(0, 1, At, B1); PG8_BAR; PG8_SCHED;
;             PG8_LDA(At, 0, 1); PG8_STAGE(PG8_SB(0, 0), b2, voffB); PG8_STAGE(PG8_SB(0, 1), b2 + hstep, voffB); PG8_STAGE(PG8_SA(0, 0), a2, voffA);
;             PG8_WAIT_V(8); PG8_WAIT_L(0); PG8_BAR; PG8_MMA(1, 0, At, B0); PG8_MMA(1, 1, At, B1); PG8_BAR; PG8_SCHED;
;             PG8_LDB(B0, 1, 0); PG8_LDB(B1, 1, 1); PG8_SCHED; PG8_LDA(At, 1, 0); PG8_STAGE(PG8_SA(0, 1), a2 + hstep, voffA);
;             PG8_WAIT_V(8); PG8_WAIT_L(0); PG8_BAR; PG8_MMA(0, 0, At, B0); PG8_MMA(0, 1, At, B1); PG8_BAR; PG8_SCHED;
;             PG8_LDA(At, 1, 1); PG8_STAGE(PG8_SB(1, 0), b3, voffB); PG8_STAGE(PG8_SB(1, 1), b3 + hstep, voffB); PG8_STAGE(PG8_SA(1, 0), a3, voffA);
;             PG8_WAIT_V(8); PG8_WAIT_L(0); PG8_BAR; PG8_MMA(1, 0, At, B0); PG8_MMA(1, 1, At, B1); PG8_BAR; PG8_SCHED;
.LBB0_589:
	s_add_i32 s62, s40, 2
	s_add_u32 s63, s22, 0x80
	s_addc_u32 s41, s23, 0
	s_add_i32 s66, 0, 0x10000
	s_cmp_eq_u32 s56, s40
	s_cselect_b32 s41, s1, s41
	s_cselect_b32 s40, s0, s63
	s_cselect_b32 s65, s21, s61
	s_cselect_b32 s64, s20, s60
	s_add_i32 s63, 0, 0x14000
	v_add_u32_e32 v144, s66, v218
	v_add_u32_e32 v160, s63, v218
	ds_read_b128 v[132:135], v144
	ds_read_b128 v[136:139], v144 offset:1024
	ds_read_b128 v[140:143], v144 offset:2048
	ds_read_b128 v[144:147], v144 offset:3072
	ds_read_b128 v[148:151], v160
	ds_read_b128 v[152:155], v160 offset:1024
	ds_read_b128 v[156:159], v160 offset:2048
	ds_read_b128 v[160:163], v160 offset:3072
	v_lshl_add_u64 v[214:215], s[22:23], 0, v[202:203]
	s_add_i32 m0, s48, 0xc000
	ds_read_b128 v[164:167], v220
	ds_read_b128 v[168:171], v220 offset:1024
	ds_read_b128 v[172:175], v220 offset:2048
	ds_read_b128 v[176:179], v220 offset:3072
	ds_read_b128 v[180:183], v220 offset:4096
	ds_read_b128 v[184:187], v220 offset:5120
	ds_read_b128 v[206:209], v220 offset:6144
	ds_read_b128 v[210:213], v220 offset:7168
	global_load_lds_dwordx4 v[214:215], off
	v_lshl_add_u64 v[214:215], s[22:23], 0, v[204:205]
	s_add_i32 m0, s48, 0xe000
	s_nop 0
	global_load_lds_dwordx4 v[214:215], off
	s_waitcnt vmcnt(8)
	s_waitcnt lgkmcnt(0)
	v_mfma_f32_16x16x32_bf16 v[128:131], v[132:135], v[164:167], v[128:131]
	v_mfma_f32_16x16x32_bf16 v[124:127], v[140:143], v[164:167], v[124:127]
	v_mfma_f32_16x16x32_bf16 v[112:115], v[132:135], v[172:175], v[112:115]
	v_mfma_f32_16x16x32_bf16 v[108:111], v[140:143], v[172:175], v[108:111]
	s_barrier
	s_setprio 1
	v_mfma_f32_16x16x32_bf16 v[96:99], v[132:135], v[180:183], v[96:99]
	v_mfma_f32_16x16x32_bf16 v[92:95], v[140:143], v[180:183], v[92:95]
	v_mfma_f32_16x16x32_bf16 v[80:83], v[132:135], v[206:209], v[80:83]
	v_mfma_f32_16x16x32_bf16 v[76:79], v[140:143], v[206:209], v[76:79]
	v_mfma_f32_16x16x32_bf16 v[128:131], v[136:139], v[168:171], v[128:131]
	v_mfma_f32_16x16x32_bf16 v[124:127], v[144:147], v[168:171], v[124:127]
	v_mfma_f32_16x16x32_bf16 v[112:115], v[136:139], v[176:179], v[112:115]
	v_mfma_f32_16x16x32_bf16 v[108:111], v[144:147], v[176:179], v[108:111]
	v_mfma_f32_16x16x32_bf16 v[96:99], v[136:139], v[184:187], v[96:99]
	v_mfma_f32_16x16x32_bf16 v[92:95], v[144:147], v[184:187], v[92:95]
	v_mfma_f32_16x16x32_bf16 v[80:83], v[136:139], v[210:213], v[80:83]
	v_mfma_f32_16x16x32_bf16 v[76:79], v[144:147], v[210:213], v[76:79]
	s_setprio 0
	s_setprio 1
	v_mfma_f32_16x16x32_bf16 v[120:123], v[148:151], v[164:167], v[120:123]
	v_mfma_f32_16x16x32_bf16 v[116:119], v[156:159], v[164:167], v[116:119]
	v_mfma_f32_16x16x32_bf16 v[104:107], v[148:151], v[172:175], v[104:107]
	v_mfma_f32_16x16x32_bf16 v[100:103], v[156:159], v[172:175], v[100:103]
	v_mfma_f32_16x16x32_bf16 v[88:91], v[148:151], v[180:183], v[88:91]
	v_mfma_f32_16x16x32_bf16 v[84:87], v[156:159], v[180:183], v[84:87]
	v_mfma_f32_16x16x32_bf16 v[72:75], v[148:151], v[206:209], v[72:75]
	v_mfma_f32_16x16x32_bf16 v[68:71], v[156:159], v[206:209], v[68:71]
	v_mfma_f32_16x16x32_bf16 v[120:123], v[152:155], v[168:171], v[120:123]
	v_mfma_f32_16x16x32_bf16 v[116:119], v[160:163], v[168:171], v[116:119]
	v_mfma_f32_16x16x32_bf16 v[104:107], v[152:155], v[176:179], v[104:107]
	v_mfma_f32_16x16x32_bf16 v[100:103], v[160:163], v[176:179], v[100:103]
	v_mfma_f32_16x16x32_bf16 v[88:91], v[152:155], v[184:187], v[88:91]
	v_mfma_f32_16x16x32_bf16 v[84:87], v[160:163], v[184:187], v[84:87]
	v_mfma_f32_16x16x32_bf16 v[72:75], v[152:155], v[210:213], v[72:75]
	v_mfma_f32_16x16x32_bf16 v[68:71], v[160:163], v[210:213], v[68:71]
	s_setprio 0
	s_barrier
	s_add_i32 s66, s66, s47
	v_lshl_add_u64 v[214:215], s[64:65], 0, v[196:197]
	s_mov_b32 m0, s66
	ds_read_b128 v[164:167], v220 offset:16384
	ds_read_b128 v[168:171], v220 offset:17408
	ds_read_b128 v[172:175], v220 offset:18432
	ds_read_b128 v[176:179], v220 offset:19456
	ds_read_b128 v[180:183], v220 offset:20480
	ds_read_b128 v[184:187], v220 offset:21504
	ds_read_b128 v[206:209], v220 offset:22528
	ds_read_b128 v[210:213], v220 offset:23552
	global_load_lds_dwordx4 v[214:215], off
	s_add_i32 m0, s66, 0x2000
	v_lshl_add_u64 v[216:217], s[64:65], 0, v[32:33]
	s_add_u32 s64, s64, s4
	s_addc_u32 s65, s65, 0
	s_add_i32 s63, s63, s47
	global_load_lds_dwordx4 v[216:217], off
	v_lshl_add_u64 v[222:223], s[64:65], 0, v[196:197]
	s_mov_b32 m0, s63
	v_lshl_add_u64 v[224:225], s[64:65], 0, v[32:33]
	global_load_lds_dwordx4 v[222:223], off
	s_add_i32 m0, s63, 0x2000
	v_lshl_add_u64 v[226:227], s[40:41], 0, v[190:191]
	global_load_lds_dwordx4 v[224:225], off
	s_mov_b32 m0, s48
	v_lshl_add_u64 v[236:237], s[40:41], 0, v[188:189]
	global_load_lds_dwordx4 v[226:227], off
	s_mov_b32 m0, s49
	s_nop 0
	global_load_lds_dwordx4 v[236:237], off
	s_waitcnt vmcnt(8)
	s_waitcnt lgkmcnt(0)
	v_mfma_f32_16x16x32_bf16 v[64:67], v[132:135], v[164:167], v[64:67]
	v_mfma_f32_16x16x32_bf16 v[60:63], v[140:143], v[164:167], v[60:63]
	v_mfma_f32_16x16x32_bf16 v[48:51], v[132:135], v[172:175], v[48:51]
	v_mfma_f32_16x16x32_bf16 v[44:47], v[140:143], v[172:175], v[44:47]
	s_barrier
; #define PG8_STAGE(bufoff, gbase, voff) do { _Pragma("unroll") for (int _i = 0; _i < 2; ++_i) \
;         __builtin_amdgcn_global_load_lds((const unsigned*)((const char*)(gbase) + (voff)[_i]), (PG8_LAS unsigned*)(lds + (bufoff) + ldsw + _i * 8192), 16, 0, 0); } while (0)
; #define PG8_LDA(dst, b, h) do { _Pragma("unroll") for (int m = 0; m < 4; ++m) _Pragma("unroll") for (int k = 0; k < 2; ++k) dst[m][k] = *(const PG8_LAS bf16x8*)(lds + PG8_SA(b, h) + aoff + m * 2048 + k * 1024); } while (0)
; #define PG8_LDB(dst, b, h) do { _Pragma("unroll") for (int n = 0; n < 2; ++n) _Pragma("unroll") for (int k = 0; k < 2; ++k) dst[n][k] = *(const PG8_LAS bf16x8*)(lds + PG8_SB(b, h) + boff + n * 2048 + k * 1024); } while (0)
; #define PG8_MMA(ai, bj, At, Bt) do { __builtin_amdgcn_s_setprio(1); _Pragma("unroll") for (int m = 0; m < 4; ++m) _Pragma("unroll") for (int n = 0; n < 2; ++n) _Pragma("unroll") for (int k = 0; k < 2; ++k) \
;         acc[ai][bj][m][n] = __builtin_amdgcn_mfma_f32_16x16x32_bf16(Bt[n][k], At[m][k], acc[ai][bj][m][n], 0, 0, 0); __builtin_amdgcn_s_setprio(0); } while (0)
; #define PG8_WAIT_V(n) asm volatile("s_waitcnt vmcnt(" #n ")" ::: "memory")
; template <class Epi, class Sched, bool ALIGN_EPI = false, bool SP2 = false>
; __device__ __forceinline__ void gemm_phase(PG8_LAS unsigned char* lds, const Gemm g, const Sched& S, const Epi& E) {
;     ...
;             PG8_LDB(B0, 0, 0); PG8_LDB(B1, 0, 1); PG8_SCHED; PG8_LDA(At, 0, 0); PG8_STAGE(PG8_SA(1, 1), a1 + hstep, voffA);
;             PG8_WAIT_V(8); PG8_WAIT_L(0); PG8_BAR; PG8_MMA(0, 0, At, B0); PG8_MMA(0, 1, At, B1); PG8_BAR; PG8_SCHED;
;             PG8_LDA(At, 0, 1); PG8_STAGE(PG8_SB(0, 0), b2, voffB); PG8_STAGE(PG8_SB(0, 1), b2 + hstep, voffB); PG8_STAGE(PG8_SA(0, 0), a2, voffA);
;             PG8_WAIT_V(8); PG8_WAIT_L(0); PG8_BAR; PG8_MMA(1, 0, At, B0); PG8_MMA(1, 1, At, B1); PG8_BAR; PG8_SCHED;
;             PG8_LDB(B0, 1, 0); PG8_LDB(B1, 1, 1); PG8_SCHED; PG8_LDA(At, 1, 0); PG8_STAGE(PG8_SA(0, 1), a2 + hstep, voffA);
;             PG8_WAIT_V(8); PG8_WAIT_L(0); PG8_BAR; PG8_MMA(0, 0, At, B0); PG8_MMA(0, 1, At, B1); PG8_BAR; PG8_SCHED;
;             PG8_LDA(At, 1, 1); PG8_STAGE(PG8_SB(1, 0), b3, voffB); PG8_STAGE(PG8_SB(1, 1), b3 + hstep, voffB); PG8_STAGE(PG8_SA(1, 0), a3, voffA);
;             PG8_WAIT_V(8); PG8_WAIT_L(0); PG8_BAR; PG8_MMA(1, 0, At, B0); PG8_MMA(1, 1, At, B1); PG8_BAR; PG8_SCHED;
	s_setprio 1
	v_mfma_f32_16x16x32_bf16 v[28:31], v[132:135], v[180:183], v[28:31]
	v_mfma_f32_16x16x32_bf16 v[24:27], v[140:143], v[180:183], v[24:27]
	v_mfma_f32_16x16x32_bf16 v[12:15], v[132:135], v[206:209], v[12:15]
	v_mfma_f32_16x16x32_bf16 v[8:11], v[140:143], v[206:209], v[8:11]
	v_mfma_f32_16x16x32_bf16 v[64:67], v[136:139], v[168:171], v[64:67]
	v_mfma_f32_16x16x32_bf16 v[60:63], v[144:147], v[168:171], v[60:63]
	v_mfma_f32_16x16x32_bf16 v[48:51], v[136:139], v[176:179], v[48:51]
	v_mfma_f32_16x16x32_bf16 v[44:47], v[144:147], v[176:179], v[44:47]
	v_mfma_f32_16x16x32_bf16 v[28:31], v[136:139], v[184:187], v[28:31]
	v_mfma_f32_16x16x32_bf16 v[24:27], v[144:147], v[184:187], v[24:27]
	v_mfma_f32_16x16x32_bf16 v[12:15], v[136:139], v[210:213], v[12:15]
	v_mfma_f32_16x16x32_bf16 v[8:11], v[144:147], v[210:213], v[8:11]
	s_setprio 0
	s_setprio 1
	v_mfma_f32_16x16x32_bf16 v[56:59], v[148:151], v[164:167], v[56:59]
	v_mfma_f32_16x16x32_bf16 v[52:55], v[156:159], v[164:167], v[52:55]
	v_mfma_f32_16x16x32_bf16 v[40:43], v[148:151], v[172:175], v[40:43]
	v_mfma_f32_16x16x32_bf16 v[36:39], v[156:159], v[172:175], v[36:39]
	v_mfma_f32_16x16x32_bf16 v[20:23], v[148:151], v[180:183], v[20:23]
	v_mfma_f32_16x16x32_bf16 v[16:19], v[156:159], v[180:183], v[16:19]
	v_mfma_f32_16x16x32_bf16 v[4:7], v[148:151], v[206:209], v[4:7]
	v_mfma_f32_16x16x32_bf16 v[0:3], v[156:159], v[206:209], v[0:3]
	v_mfma_f32_16x16x32_bf16 v[56:59], v[152:155], v[168:171], v[56:59]
	v_mfma_f32_16x16x32_bf16 v[52:55], v[160:163], v[168:171], v[52:55]
	v_mfma_f32_16x16x32_bf16 v[40:43], v[152:155], v[176:179], v[40:43]
	v_mfma_f32_16x16x32_bf16 v[36:39], v[160:163], v[176:179], v[36:39]
	v_mfma_f32_16x16x32_bf16 v[20:23], v[152:155], v[184:187], v[20:23]
	v_mfma_f32_16x16x32_bf16 v[16:19], v[160:163], v[184:187], v[16:19]
	v_mfma_f32_16x16x32_bf16 v[4:7], v[152:155], v[210:213], v[4:7]
	v_mfma_f32_16x16x32_bf16 v[0:3], v[160:163], v[210:213], v[0:3]
	s_setprio 0
	s_barrier
	s_add_i32 s63, 0, 0x18000
	s_add_i32 s64, 0, 0x1c000
	v_add_u32_e32 v144, s63, v218
	v_add_u32_e32 v160, s64, v218
	ds_read_b128 v[132:135], v144
	ds_read_b128 v[136:139], v144 offset:1024
	ds_read_b128 v[140:143], v144 offset:2048
	ds_read_b128 v[144:147], v144 offset:3072
	ds_read_b128 v[148:151], v160
	ds_read_b128 v[152:155], v160 offset:1024
	ds_read_b128 v[156:159], v160 offset:2048
	ds_read_b128 v[160:163], v160 offset:3072
	s_add_u32 s40, s40, s4
	s_addc_u32 s41, s41, 0
	s_mov_b32 m0, s50
	v_lshl_add_u64 v[238:239], s[40:41], 0, v[190:191]
	ds_read_b128 v[164:167], v220 offset:32768
	ds_read_b128 v[168:171], v220 offset:33792
	ds_read_b128 v[172:175], v220 offset:34816
	ds_read_b128 v[176:179], v220 offset:35840
	ds_read_b128 v[180:183], v220 offset:36864
	ds_read_b128 v[184:187], v220 offset:37888
	ds_read_b128 v[206:209], v220 offset:38912
	ds_read_b128 v[210:213], v220 offset:39936
	global_load_lds_dwordx4 v[238:239], off
	v_lshl_add_u64 v[238:239], s[40:41], 0, v[188:189]
	s_mov_b32 m0, s51
	s_nop 0
	global_load_lds_dwordx4 v[238:239], off
	s_waitcnt vmcnt(8)
	s_waitcnt lgkmcnt(0)
	v_mfma_f32_16x16x32_bf16 v[128:131], v[132:135], v[164:167], v[128:131]
	v_mfma_f32_16x16x32_bf16 v[124:127], v[140:143], v[164:167], v[124:127]
	v_mfma_f32_16x16x32_bf16 v[112:115], v[132:135], v[172:175], v[112:115]
	v_mfma_f32_16x16x32_bf16 v[108:111], v[140:143], v[172:175], v[108:111]
	s_barrier
	s_setprio 1
	v_mfma_f32_16x16x32_bf16 v[96:99], v[132:135], v[180:183], v[96:99]
	v_mfma_f32_16x16x32_bf16 v[92:95], v[140:143], v[180:183], v[92:95]
	v_mfma_f32_16x16x32_bf16 v[80:83], v[132:135], v[206:209], v[80:83]
	v_mfma_f32_16x16x32_bf16 v[76:79], v[140:143], v[206:209], v[76:79]
	v_mfma_f32_16x16x32_bf16 v[128:131], v[136:139], v[168:171], v[128:131]
	v_mfma_f32_16x16x32_bf16 v[124:127], v[144:147], v[168:171], v[124:127]
	v_mfma_f32_16x16x32_bf16 v[112:115], v[136:139], v[176:179], v[112:115]
	v_mfma_f32_16x16x32_bf16 v[108:111], v[144:147], v[176:179], v[108:111]
	v_mfma_f32_16x16x32_bf16 v[96:99], v[136:139], v[184:187], v[96:99]
	v_mfma_f32_16x16x32_bf16 v[92:95], v[144:147], v[184:187], v[92:95]
	v_mfma_f32_16x16x32_bf16 v[80:83], v[136:139], v[210:213], v[80:83]
	v_mfma_f32_16x16x32_bf16 v[76:79], v[144:147], v[210:213], v[76:79]
	s_setprio 0
	s_setprio 1
	v_mfma_f32_16x16x32_bf16 v[120:123], v[148:151], v[164:167], v[120:123]
	v_mfma_f32_16x16x32_bf16 v[116:119], v[156:159], v[164:167], v[116:119]
	v_mfma_f32_16x16x32_bf16 v[104:107], v[148:151], v[172:175], v[104:107]
	v_mfma_f32_16x16x32_bf16 v[100:103], v[156:159], v[172:175], v[100:103]
	v_mfma_f32_16x16x32_bf16 v[88:91], v[148:151], v[180:183], v[88:91]
	v_mfma_f32_16x16x32_bf16 v[84:87], v[156:159], v[180:183], v[84:87]
	v_mfma_f32_16x16x32_bf16 v[72:75], v[148:151], v[206:209], v[72:75]
	v_mfma_f32_16x16x32_bf16 v[68:71], v[156:159], v[206:209], v[68:71]
	v_mfma_f32_16x16x32_bf16 v[120:123], v[152:155], v[168:171], v[120:123]
	v_mfma_f32_16x16x32_bf16 v[116:119], v[160:163], v[168:171], v[116:119]
	v_mfma_f32_16x16x32_bf16 v[104:107], v[152:155], v[176:179], v[104:107]
	v_mfma_f32_16x16x32_bf16 v[100:103], v[160:163], v[176:179], v[100:103]
	v_mfma_f32_16x16x32_bf16 v[88:91], v[152:155], v[184:187], v[88:91]
	v_mfma_f32_16x16x32_bf16 v[84:87], v[160:163], v[184:187], v[84:87]
	v_mfma_f32_16x16x32_bf16 v[72:75], v[152:155], v[210:213], v[72:75]
	v_mfma_f32_16x16x32_bf16 v[68:71], v[160:163], v[210:213], v[68:71]
	s_setprio 0
	s_barrier
; #define PG8_STAGE(bufoff, gbase, voff) do { _Pragma("unroll") for (int _i = 0; _i < 2; ++_i) \
;         __builtin_amdgcn_global_load_lds((const unsigned*)((const char*)(gbase) + (voff)[_i]), (PG8_LAS unsigned*)(lds + (bufoff) + ldsw + _i * 8192), 16, 0, 0); } while (0)
; #define PG8_LDA(dst, b, h) do { _Pragma("unroll") for (int m = 0; m < 4; ++m) _Pragma("unroll") for (int k = 0; k < 2; ++k) dst[m][k] = *(const PG8_LAS bf16x8*)(lds + PG8_SA(b, h) + aoff + m * 2048 + k * 1024); } while (0)
; #define PG8_LDB(dst, b, h) do { _Pragma("unroll") for (int n = 0; n < 2; ++n) _Pragma("unroll") for (int k = 0; k < 2; ++k) dst[n][k] = *(const PG8_LAS bf16x8*)(lds + PG8_SB(b, h) + boff + n * 2048 + k * 1024); } while (0)
; #define PG8_MMA(ai, bj, At, Bt) do { __builtin_amdgcn_s_setprio(1); _Pragma("unroll") for (int m = 0; m < 4; ++m) _Pragma("unroll") for (int n = 0; n < 2; ++n) _Pragma("unroll") for (int k = 0; k < 2; ++k) \
;         acc[ai][bj][m][n] = __builtin_amdgcn_mfma_f32_16x16x32_bf16(Bt[n][k], At[m][k], acc[ai][bj][m][n], 0, 0, 0); __builtin_amdgcn_s_setprio(0); } while (0)
; #define PG8_WAIT_V(n) asm volatile("s_waitcnt vmcnt(" #n ")" ::: "memory")
; template <class Epi, class Sched, bool ALIGN_EPI = false, bool SP2 = false>
; __device__ __forceinline__ void gemm_phase(PG8_LAS unsigned char* lds, const Gemm g, const Sched& S, const Epi& E) {
;     ...
;             PG8_LDB(B0, 0, 0); PG8_LDB(B1, 0, 1); PG8_SCHED; PG8_LDA(At, 0, 0); PG8_STAGE(PG8_SA(1, 1), a1 + hstep, voffA);
;             PG8_WAIT_V(8); PG8_WAIT_L(0); PG8_BAR; PG8_MMA(0, 0, At, B0); PG8_MMA(0, 1, At, B1); PG8_BAR; PG8_SCHED;
;             PG8_LDA(At, 0, 1); PG8_STAGE(PG8_SB(0, 0), b2, voffB); PG8_STAGE(PG8_SB(0, 1), b2 + hstep, voffB); PG8_STAGE(PG8_SA(0, 0), a2, voffA);
;             PG8_WAIT_V(8); PG8_WAIT_L(0); PG8_BAR; PG8_MMA(1, 0, At, B0); PG8_MMA(1, 1, At, B1); PG8_BAR; PG8_SCHED;
;             PG8_LDB(B0, 1, 0); PG8_LDB(B1, 1, 1); PG8_SCHED; PG8_LDA(At, 1, 0); PG8_STAGE(PG8_SA(0, 1), a2 + hstep, voffA);
;             PG8_WAIT_V(8); PG8_WAIT_L(0); PG8_BAR; PG8_MMA(0, 0, At, B0); PG8_MMA(0, 1, At, B1); PG8_BAR; PG8_SCHED;
;             PG8_LDA(At, 1, 1); PG8_STAGE(PG8_SB(1, 0), b3, voffB); PG8_STAGE(PG8_SB(1, 1), b3 + hstep, voffB); PG8_STAGE(PG8_SA(1, 0), a3, voffA);
;             PG8_WAIT_V(8); PG8_WAIT_L(0); PG8_BAR; PG8_MMA(1, 0, At, B0); PG8_MMA(1, 1, At, B1); PG8_BAR; PG8_SCHED;
	s_add_i32 s40, s63, s47
	v_lshl_add_u64 v[214:215], v[214:215], 0, s[36:37]
	s_mov_b32 m0, s40
	ds_read_b128 v[164:167], v220 offset:49152
	ds_read_b128 v[168:171], v220 offset:50176
	ds_read_b128 v[172:175], v220 offset:51200
	ds_read_b128 v[176:179], v220 offset:52224
	ds_read_b128 v[180:183], v220 offset:53248
	ds_read_b128 v[184:187], v220 offset:54272
	ds_read_b128 v[206:209], v220 offset:55296
	ds_read_b128 v[210:213], v220 offset:56320
	global_load_lds_dwordx4 v[214:215], off
	v_lshl_add_u64 v[214:215], v[216:217], 0, s[36:37]
	s_add_i32 m0, s40, 0x2000
	s_add_i32 s40, s64, s47
	global_load_lds_dwordx4 v[214:215], off
	v_lshl_add_u64 v[214:215], v[222:223], 0, s[36:37]
	s_mov_b32 m0, s40
	s_nop 0
	global_load_lds_dwordx4 v[214:215], off
	v_lshl_add_u64 v[214:215], v[224:225], 0, s[36:37]
	s_add_i32 m0, s40, 0x2000
	s_nop 0
	global_load_lds_dwordx4 v[214:215], off
	v_lshl_add_u64 v[214:215], v[226:227], 0, s[36:37]
	s_mov_b32 m0, s52
	s_nop 0
	global_load_lds_dwordx4 v[214:215], off
	v_lshl_add_u64 v[214:215], v[236:237], 0, s[36:37]
	s_mov_b32 m0, s53
	s_nop 0
	global_load_lds_dwordx4 v[214:215], off
	s_waitcnt vmcnt(8)
	s_waitcnt lgkmcnt(0)
	v_mfma_f32_16x16x32_bf16 v[64:67], v[132:135], v[164:167], v[64:67]
	v_mfma_f32_16x16x32_bf16 v[60:63], v[140:143], v[164:167], v[60:63]
	v_mfma_f32_16x16x32_bf16 v[48:51], v[132:135], v[172:175], v[48:51]
	v_mfma_f32_16x16x32_bf16 v[44:47], v[140:143], v[172:175], v[44:47]
	s_barrier
	s_setprio 1
	v_mfma_f32_16x16x32_bf16 v[28:31], v[132:135], v[180:183], v[28:31]
	v_mfma_f32_16x16x32_bf16 v[24:27], v[140:143], v[180:183], v[24:27]
	v_mfma_f32_16x16x32_bf16 v[12:15], v[132:135], v[206:209], v[12:15]
	v_mfma_f32_16x16x32_bf16 v[8:11], v[140:143], v[206:209], v[8:11]
	v_mfma_f32_16x16x32_bf16 v[64:67], v[136:139], v[168:171], v[64:67]
	v_mfma_f32_16x16x32_bf16 v[60:63], v[144:147], v[168:171], v[60:63]
	v_mfma_f32_16x16x32_bf16 v[48:51], v[136:139], v[176:179], v[48:51]
	v_mfma_f32_16x16x32_bf16 v[44:47], v[144:147], v[176:179], v[44:47]
	v_mfma_f32_16x16x32_bf16 v[28:31], v[136:139], v[184:187], v[28:31]
	v_mfma_f32_16x16x32_bf16 v[24:27], v[144:147], v[184:187], v[24:27]
	v_mfma_f32_16x16x32_bf16 v[12:15], v[136:139], v[210:213], v[12:15]
	v_mfma_f32_16x16x32_bf16 v[8:11], v[144:147], v[210:213], v[8:11]
	s_setprio 0
	s_setprio 1
	v_mfma_f32_16x16x32_bf16 v[56:59], v[148:151], v[164:167], v[56:59]
	v_mfma_f32_16x16x32_bf16 v[52:55], v[156:159], v[164:167], v[52:55]
	v_mfma_f32_16x16x32_bf16 v[40:43], v[148:151], v[172:175], v[40:43]
	v_mfma_f32_16x16x32_bf16 v[36:39], v[156:159], v[172:175], v[36:39]
	v_mfma_f32_16x16x32_bf16 v[20:23], v[148:151], v[180:183], v[20:23]
	v_mfma_f32_16x16x32_bf16 v[16:19], v[156:159], v[180:183], v[16:19]
	v_mfma_f32_16x16x32_bf16 v[4:7], v[148:151], v[206:209], v[4:7]
	v_mfma_f32_16x16x32_bf16 v[0:3], v[156:159], v[206:209], v[0:3]
	v_mfma_f32_16x16x32_bf16 v[56:59], v[152:155], v[168:171], v[56:59]
	v_mfma_f32_16x16x32_bf16 v[52:55], v[160:163], v[168:171], v[52:55]
	v_mfma_f32_16x16x32_bf16 v[40:43], v[152:155], v[176:179], v[40:43]
	v_mfma_f32_16x16x32_bf16 v[36:39], v[160:163], v[176:179], v[36:39]
	v_mfma_f32_16x16x32_bf16 v[20:23], v[152:155], v[184:187], v[20:23]
	v_mfma_f32_16x16x32_bf16 v[16:19], v[160:163], v[184:187], v[16:19]
	v_mfma_f32_16x16x32_bf16 v[4:7], v[152:155], v[210:213], v[4:7]
	v_mfma_f32_16x16x32_bf16 v[0:3], v[160:163], v[210:213], v[0:3]
	s_setprio 0
	s_barrier
	s_add_u32 s22, s22, 0x100
	s_addc_u32 s23, s23, 0
	s_add_u32 s60, s60, 0x100
	s_addc_u32 s61, s61, 0
	s_cmp_ge_u32 s62, s55
	s_mov_b32 s40, s62
	s_cbranch_scc0 .LBB0_589
	s_and_b64 vcc, exec, s[16:17]
	s_cbranch_vccz .LBB0_592
	s_barrier

; #define PG8_STAGE(bufoff, gbase, voff) do { _Pragma("unroll") for (int _i = 0; _i < 2; ++_i) \
;         __builtin_amdgcn_global_load_lds((const unsigned*)((const char*)(gbase) + (voff)[_i]), (PG8_LAS unsigned*)(lds + (bufoff) + ldsw + _i * 8192), 16, 0, 0); } while (0)
; #define PG8_LDA(dst, b, h) do { _Pragma("unroll") for (int m = 0; m < 4; ++m) _Pragma("unroll") for (int k = 0; k < 2; ++k) dst[m][k] = *(const PG8_LAS bf16x8*)(lds + PG8_SA(b, h) + aoff + m * 2048 + k * 1024); } while (0)
; #define PG8_LDB(dst, b, h) do { _Pragma("unroll") for (int n = 0; n < 2; ++n) _Pragma("unroll") for (int k = 0; k < 2; ++k) dst[n][k] = *(const PG8_LAS bf16x8*)(lds + PG8_SB(b, h) + boff + n * 2048 + k * 1024); } while (0)
; #define PG8_MMA(ai, bj, At, Bt) do { __builtin_amdgcn_s_setprio(1); _Pragma("unroll") for (int m = 0; m < 4; ++m) _Pragma("unroll") for (int n = 0; n < 2; ++n) _Pragma("unroll") for (int k = 0; k < 2; ++k) \
;         acc[ai][bj][m][n] = __builtin_amdgcn_mfma_f32_16x16x32_bf16(Bt[n][k], At[m][k], acc[ai][bj][m][n], 0, 0, 0); __builtin_amdgcn_s_setprio(0); } while (0)
; #define PG8_WAIT_V(n) asm volatile("s_waitcnt vmcnt(" #n ")" ::: "memory")
; template <class Epi, class Sched, bool ALIGN_EPI = false, bool SP2 = false>
; __device__ __forceinline__ void gemm_phase(PG8_LAS unsigned char* lds, const Gemm g, const Sched& S, const Epi& E) {
;     ...
;             PG8_LDB(B0, 0, 0); PG8_LDB(B1, 0, 1); PG8_SCHED; PG8_LDA(At, 0, 0); PG8_STAGE(PG8_SA(1, 1), a1 + hstep, voffA);
;             PG8_WAIT_V(8); PG8_WAIT_L(0); PG8_BAR; PG8_MMA(0, 0, At, B0); PG8_MMA(0, 1, At, B1); PG8_BAR; PG8_SCHED;
;             PG8_LDA(At, 0, 1); PG8_STAGE(PG8_SB(0, 0), b2, voffB); PG8_STAGE(PG8_SB(0, 1), b2 + hstep, voffB); PG8_STAGE(PG8_SA(0, 0), a2, voffA);
;             PG8_WAIT_V(8); PG8_WAIT_L(0); PG8_BAR; PG8_MMA(1, 0, At, B0); PG8_MMA(1, 1, At, B1); PG8_BAR; PG8_SCHED;
;             PG8_LDB(B0, 1, 0); PG8_LDB(B1, 1, 1); PG8_SCHED; PG8_LDA(At, 1, 0); PG8_STAGE(PG8_SA(0, 1), a2 + hstep, voffA);
;             PG8_WAIT_V(8); PG8_WAIT_L(0); PG8_BAR; PG8_MMA(0, 0, At, B0); PG8_MMA(0, 1, At, B1); PG8_BAR; PG8_SCHED;
;             PG8_LDA(At, 1, 1); PG8_STAGE(PG8_SB(1, 0), b3, voffB); PG8_STAGE(PG8_SB(1, 1), b3 + hstep, voffB); PG8_STAGE(PG8_SA(1, 0), a3, voffA);
;             PG8_WAIT_V(8); PG8_WAIT_L(0); PG8_BAR; PG8_MMA(1, 0, At, B0); PG8_MMA(1, 1, At, B1); PG8_BAR; PG8_SCHED;
.LBB0_623:
	s_add_u32 s22, s0, 0xfffc0080
	s_addc_u32 s23, s1, -1
	s_add_i32 s58, 0, 0x10000
	s_cmp_eq_u32 s57, 12
	s_cselect_b32 s41, s17, s23
	s_cselect_b32 s40, s53, s22
	v_add_u32_e32 v144, s58, v147
	s_cselect_b32 s23, s15, s56
	s_cselect_b32 s22, s54, s55
	s_add_i32 s60, 0, 0x14000
	ds_read_b128 v[140:143], v144
	ds_read_b128 v[150:153], v144 offset:1024
	ds_read_b128 v[154:157], v144 offset:2048
	ds_read_b128 v[158:161], v144 offset:3072
	v_add_u32_e32 v144, s60, v147
	ds_read_b128 v[162:165], v144
	ds_read_b128 v[166:169], v144 offset:1024
	ds_read_b128 v[170:173], v144 offset:2048
	ds_read_b128 v[174:177], v144 offset:3072
	v_lshl_add_u64 v[144:145], s[0:1], 0, v[136:137]
	s_add_i32 m0, s44, 0xc000
	ds_read_b128 v[178:181], v149
	ds_read_b128 v[182:185], v149 offset:1024
	ds_read_b128 v[186:189], v149 offset:2048
	ds_read_b128 v[190:193], v149 offset:3072
	ds_read_b128 v[202:205], v149 offset:4096
	ds_read_b128 v[206:209], v149 offset:5120
	ds_read_b128 v[210:213], v149 offset:6144
	ds_read_b128 v[214:217], v149 offset:7168
	global_load_lds_dwordx4 v[144:145], off
	v_lshl_add_u64 v[144:145], s[0:1], 0, v[138:139]
	s_add_i32 m0, s44, 0xe000
	s_nop 0
	global_load_lds_dwordx4 v[144:145], off
	s_waitcnt vmcnt(8)
	s_waitcnt lgkmcnt(0)
	v_mfma_f32_16x16x32_bf16 v[128:131], v[140:143], v[178:181], v[128:131]
	v_mfma_f32_16x16x32_bf16 v[124:127], v[154:157], v[178:181], v[124:127]
	v_mfma_f32_16x16x32_bf16 v[112:115], v[140:143], v[186:189], v[112:115]
	v_mfma_f32_16x16x32_bf16 v[108:111], v[154:157], v[186:189], v[108:111]
	s_barrier
	s_setprio 1
	v_mfma_f32_16x16x32_bf16 v[96:99], v[140:143], v[202:205], v[96:99]
	v_mfma_f32_16x16x32_bf16 v[92:95], v[154:157], v[202:205], v[92:95]
	v_mfma_f32_16x16x32_bf16 v[80:83], v[140:143], v[210:213], v[80:83]
	v_mfma_f32_16x16x32_bf16 v[76:79], v[154:157], v[210:213], v[76:79]
	v_mfma_f32_16x16x32_bf16 v[128:131], v[150:153], v[182:185], v[128:131]
	v_mfma_f32_16x16x32_bf16 v[124:127], v[158:161], v[182:185], v[124:127]
	v_mfma_f32_16x16x32_bf16 v[112:115], v[150:153], v[190:193], v[112:115]
	v_mfma_f32_16x16x32_bf16 v[108:111], v[158:161], v[190:193], v[108:111]
	v_mfma_f32_16x16x32_bf16 v[96:99], v[150:153], v[206:209], v[96:99]
	v_mfma_f32_16x16x32_bf16 v[92:95], v[158:161], v[206:209], v[92:95]
	v_mfma_f32_16x16x32_bf16 v[80:83], v[150:153], v[214:217], v[80:83]
	v_mfma_f32_16x16x32_bf16 v[76:79], v[158:161], v[214:217], v[76:79]
	s_setprio 0
	s_setprio 1
	v_mfma_f32_16x16x32_bf16 v[120:123], v[162:165], v[178:181], v[120:123]
	v_mfma_f32_16x16x32_bf16 v[116:119], v[170:173], v[178:181], v[116:119]
	v_mfma_f32_16x16x32_bf16 v[104:107], v[162:165], v[186:189], v[104:107]
	v_mfma_f32_16x16x32_bf16 v[100:103], v[170:173], v[186:189], v[100:103]
	v_mfma_f32_16x16x32_bf16 v[88:91], v[162:165], v[202:205], v[88:91]
	v_mfma_f32_16x16x32_bf16 v[84:87], v[170:173], v[202:205], v[84:87]
	v_mfma_f32_16x16x32_bf16 v[72:75], v[162:165], v[210:213], v[72:75]
	v_mfma_f32_16x16x32_bf16 v[68:71], v[170:173], v[210:213], v[68:71]
	v_mfma_f32_16x16x32_bf16 v[120:123], v[166:169], v[182:185], v[120:123]
	v_mfma_f32_16x16x32_bf16 v[116:119], v[174:177], v[182:185], v[116:119]
	v_mfma_f32_16x16x32_bf16 v[104:107], v[166:169], v[190:193], v[104:107]
	v_mfma_f32_16x16x32_bf16 v[100:103], v[174:177], v[190:193], v[100:103]
	v_mfma_f32_16x16x32_bf16 v[88:91], v[166:169], v[206:209], v[88:91]
	v_mfma_f32_16x16x32_bf16 v[84:87], v[174:177], v[206:209], v[84:87]
	v_mfma_f32_16x16x32_bf16 v[72:75], v[166:169], v[214:217], v[72:75]
	v_mfma_f32_16x16x32_bf16 v[68:71], v[174:177], v[214:217], v[68:71]
	s_setprio 0
	s_barrier
	s_add_i32 s58, s58, s43
	v_lshl_add_u64 v[144:145], s[22:23], 0, v[196:197]
	s_mov_b32 m0, s58
	ds_read_b128 v[178:181], v149 offset:16384
	ds_read_b128 v[182:185], v149 offset:17408
	ds_read_b128 v[186:189], v149 offset:18432
	ds_read_b128 v[190:193], v149 offset:19456
	ds_read_b128 v[202:205], v149 offset:20480
	ds_read_b128 v[206:209], v149 offset:21504
	ds_read_b128 v[210:213], v149 offset:22528
	ds_read_b128 v[214:217], v149 offset:23552
	global_load_lds_dwordx4 v[144:145], off
	s_add_i32 m0, s58, 0x2000
	s_add_u32 s58, s22, 0x40000
	v_lshl_add_u64 v[194:195], s[22:23], 0, v[32:33]
	s_addc_u32 s59, s23, 0
	s_add_i32 s60, s60, s43
	global_load_lds_dwordx4 v[194:195], off
	v_lshl_add_u64 v[218:219], s[58:59], 0, v[196:197]
	s_mov_b32 m0, s60
	v_lshl_add_u64 v[220:221], s[40:41], 0, v[132:133]
	global_load_lds_dwordx4 v[218:219], off
	v_lshl_add_u64 v[218:219], s[58:59], 0, v[32:33]
	s_add_i32 m0, s60, 0x2000
	s_nop 0
	global_load_lds_dwordx4 v[218:219], off
	v_lshl_add_u64 v[218:219], s[40:41], 0, v[134:135]
	s_mov_b32 m0, s44
	s_nop 0
	global_load_lds_dwordx4 v[218:219], off
	s_mov_b32 m0, s45
	s_nop 0
	global_load_lds_dwordx4 v[220:221], off
	s_waitcnt vmcnt(8)
	s_waitcnt lgkmcnt(0)
	v_mfma_f32_16x16x32_bf16 v[64:67], v[140:143], v[178:181], v[64:67]
	v_mfma_f32_16x16x32_bf16 v[60:63], v[154:157], v[178:181], v[60:63]
	v_mfma_f32_16x16x32_bf16 v[48:51], v[140:143], v[186:189], v[48:51]
	v_mfma_f32_16x16x32_bf16 v[44:47], v[154:157], v[186:189], v[44:47]
	s_barrier
; #define PG8_STAGE(bufoff, gbase, voff) do { _Pragma("unroll") for (int _i = 0; _i < 2; ++_i) \
;         __builtin_amdgcn_global_load_lds((const unsigned*)((const char*)(gbase) + (voff)[_i]), (PG8_LAS unsigned*)(lds + (bufoff) + ldsw + _i * 8192), 16, 0, 0); } while (0)
; #define PG8_LDA(dst, b, h) do { _Pragma("unroll") for (int m = 0; m < 4; ++m) _Pragma("unroll") for (int k = 0; k < 2; ++k) dst[m][k] = *(const PG8_LAS bf16x8*)(lds + PG8_SA(b, h) + aoff + m * 2048 + k * 1024); } while (0)
; #define PG8_LDB(dst, b, h) do { _Pragma("unroll") for (int n = 0; n < 2; ++n) _Pragma("unroll") for (int k = 0; k < 2; ++k) dst[n][k] = *(const PG8_LAS bf16x8*)(lds + PG8_SB(b, h) + boff + n * 2048 + k * 1024); } while (0)
; #define PG8_MMA(ai, bj, At, Bt) do { __builtin_amdgcn_s_setprio(1); _Pragma("unroll") for (int m = 0; m < 4; ++m) _Pragma("unroll") for (int n = 0; n < 2; ++n) _Pragma("unroll") for (int k = 0; k < 2; ++k) \
;         acc[ai][bj][m][n] = __builtin_amdgcn_mfma_f32_16x16x32_bf16(Bt[n][k], At[m][k], acc[ai][bj][m][n], 0, 0, 0); __builtin_amdgcn_s_setprio(0); } while (0)
; #define PG8_WAIT_V(n) asm volatile("s_waitcnt vmcnt(" #n ")" ::: "memory")
; template <class Epi, class Sched, bool ALIGN_EPI = false, bool SP2 = false>
; __device__ __forceinline__ void gemm_phase(PG8_LAS unsigned char* lds, const Gemm g, const Sched& S, const Epi& E) {
;     ...
;             PG8_LDB(B0, 0, 0); PG8_LDB(B1, 0, 1); PG8_SCHED; PG8_LDA(At, 0, 0); PG8_STAGE(PG8_SA(1, 1), a1 + hstep, voffA);
;             PG8_WAIT_V(8); PG8_WAIT_L(0); PG8_BAR; PG8_MMA(0, 0, At, B0); PG8_MMA(0, 1, At, B1); PG8_BAR; PG8_SCHED;
;             PG8_LDA(At, 0, 1); PG8_STAGE(PG8_SB(0, 0), b2, voffB); PG8_STAGE(PG8_SB(0, 1), b2 + hstep, voffB); PG8_STAGE(PG8_SA(0, 0), a2, voffA);
;             PG8_WAIT_V(8); PG8_WAIT_L(0); PG8_BAR; PG8_MMA(1, 0, At, B0); PG8_MMA(1, 1, At, B1); PG8_BAR; PG8_SCHED;
;             PG8_LDB(B0, 1, 0); PG8_LDB(B1, 1, 1); PG8_SCHED; PG8_LDA(At, 1, 0); PG8_STAGE(PG8_SA(0, 1), a2 + hstep, voffA);
;             PG8_WAIT_V(8); PG8_WAIT_L(0); PG8_BAR; PG8_MMA(0, 0, At, B0); PG8_MMA(0, 1, At, B1); PG8_BAR; PG8_SCHED;
;             PG8_LDA(At, 1, 1); PG8_STAGE(PG8_SB(1, 0), b3, voffB); PG8_STAGE(PG8_SB(1, 1), b3 + hstep, voffB); PG8_STAGE(PG8_SA(1, 0), a3, voffA);
;             PG8_WAIT_V(8); PG8_WAIT_L(0); PG8_BAR; PG8_MMA(1, 0, At, B0); PG8_MMA(1, 1, At, B1); PG8_BAR; PG8_SCHED;
	s_setprio 1
	v_mfma_f32_16x16x32_bf16 v[28:31], v[140:143], v[202:205], v[28:31]
	v_mfma_f32_16x16x32_bf16 v[24:27], v[154:157], v[202:205], v[24:27]
	v_mfma_f32_16x16x32_bf16 v[12:15], v[140:143], v[210:213], v[12:15]
	v_mfma_f32_16x16x32_bf16 v[8:11], v[154:157], v[210:213], v[8:11]
	v_mfma_f32_16x16x32_bf16 v[64:67], v[150:153], v[182:185], v[64:67]
	v_mfma_f32_16x16x32_bf16 v[60:63], v[158:161], v[182:185], v[60:63]
	v_mfma_f32_16x16x32_bf16 v[48:51], v[150:153], v[190:193], v[48:51]
	v_mfma_f32_16x16x32_bf16 v[44:47], v[158:161], v[190:193], v[44:47]
	v_mfma_f32_16x16x32_bf16 v[28:31], v[150:153], v[206:209], v[28:31]
	v_mfma_f32_16x16x32_bf16 v[24:27], v[158:161], v[206:209], v[24:27]
	v_mfma_f32_16x16x32_bf16 v[12:15], v[150:153], v[214:217], v[12:15]
	v_mfma_f32_16x16x32_bf16 v[8:11], v[158:161], v[214:217], v[8:11]
	s_setprio 0
	s_setprio 1
	v_mfma_f32_16x16x32_bf16 v[56:59], v[162:165], v[178:181], v[56:59]
	v_mfma_f32_16x16x32_bf16 v[52:55], v[170:173], v[178:181], v[52:55]
	v_mfma_f32_16x16x32_bf16 v[40:43], v[162:165], v[186:189], v[40:43]
	v_mfma_f32_16x16x32_bf16 v[36:39], v[170:173], v[186:189], v[36:39]
	v_mfma_f32_16x16x32_bf16 v[20:23], v[162:165], v[202:205], v[20:23]
	v_mfma_f32_16x16x32_bf16 v[16:19], v[170:173], v[202:205], v[16:19]
	v_mfma_f32_16x16x32_bf16 v[4:7], v[162:165], v[210:213], v[4:7]
	v_mfma_f32_16x16x32_bf16 v[0:3], v[170:173], v[210:213], v[0:3]
	v_mfma_f32_16x16x32_bf16 v[56:59], v[166:169], v[182:185], v[56:59]
	v_mfma_f32_16x16x32_bf16 v[52:55], v[174:177], v[182:185], v[52:55]
	v_mfma_f32_16x16x32_bf16 v[40:43], v[166:169], v[190:193], v[40:43]
	v_mfma_f32_16x16x32_bf16 v[36:39], v[174:177], v[190:193], v[36:39]
	v_mfma_f32_16x16x32_bf16 v[20:23], v[166:169], v[206:209], v[20:23]
	v_mfma_f32_16x16x32_bf16 v[16:19], v[174:177], v[206:209], v[16:19]
	v_mfma_f32_16x16x32_bf16 v[4:7], v[166:169], v[214:217], v[4:7]
	v_mfma_f32_16x16x32_bf16 v[0:3], v[174:177], v[214:217], v[0:3]
	s_setprio 0
	s_barrier
	s_add_i32 s58, 0, 0x18000
	v_add_u32_e32 v146, s58, v147
	s_add_i32 s59, 0, 0x1c000
	ds_read_b128 v[140:143], v146
	ds_read_b128 v[150:153], v146 offset:1024
	ds_read_b128 v[154:157], v146 offset:2048
	ds_read_b128 v[158:161], v146 offset:3072
	v_add_u32_e32 v146, s59, v147
	ds_read_b128 v[162:165], v146
	ds_read_b128 v[166:169], v146 offset:1024
	ds_read_b128 v[170:173], v146 offset:2048
	ds_read_b128 v[174:177], v146 offset:3072
	s_add_u32 s40, s40, 0x40000
	s_addc_u32 s41, s41, 0
	s_mov_b32 m0, s46
	v_lshl_add_u64 v[222:223], s[40:41], 0, v[134:135]
	ds_read_b128 v[178:181], v149 offset:32768
	ds_read_b128 v[182:185], v149 offset:33792
	ds_read_b128 v[186:189], v149 offset:34816
	ds_read_b128 v[190:193], v149 offset:35840
	ds_read_b128 v[202:205], v149 offset:36864
	ds_read_b128 v[206:209], v149 offset:37888
	ds_read_b128 v[210:213], v149 offset:38912
	ds_read_b128 v[214:217], v149 offset:39936
	global_load_lds_dwordx4 v[222:223], off
	v_lshl_add_u64 v[222:223], s[40:41], 0, v[132:133]
	s_mov_b32 m0, s47
	s_nop 0
	global_load_lds_dwordx4 v[222:223], off
	s_waitcnt vmcnt(8)
	s_waitcnt lgkmcnt(0)
	v_mfma_f32_16x16x32_bf16 v[128:131], v[140:143], v[178:181], v[128:131]
	v_mfma_f32_16x16x32_bf16 v[124:127], v[154:157], v[178:181], v[124:127]
	v_mfma_f32_16x16x32_bf16 v[112:115], v[140:143], v[186:189], v[112:115]
	v_mfma_f32_16x16x32_bf16 v[108:111], v[154:157], v[186:189], v[108:111]
	s_barrier
	s_setprio 1
	v_mfma_f32_16x16x32_bf16 v[96:99], v[140:143], v[202:205], v[96:99]
	v_mfma_f32_16x16x32_bf16 v[92:95], v[154:157], v[202:205], v[92:95]
	v_mfma_f32_16x16x32_bf16 v[80:83], v[140:143], v[210:213], v[80:83]
	v_mfma_f32_16x16x32_bf16 v[76:79], v[154:157], v[210:213], v[76:79]
	v_mfma_f32_16x16x32_bf16 v[128:131], v[150:153], v[182:185], v[128:131]
	v_mfma_f32_16x16x32_bf16 v[124:127], v[158:161], v[182:185], v[124:127]
	v_mfma_f32_16x16x32_bf16 v[112:115], v[150:153], v[190:193], v[112:115]
	v_mfma_f32_16x16x32_bf16 v[108:111], v[158:161], v[190:193], v[108:111]
	v_mfma_f32_16x16x32_bf16 v[96:99], v[150:153], v[206:209], v[96:99]
	v_mfma_f32_16x16x32_bf16 v[92:95], v[158:161], v[206:209], v[92:95]
	v_mfma_f32_16x16x32_bf16 v[80:83], v[150:153], v[214:217], v[80:83]
	v_mfma_f32_16x16x32_bf16 v[76:79], v[158:161], v[214:217], v[76:79]
	s_setprio 0
	s_setprio 1
	v_mfma_f32_16x16x32_bf16 v[120:123], v[162:165], v[178:181], v[120:123]
	v_mfma_f32_16x16x32_bf16 v[116:119], v[170:173], v[178:181], v[116:119]
	v_mfma_f32_16x16x32_bf16 v[104:107], v[162:165], v[186:189], v[104:107]
	v_mfma_f32_16x16x32_bf16 v[100:103], v[170:173], v[186:189], v[100:103]
	v_mfma_f32_16x16x32_bf16 v[88:91], v[162:165], v[202:205], v[88:91]
	v_mfma_f32_16x16x32_bf16 v[84:87], v[170:173], v[202:205], v[84:87]
	v_mfma_f32_16x16x32_bf16 v[72:75], v[162:165], v[210:213], v[72:75]
	v_mfma_f32_16x16x32_bf16 v[68:71], v[170:173], v[210:213], v[68:71]
	v_mfma_f32_16x16x32_bf16 v[120:123], v[166:169], v[182:185], v[120:123]
	v_mfma_f32_16x16x32_bf16 v[116:119], v[174:177], v[182:185], v[116:119]
	v_mfma_f32_16x16x32_bf16 v[104:107], v[166:169], v[190:193], v[104:107]
	v_mfma_f32_16x16x32_bf16 v[100:103], v[174:177], v[190:193], v[100:103]
	v_mfma_f32_16x16x32_bf16 v[88:91], v[166:169], v[206:209], v[88:91]
	v_mfma_f32_16x16x32_bf16 v[84:87], v[174:177], v[206:209], v[84:87]
	v_mfma_f32_16x16x32_bf16 v[72:75], v[166:169], v[214:217], v[72:75]
	v_mfma_f32_16x16x32_bf16 v[68:71], v[174:177], v[214:217], v[68:71]
	s_setprio 0
	s_barrier
; #define PG8_STAGE(bufoff, gbase, voff) do { _Pragma("unroll") for (int _i = 0; _i < 2; ++_i) \
;         __builtin_amdgcn_global_load_lds((const unsigned*)((const char*)(gbase) + (voff)[_i]), (PG8_LAS unsigned*)(lds + (bufoff) + ldsw + _i * 8192), 16, 0, 0); } while (0)
; #define PG8_LDA(dst, b, h) do { _Pragma("unroll") for (int m = 0; m < 4; ++m) _Pragma("unroll") for (int k = 0; k < 2; ++k) dst[m][k] = *(const PG8_LAS bf16x8*)(lds + PG8_SA(b, h) + aoff + m * 2048 + k * 1024); } while (0)
; #define PG8_WAIT_V(n) asm volatile("s_waitcnt vmcnt(" #n ")" ::: "memory")
; template <class Epi, class Sched, bool ALIGN_EPI = false, bool SP2 = false>
; __device__ __forceinline__ void gemm_phase(PG8_LAS unsigned char* lds, const Gemm g, const Sched& S, const Epi& E) {
;     ...
;             PG8_WAIT_V(8); PG8_WAIT_L(0); PG8_BAR; PG8_MMA(0, 0, At, B0); PG8_MMA(0, 1, At, B1); PG8_BAR; PG8_SCHED;
;             PG8_LDA(At, 1, 1); PG8_STAGE(PG8_SB(1, 0), b3, voffB); PG8_STAGE(PG8_SB(1, 1), b3 + hstep, voffB); PG8_STAGE(PG8_SA(1, 0), a3, voffA);
;             PG8_WAIT_V(8); PG8_WAIT_L(0); PG8_BAR; PG8_MMA(1, 0, At, B0); PG8_MMA(1, 1, At, B1); PG8_BAR; PG8_SCHED;
; __device__ __forceinline__ float rstd_of(const float* ssq, int row) {
;     const f32x4* q = (const f32x4*)(ssq + (size_t)row * 16); const f32x4 a = q[0], b = q[1], c = q[2], d = q[3];
;     const float t = (((a.x + a.y) + (a.z + a.w)) + ((b.x + b.y) + (b.z + b.w))) + (((c.x + c.y) + (c.z + c.w)) + ((d.x + d.y) + (d.z + d.w)));
;     return 1.0f / sqrtf(t * (1.0f / DM) + 1e-6f); }
;     __device__ __forceinline__ void operator()(const pg8::f32x4 (&acc)[2][2][4][2], const pg8::Unit& u, int wr, int wc, int fr, int fq) const {
;         const int row0 = u.pm * 256 + wr * 64 + fr, col0 = u.pn * 128 + wc * 32 + 8 * fq;
; #pragma unroll
;         for (int ai = 0; ai < 2; ++ai)
; #pragma unroll
;             for (int m = 0; m < 4; ++m) {
;                 const int row = row0 + ai * 128 + m * 16; const float rs = rstd_of(ssq, row);
;                 bf16_t* dst = O + (size_t)row * DFF + col0;
;                 float v[8];
; #pragma unroll
;                 for (int n = 0; n < 2; ++n)
; #pragma unroll
;                     for (int j = 0; j < 4; ++j) { const float g = acc[ai][0][m][n][j] * rs, uu = acc[ai][1][m][n][j] * rs; v[n * 4 + j] = g * fast_rcp(1.0f + fast_exp2(-g * LOG2E)) * uu; }
	s_add_i32 s40, s58, s43
	v_lshl_add_u64 v[144:145], v[144:145], 0, s[36:37]
	s_mov_b32 m0, s40
	ds_read_b128 v[178:181], v149 offset:49152
	ds_read_b128 v[182:185], v149 offset:50176
	ds_read_b128 v[186:189], v149 offset:51200
	ds_read_b128 v[190:193], v149 offset:52224
	ds_read_b128 v[202:205], v149 offset:53248
	ds_read_b128 v[206:209], v149 offset:54272
	ds_read_b128 v[210:213], v149 offset:55296
	ds_read_b128 v[214:217], v149 offset:56320
	global_load_lds_dwordx4 v[144:145], off
	s_add_i32 m0, s40, 0x2000
	s_add_u32 s22, s22, 0x40080
	v_lshl_add_u64 v[144:145], v[194:195], 0, s[36:37]
	s_addc_u32 s23, s23, 0
	s_add_i32 s40, s59, s43
	global_load_lds_dwordx4 v[144:145], off
	v_lshl_add_u64 v[144:145], s[22:23], 0, v[196:197]
	s_mov_b32 m0, s40
	s_nop 0
	global_load_lds_dwordx4 v[144:145], off
	v_lshl_add_u64 v[144:145], s[22:23], 0, v[32:33]
	s_add_i32 m0, s40, 0x2000
	s_nop 0
	global_load_lds_dwordx4 v[144:145], off
	v_lshl_add_u64 v[144:145], v[218:219], 0, s[36:37]
	s_mov_b32 m0, s49
	s_nop 0
	global_load_lds_dwordx4 v[144:145], off
	v_lshl_add_u64 v[144:145], v[220:221], 0, s[36:37]
	s_mov_b32 m0, s50
	s_nop 0
	global_load_lds_dwordx4 v[144:145], off
	s_waitcnt vmcnt(8)
	s_waitcnt lgkmcnt(0)
	v_mfma_f32_16x16x32_bf16 v[64:67], v[140:143], v[178:181], v[64:67]
	v_mfma_f32_16x16x32_bf16 v[60:63], v[154:157], v[178:181], v[60:63]
	v_mfma_f32_16x16x32_bf16 v[48:51], v[140:143], v[186:189], v[48:51]
	v_mfma_f32_16x16x32_bf16 v[44:47], v[154:157], v[186:189], v[44:47]
	s_barrier
	s_setprio 1
	v_mfma_f32_16x16x32_bf16 v[28:31], v[140:143], v[202:205], v[28:31]
	v_mfma_f32_16x16x32_bf16 v[24:27], v[154:157], v[202:205], v[24:27]
	v_mfma_f32_16x16x32_bf16 v[12:15], v[140:143], v[210:213], v[12:15]
	v_mfma_f32_16x16x32_bf16 v[8:11], v[154:157], v[210:213], v[8:11]
	v_mfma_f32_16x16x32_bf16 v[64:67], v[150:153], v[182:185], v[64:67]
	v_mfma_f32_16x16x32_bf16 v[60:63], v[158:161], v[182:185], v[60:63]
	v_mfma_f32_16x16x32_bf16 v[48:51], v[150:153], v[190:193], v[48:51]
	v_mfma_f32_16x16x32_bf16 v[44:47], v[158:161], v[190:193], v[44:47]
	v_mfma_f32_16x16x32_bf16 v[28:31], v[150:153], v[206:209], v[28:31]
	v_mfma_f32_16x16x32_bf16 v[24:27], v[158:161], v[206:209], v[24:27]
	v_mfma_f32_16x16x32_bf16 v[12:15], v[150:153], v[214:217], v[12:15]
	v_mfma_f32_16x16x32_bf16 v[8:11], v[158:161], v[214:217], v[8:11]
	s_setprio 0
	s_setprio 1
	v_mfma_f32_16x16x32_bf16 v[56:59], v[162:165], v[178:181], v[56:59]
	v_mfma_f32_16x16x32_bf16 v[52:55], v[170:173], v[178:181], v[52:55]
	v_mfma_f32_16x16x32_bf16 v[40:43], v[162:165], v[186:189], v[40:43]
	v_mfma_f32_16x16x32_bf16 v[36:39], v[170:173], v[186:189], v[36:39]
	v_mfma_f32_16x16x32_bf16 v[20:23], v[162:165], v[202:205], v[20:23]
	v_mfma_f32_16x16x32_bf16 v[16:19], v[170:173], v[202:205], v[16:19]
	v_mfma_f32_16x16x32_bf16 v[4:7], v[162:165], v[210:213], v[4:7]
	v_mfma_f32_16x16x32_bf16 v[0:3], v[170:173], v[210:213], v[0:3]
	v_mfma_f32_16x16x32_bf16 v[56:59], v[166:169], v[182:185], v[56:59]
	v_mfma_f32_16x16x32_bf16 v[52:55], v[174:177], v[182:185], v[52:55]
	v_mfma_f32_16x16x32_bf16 v[40:43], v[166:169], v[190:193], v[40:43]
	v_mfma_f32_16x16x32_bf16 v[36:39], v[174:177], v[190:193], v[36:39]
	v_mfma_f32_16x16x32_bf16 v[20:23], v[166:169], v[206:209], v[20:23]
	v_mfma_f32_16x16x32_bf16 v[16:19], v[174:177], v[206:209], v[16:19]
	v_mfma_f32_16x16x32_bf16 v[4:7], v[166:169], v[214:217], v[4:7]
	v_mfma_f32_16x16x32_bf16 v[0:3], v[174:177], v[214:217], v[0:3]
	s_setprio 0
	s_barrier
	s_add_i32 s57, s57, 2
	s_add_u32 s0, s0, 0x100
	s_addc_u32 s1, s1, 0
	s_add_u32 s55, s55, 0x100
	s_addc_u32 s56, s56, 0
	s_cmp_gt_u32 s57, 13
	s_cbranch_scc0 .LBB0_623
	s_and_b64 vcc, exec, s[12:13]
	s_cbranch_vccz .LBB0_626
	s_barrier
.LBB0_626:
	v_lshl_add_u32 v142, s52, 8, v35
	v_mbcnt_lo_u32_b32 v206, -1, 0
	v_mbcnt_hi_u32_b32 v206, -1, v206
	v_lshrrev_b32_e32 v207, 4, v206
	v_and_b32_e32 v208, 1, v207
	v_lshrrev_b32_e32 v207, 1, v207
	v_lshlrev_b32_e32 v208, 5, v208
	v_lshl_add_u32 v208, v207, 7, v208
	v_add_u32_e32 v208, v208, v142
	v_mov_b32_e32 v209, 0
	v_lshlrev_b64 v[208:209], 6, v[208:209]
	v_lshl_add_u64 v[208:209], s[10:11], 0, v[208:209]
	global_load_dwordx4 v[166:169], v[208:209], off
	global_load_dwordx4 v[170:173], v[208:209], off offset:16
	global_load_dwordx4 v[174:177], v[208:209], off offset:32
	global_load_dwordx4 v[178:181], v[208:209], off offset:48
	global_load_dwordx4 v[182:185], v[208:209], off offset:1024
	global_load_dwordx4 v[186:189], v[208:209], off offset:1040
	global_load_dwordx4 v[190:193], v[208:209], off offset:1056
	global_load_dwordx4 v[202:205], v[208:209], off offset:1072
	v_and_b32_e32 v210, 15, v206
	v_lshlrev_b32_e32 v210, 2, v210
	v_add_u32_e32 v211, 64, v210
	v_add_u32_e32 v212, 0x80, v210
	v_add_u32_e32 v213, 0xc0, v210
	s_waitcnt vmcnt(4)
	v_add_f32_e32 v166, v166, v167
	v_add_f32_e32 v168, v168, v169
	v_add_f32_e32 v166, v166, v168
	v_add_f32_e32 v170, v170, v171
	v_add_f32_e32 v172, v172, v173
	v_add_f32_e32 v170, v170, v172
	v_add_f32_e32 v174, v174, v175
	v_add_f32_e32 v176, v176, v177
	v_add_f32_e32 v174, v174, v176
	v_add_f32_e32 v178, v178, v179
	v_add_f32_e32 v180, v180, v181
	v_add_f32_e32 v178, v178, v180
	v_add_f32_e32 v166, v166, v170
	v_add_f32_e32 v174, v174, v178
	v_add_f32_e32 v166, v166, v174
	v_fmamk_f32 v166, v166, 0x3a800000, v229
	v_cmp_gt_f32_e32 vcc, 0xf800000, v166
	v_mul_f32_e32 v171, 0x4f800000, v166
	s_nop 0
	v_cndmask_b32_e32 v166, v166, v171, vcc
	v_sqrt_f32_e32 v171, v166
	s_nop 0
	v_add_u32_e32 v172, -1, v171
	v_fma_f32 v173, -v172, v171, v166
	v_cmp_ge_f32_e64 s[100:101], 0, v173
	v_add_u32_e32 v173, 1, v171
	s_nop 0
	v_cndmask_b32_e64 v172, v171, v172, s[100:101]
	v_fma_f32 v171, -v173, v171, v166
	v_cmp_lt_f32_e64 s[100:101], 0, v171
	s_nop 1
	v_cndmask_b32_e64 v171, v172, v173, s[100:101]
	v_mul_f32_e32 v172, 0x37800000, v171
	v_cndmask_b32_e32 v171, v171, v172, vcc
	v_cmp_class_f32_e32 vcc, v166, v230
	s_nop 1
	v_cndmask_b32_e32 v166, v171, v166, vcc
	v_div_scale_f32 v171, s[100:101], v166, v166, 1.0
	v_rcp_f32_e32 v172, v171
	s_nop 0
	v_fma_f32 v173, -v171, v172, 1.0
	v_fmac_f32_e32 v172, v173, v172
	v_div_scale_f32 v173, vcc, 1.0, v166, 1.0
	v_mul_f32_e32 v175, v173, v172
	v_fma_f32 v176, -v171, v175, v173
	v_fmac_f32_e32 v175, v176, v172
	v_fma_f32 v171, -v171, v175, v173
	v_div_fmas_f32 v171, v171, v172, v175
	v_div_fixup_f32 v214, v171, v166, 1.0
	s_waitcnt vmcnt(0)
; __device__ __forceinline__ unsigned pk2(float lo, float hi) { return pg8::cvt_pk_bf16(lo, hi); }
; __device__ __forceinline__ float fast_exp2(float x) { return __builtin_amdgcn_exp2f(x); }
; __device__ __forceinline__ float fast_rcp(float x) { return __builtin_amdgcn_rcpf(x); }
; __device__ __forceinline__ float rstd_of(const float* ssq, int row) {
;     const f32x4* q = (const f32x4*)(ssq + (size_t)row * 16); const f32x4 a = q[0], b = q[1], c = q[2], d = q[3];
;     const float t = (((a.x + a.y) + (a.z + a.w)) + ((b.x + b.y) + (b.z + b.w))) + (((c.x + c.y) + (c.z + c.w)) + ((d.x + d.y) + (d.z + d.w)));
;     return 1.0f / sqrtf(t * (1.0f / DM) + 1e-6f); }
;     __device__ __forceinline__ void operator()(const pg8::f32x4 (&acc)[2][2][4][2], const pg8::Unit& u, int wr, int wc, int fr, int fq) const {
;         const int row0 = u.pm * 256 + wr * 64 + fr, col0 = u.pn * 128 + wc * 32 + 8 * fq;
; #pragma unroll
;         for (int ai = 0; ai < 2; ++ai)
; #pragma unroll
;             for (int m = 0; m < 4; ++m) {
;                 const int row = row0 + ai * 128 + m * 16; const float rs = rstd_of(ssq, row);
;                 bf16_t* dst = O + (size_t)row * DFF + col0;
;                 float v[8];
; #pragma unroll
;                 for (int n = 0; n < 2; ++n)
; #pragma unroll
;                     for (int j = 0; j < 4; ++j) { const float g = acc[ai][0][m][n][j] * rs, uu = acc[ai][1][m][n][j] * rs; v[n * 4 + j] = g * fast_rcp(1.0f + fast_exp2(-g * LOG2E)) * uu; }
;                 u32x4 w; w.x = pk2(v[0], v[1]); w.y = pk2(v[2], v[3]); w.z = pk2(v[4], v[5]); w.w = pk2(v[6], v[7]);
;                 *(u32x4*)dst = w;
	v_add_f32_e32 v182, v182, v183
	v_add_f32_e32 v184, v184, v185
	v_add_f32_e32 v182, v182, v184
	v_add_f32_e32 v186, v186, v187
	v_add_f32_e32 v188, v188, v189
	v_add_f32_e32 v186, v186, v188
	v_add_f32_e32 v190, v190, v191
	v_add_f32_e32 v192, v192, v193
	v_add_f32_e32 v190, v190, v192
	v_add_f32_e32 v202, v202, v203
	v_add_f32_e32 v204, v204, v205
	v_add_f32_e32 v202, v202, v204
	v_add_f32_e32 v182, v182, v186
	v_add_f32_e32 v190, v190, v202
	v_add_f32_e32 v182, v182, v190
	v_fmamk_f32 v182, v182, 0x3a800000, v229
	v_cmp_gt_f32_e32 vcc, 0xf800000, v182
	v_mul_f32_e32 v187, 0x4f800000, v182
	s_nop 0
	v_cndmask_b32_e32 v182, v182, v187, vcc
	v_sqrt_f32_e32 v187, v182
	s_nop 0
	v_add_u32_e32 v188, -1, v187
	v_fma_f32 v189, -v188, v187, v182
	v_cmp_ge_f32_e64 s[100:101], 0, v189
	v_add_u32_e32 v189, 1, v187
	s_nop 0
	v_cndmask_b32_e64 v188, v187, v188, s[100:101]
	v_fma_f32 v187, -v189, v187, v182
	v_cmp_lt_f32_e64 s[100:101], 0, v187
	s_nop 1
	v_cndmask_b32_e64 v187, v188, v189, s[100:101]
	v_mul_f32_e32 v188, 0x37800000, v187
	v_cndmask_b32_e32 v187, v187, v188, vcc
	v_cmp_class_f32_e32 vcc, v182, v230
	s_nop 1
	v_cndmask_b32_e32 v182, v187, v182, vcc
	v_div_scale_f32 v187, s[100:101], v182, v182, 1.0
	v_rcp_f32_e32 v188, v187
	s_nop 0
	v_fma_f32 v189, -v187, v188, 1.0
	v_fmac_f32_e32 v188, v189, v188
	v_div_scale_f32 v189, vcc, 1.0, v182, 1.0
	v_mul_f32_e32 v191, v189, v188
	v_fma_f32 v192, -v187, v191, v189
	v_fmac_f32_e32 v191, v192, v188
	v_fma_f32 v187, -v187, v191, v189
	v_div_fmas_f32 v187, v187, v188, v191
	v_div_fixup_f32 v215, v187, v182, 1.0
	ds_bpermute_b32 v218, v210, v214
	ds_bpermute_b32 v219, v210, v215
	ds_bpermute_b32 v220, v211, v214
	ds_bpermute_b32 v221, v211, v215
	ds_bpermute_b32 v222, v212, v214
	ds_bpermute_b32 v223, v212, v215
	ds_bpermute_b32 v194, v213, v214
	ds_bpermute_b32 v195, v213, v215
	s_waitcnt lgkmcnt(0)
	s_mov_b32 s15, 0xf800000
	v_lshl_or_b32 v144, s51, 7, v148
	v_ashrrev_i32_e32 v145, 31, v144
	s_movk_i32 s17, 0x1600
	s_nop 1
	v_readlane_b32 s0, v252, 4
	v_readlane_b32 s1, v252, 5
	v_mov_b32_e32 v146, v218
	v_pk_mul_f32 v[128:129], v[128:129], v[146:147] op_sel_hi:[1,0]
	v_pk_mul_f32 v[120:121], v[120:121], v[146:147] op_sel_hi:[1,0]
	v_mul_f32_e32 v143, 0xbfb8aa3b, v128
	v_exp_f32_e32 v143, v143
	v_pk_mul_f32 v[122:123], v[122:123], v[146:147] op_sel_hi:[1,0]
	v_pk_mul_f32 v[124:125], v[124:125], v[146:147] op_sel_hi:[1,0]
	v_pk_mul_f32 v[116:117], v[116:117], v[146:147] op_sel_hi:[1,0]
	v_add_f32_e32 v143, 1.0, v143
	v_rcp_f32_e32 v152, v143
	v_mul_f32_e32 v143, 0xbfb8aa3b, v129
	v_exp_f32_e32 v143, v143
	v_pk_mul_f32 v[118:119], v[118:119], v[146:147] op_sel_hi:[1,0]
	v_mov_b64_e32 v[140:141], s[0:1]
	v_mad_i64_i32 v[150:151], s[0:1], v142, s17, v[140:141]
	v_add_f32_e32 v143, 1.0, v143
	v_rcp_f32_e32 v153, v143
	s_nop 0
	v_pk_mul_f32 v[128:129], v[128:129], v[152:153]
	s_nop 0
	v_pk_mul_f32 v[120:121], v[120:121], v[128:129]
	v_pk_mul_f32 v[128:129], v[130:131], v[146:147] op_sel_hi:[1,0]
	s_nop 0
	v_mul_f32_e32 v130, 0xbfb8aa3b, v128
	v_mul_f32_e32 v131, 0xbfb8aa3b, v129
	v_exp_f32_e32 v130, v130
	v_exp_f32_e32 v131, v131
	v_add_f32_e32 v130, 1.0, v130
	v_add_f32_e32 v131, 1.0, v131
	v_rcp_f32_e32 v130, v130
	v_rcp_f32_e32 v131, v131
	s_nop 0
	v_pk_mul_f32 v[128:129], v[128:129], v[130:131]
	s_nop 0
	v_pk_mul_f32 v[122:123], v[122:123], v[128:129]
	v_mul_f32_e32 v128, 0xbfb8aa3b, v124
	v_mul_f32_e32 v129, 0xbfb8aa3b, v125
	v_exp_f32_e32 v128, v128
	v_exp_f32_e32 v129, v129
	v_add_f32_e32 v128, 1.0, v128
	v_add_f32_e32 v129, 1.0, v129
	v_rcp_f32_e32 v128, v128
	v_rcp_f32_e32 v129, v129
	s_nop 0
	v_pk_mul_f32 v[124:125], v[124:125], v[128:129]
	s_nop 0
	v_pk_mul_f32 v[128:129], v[116:117], v[124:125]
	v_pk_mul_f32 v[116:117], v[126:127], v[146:147] op_sel_hi:[1,0]
	s_nop 0
	v_mul_f32_e32 v124, 0xbfb8aa3b, v116
	v_mul_f32_e32 v125, 0xbfb8aa3b, v117
	v_exp_f32_e32 v124, v124
	v_exp_f32_e32 v125, v125
	v_add_f32_e32 v124, 1.0, v124
	v_add_f32_e32 v125, 1.0, v125
	v_rcp_f32_e32 v124, v124
	v_rcp_f32_e32 v125, v125
	s_nop 0
	v_pk_mul_f32 v[116:117], v[116:117], v[124:125]
	s_nop 0
	v_pk_mul_f32 v[126:127], v[118:119], v[116:117]
	v_lshlrev_b64 v[124:125], 1, v[144:145]
	v_cvt_pk_bf16_f32 v119, v126, v127
	v_or_b32_e32 v126, 16, v142
	v_lshl_add_u64 v[130:131], v[150:151], 0, v[124:125]
	v_cvt_pk_bf16_f32 v116, v120, v121
	v_cvt_pk_bf16_f32 v117, v122, v123
	v_cvt_pk_bf16_f32 v118, v128, v129
	global_store_dwordx4 v[130:131], v[116:119], off
	s_nop 1
	v_mov_b32_e32 v116, v219
	v_pk_mul_f32 v[112:113], v[112:113], v[116:117] op_sel_hi:[1,0]
	v_mad_i64_i32 v[118:119], s[0:1], v126, s17, v[140:141]
	v_mul_f32_e32 v117, 0xbfb8aa3b, v112
	v_exp_f32_e32 v117, v117
	s_nop 0
	v_add_f32_e32 v117, 1.0, v117
	v_rcp_f32_e32 v120, v117
	v_pk_mul_f32 v[104:105], v[104:105], v[116:117] op_sel_hi:[1,0]
	v_mul_f32_e32 v117, 0xbfb8aa3b, v113
	v_exp_f32_e32 v117, v117
	s_nop 0
	v_add_f32_e32 v117, 1.0, v117
	v_rcp_f32_e32 v121, v117
	v_pk_mul_f32 v[106:107], v[106:107], v[116:117] op_sel_hi:[1,0]
	v_pk_mul_f32 v[108:109], v[108:109], v[116:117] op_sel_hi:[1,0]
	v_pk_mul_f32 v[100:101], v[100:101], v[116:117] op_sel_hi:[1,0]
	v_pk_mul_f32 v[112:113], v[112:113], v[120:121]
	v_pk_mul_f32 v[102:103], v[102:103], v[116:117] op_sel_hi:[1,0]
	v_pk_mul_f32 v[104:105], v[104:105], v[112:113]
	v_pk_mul_f32 v[112:113], v[114:115], v[116:117] op_sel_hi:[1,0]
	s_nop 0
	v_mul_f32_e32 v114, 0xbfb8aa3b, v112
	v_mul_f32_e32 v115, 0xbfb8aa3b, v113
	v_exp_f32_e32 v114, v114
	v_exp_f32_e32 v115, v115
	v_add_f32_e32 v114, 1.0, v114
	v_add_f32_e32 v115, 1.0, v115
	v_rcp_f32_e32 v114, v114
	v_rcp_f32_e32 v115, v115
	s_nop 0
; __device__ __forceinline__ unsigned pk2(float lo, float hi) { return pg8::cvt_pk_bf16(lo, hi); }
; __device__ __forceinline__ float fast_exp2(float x) { return __builtin_amdgcn_exp2f(x); }
; __device__ __forceinline__ float fast_rcp(float x) { return __builtin_amdgcn_rcpf(x); }
;     __device__ __forceinline__ void operator()(const pg8::f32x4 (&acc)[2][2][4][2], const pg8::Unit& u, int wr, int wc, int fr, int fq) const {
;         const int row0 = u.pm * 256 + wr * 64 + fr, col0 = u.pn * 128 + wc * 32 + 8 * fq;
; #pragma unroll
;         for (int ai = 0; ai < 2; ++ai)
; #pragma unroll
;             for (int m = 0; m < 4; ++m) {
;                 const int row = row0 + ai * 128 + m * 16; const float rs = rstd_of(ssq, row);
;                 bf16_t* dst = O + (size_t)row * DFF + col0;
;                 float v[8];
; #pragma unroll
;                 for (int n = 0; n < 2; ++n)
; #pragma unroll
;                     for (int j = 0; j < 4; ++j) { const float g = acc[ai][0][m][n][j] * rs, uu = acc[ai][1][m][n][j] * rs; v[n * 4 + j] = g * fast_rcp(1.0f + fast_exp2(-g * LOG2E)) * uu; }
;                 u32x4 w; w.x = pk2(v[0], v[1]); w.y = pk2(v[2], v[3]); w.z = pk2(v[4], v[5]); w.w = pk2(v[6], v[7]);
;                 *(u32x4*)dst = w;
;             }
	v_pk_mul_f32 v[112:113], v[112:113], v[114:115]
	s_nop 0
	v_pk_mul_f32 v[106:107], v[106:107], v[112:113]
	v_mul_f32_e32 v112, 0xbfb8aa3b, v108
	v_mul_f32_e32 v113, 0xbfb8aa3b, v109
	v_exp_f32_e32 v112, v112
	v_exp_f32_e32 v113, v113
	v_add_f32_e32 v112, 1.0, v112
	v_add_f32_e32 v113, 1.0, v113
	v_rcp_f32_e32 v112, v112
	v_rcp_f32_e32 v113, v113
	s_nop 0
	v_pk_mul_f32 v[108:109], v[108:109], v[112:113]
	s_nop 0
	v_pk_mul_f32 v[108:109], v[100:101], v[108:109]
	v_pk_mul_f32 v[100:101], v[110:111], v[116:117] op_sel_hi:[1,0]
	v_lshl_add_u64 v[112:113], v[118:119], 0, v[124:125]
	v_mul_f32_e32 v110, 0xbfb8aa3b, v100
	v_mul_f32_e32 v111, 0xbfb8aa3b, v101
	v_exp_f32_e32 v110, v110
	v_exp_f32_e32 v111, v111
	v_add_f32_e32 v110, 1.0, v110
	v_add_f32_e32 v111, 1.0, v111
	v_rcp_f32_e32 v110, v110
	v_rcp_f32_e32 v111, v111
	s_nop 0
	v_pk_mul_f32 v[100:101], v[100:101], v[110:111]
	s_nop 0
	v_pk_mul_f32 v[110:111], v[102:103], v[100:101]
	v_cvt_pk_bf16_f32 v102, v108, v109
	v_or_b32_e32 v108, 32, v142
	v_cvt_pk_bf16_f32 v100, v104, v105
	v_cvt_pk_bf16_f32 v101, v106, v107
	v_cvt_pk_bf16_f32 v103, v110, v111
	global_store_dwordx4 v[112:113], v[100:103], off
	s_nop 1
	v_mov_b32_e32 v100, v220
	v_pk_mul_f32 v[96:97], v[96:97], v[100:101] op_sel_hi:[1,0]
	v_mad_i64_i32 v[102:103], s[0:1], v108, s17, v[140:141]
	v_mul_f32_e32 v101, 0xbfb8aa3b, v96
	v_exp_f32_e32 v101, v101
	s_nop 0
	v_add_f32_e32 v101, 1.0, v101
	v_rcp_f32_e32 v104, v101
	v_pk_mul_f32 v[88:89], v[88:89], v[100:101] op_sel_hi:[1,0]
	v_mul_f32_e32 v101, 0xbfb8aa3b, v97
	v_exp_f32_e32 v101, v101
	s_nop 0
	v_add_f32_e32 v101, 1.0, v101
	v_rcp_f32_e32 v105, v101
	v_pk_mul_f32 v[90:91], v[90:91], v[100:101] op_sel_hi:[1,0]
	v_pk_mul_f32 v[92:93], v[92:93], v[100:101] op_sel_hi:[1,0]
	v_pk_mul_f32 v[84:85], v[84:85], v[100:101] op_sel_hi:[1,0]
	v_pk_mul_f32 v[96:97], v[96:97], v[104:105]
	v_pk_mul_f32 v[86:87], v[86:87], v[100:101] op_sel_hi:[1,0]
	v_pk_mul_f32 v[88:89], v[88:89], v[96:97]
	v_pk_mul_f32 v[96:97], v[98:99], v[100:101] op_sel_hi:[1,0]
	s_nop 0
	v_mul_f32_e32 v98, 0xbfb8aa3b, v96
	v_mul_f32_e32 v99, 0xbfb8aa3b, v97
	v_exp_f32_e32 v98, v98
	v_exp_f32_e32 v99, v99
	v_add_f32_e32 v98, 1.0, v98
	v_add_f32_e32 v99, 1.0, v99
	v_rcp_f32_e32 v98, v98
	v_rcp_f32_e32 v99, v99
	s_nop 0
	v_pk_mul_f32 v[96:97], v[96:97], v[98:99]
	s_nop 0
	v_pk_mul_f32 v[90:91], v[90:91], v[96:97]
	v_mul_f32_e32 v96, 0xbfb8aa3b, v92
	v_mul_f32_e32 v97, 0xbfb8aa3b, v93
	v_exp_f32_e32 v96, v96
	v_exp_f32_e32 v97, v97
	v_add_f32_e32 v96, 1.0, v96
	v_add_f32_e32 v97, 1.0, v97
	v_rcp_f32_e32 v96, v96
	v_rcp_f32_e32 v97, v97
	s_nop 0
	v_pk_mul_f32 v[92:93], v[92:93], v[96:97]
	s_nop 0
	v_pk_mul_f32 v[92:93], v[84:85], v[92:93]
	v_pk_mul_f32 v[84:85], v[94:95], v[100:101] op_sel_hi:[1,0]
	v_lshl_add_u64 v[96:97], v[102:103], 0, v[124:125]
	v_mul_f32_e32 v94, 0xbfb8aa3b, v84
	v_mul_f32_e32 v95, 0xbfb8aa3b, v85
	v_exp_f32_e32 v94, v94
	v_exp_f32_e32 v95, v95
	v_add_f32_e32 v94, 1.0, v94
	v_add_f32_e32 v95, 1.0, v95
	v_rcp_f32_e32 v94, v94
	v_rcp_f32_e32 v95, v95
	s_nop 0
	v_pk_mul_f32 v[84:85], v[84:85], v[94:95]
	s_nop 0
	v_pk_mul_f32 v[94:95], v[86:87], v[84:85]
	v_cvt_pk_bf16_f32 v86, v92, v93
	v_or_b32_e32 v92, 48, v142
	v_cvt_pk_bf16_f32 v84, v88, v89
	v_cvt_pk_bf16_f32 v85, v90, v91
	v_cvt_pk_bf16_f32 v87, v94, v95
	global_store_dwordx4 v[96:97], v[84:87], off
	s_nop 1
	v_mov_b32_e32 v84, v221
	v_pk_mul_f32 v[80:81], v[80:81], v[84:85] op_sel_hi:[1,0]
	v_mad_i64_i32 v[86:87], s[0:1], v92, s17, v[140:141]
	v_mul_f32_e32 v85, 0xbfb8aa3b, v80
	v_exp_f32_e32 v85, v85
	s_nop 0
	v_add_f32_e32 v85, 1.0, v85
	v_rcp_f32_e32 v88, v85
	v_pk_mul_f32 v[72:73], v[72:73], v[84:85] op_sel_hi:[1,0]
	v_mul_f32_e32 v85, 0xbfb8aa3b, v81
	v_exp_f32_e32 v85, v85
	s_nop 0
	v_add_f32_e32 v85, 1.0, v85
	v_rcp_f32_e32 v89, v85
	v_pk_mul_f32 v[74:75], v[74:75], v[84:85] op_sel_hi:[1,0]
	v_pk_mul_f32 v[76:77], v[76:77], v[84:85] op_sel_hi:[1,0]
	v_pk_mul_f32 v[68:69], v[68:69], v[84:85] op_sel_hi:[1,0]
	v_pk_mul_f32 v[80:81], v[80:81], v[88:89]
	v_pk_mul_f32 v[70:71], v[70:71], v[84:85] op_sel_hi:[1,0]
	v_pk_mul_f32 v[72:73], v[72:73], v[80:81]
	v_pk_mul_f32 v[80:81], v[82:83], v[84:85] op_sel_hi:[1,0]
	s_nop 0
	v_mul_f32_e32 v82, 0xbfb8aa3b, v80
	v_mul_f32_e32 v83, 0xbfb8aa3b, v81
	v_exp_f32_e32 v82, v82
	v_exp_f32_e32 v83, v83
	v_add_f32_e32 v82, 1.0, v82
	v_add_f32_e32 v83, 1.0, v83
	v_rcp_f32_e32 v82, v82
	v_rcp_f32_e32 v83, v83
	s_nop 0
	v_pk_mul_f32 v[80:81], v[80:81], v[82:83]
	s_nop 0
	v_pk_mul_f32 v[74:75], v[74:75], v[80:81]
	v_mul_f32_e32 v80, 0xbfb8aa3b, v76
	v_mul_f32_e32 v81, 0xbfb8aa3b, v77
	v_exp_f32_e32 v80, v80
	v_exp_f32_e32 v81, v81
	v_add_f32_e32 v80, 1.0, v80
	v_add_f32_e32 v81, 1.0, v81
	v_rcp_f32_e32 v80, v80
	v_rcp_f32_e32 v81, v81
	s_nop 0
	v_pk_mul_f32 v[76:77], v[76:77], v[80:81]
	s_nop 0
	v_pk_mul_f32 v[76:77], v[68:69], v[76:77]
	v_pk_mul_f32 v[68:69], v[78:79], v[84:85] op_sel_hi:[1,0]
	v_lshl_add_u64 v[80:81], v[86:87], 0, v[124:125]
	v_mul_f32_e32 v78, 0xbfb8aa3b, v68
	v_mul_f32_e32 v79, 0xbfb8aa3b, v69
	v_exp_f32_e32 v78, v78
	v_exp_f32_e32 v79, v79
	v_add_f32_e32 v78, 1.0, v78
	v_add_f32_e32 v79, 1.0, v79
	v_rcp_f32_e32 v78, v78
	v_rcp_f32_e32 v79, v79
	s_nop 0
	v_pk_mul_f32 v[68:69], v[68:69], v[78:79]
	s_nop 0
	v_pk_mul_f32 v[78:79], v[70:71], v[68:69]
	v_cvt_pk_bf16_f32 v70, v76, v77
	v_add_u32_e32 v76, 0x80, v142
	v_cvt_pk_bf16_f32 v68, v72, v73
	v_cvt_pk_bf16_f32 v69, v74, v75
	v_cvt_pk_bf16_f32 v71, v78, v79
	global_store_dwordx4 v[80:81], v[68:71], off
	s_nop 1
	v_mov_b32_e32 v68, v222
	v_pk_mul_f32 v[64:65], v[64:65], v[68:69] op_sel_hi:[1,0]
	v_mad_i64_i32 v[70:71], s[0:1], v76, s17, v[140:141]
; __device__ __forceinline__ unsigned pk2(float lo, float hi) { return pg8::cvt_pk_bf16(lo, hi); }
; __device__ __forceinline__ float fast_exp2(float x) { return __builtin_amdgcn_exp2f(x); }
; __device__ __forceinline__ float fast_rcp(float x) { return __builtin_amdgcn_rcpf(x); }
;     __device__ __forceinline__ void operator()(const pg8::f32x4 (&acc)[2][2][4][2], const pg8::Unit& u, int wr, int wc, int fr, int fq) const {
;         const int row0 = u.pm * 256 + wr * 64 + fr, col0 = u.pn * 128 + wc * 32 + 8 * fq;
; #pragma unroll
;         for (int ai = 0; ai < 2; ++ai)
; #pragma unroll
;             for (int m = 0; m < 4; ++m) {
;                 const int row = row0 + ai * 128 + m * 16; const float rs = rstd_of(ssq, row);
;                 bf16_t* dst = O + (size_t)row * DFF + col0;
;                 float v[8];
; #pragma unroll
;                 for (int n = 0; n < 2; ++n)
; #pragma unroll
;                     for (int j = 0; j < 4; ++j) { const float g = acc[ai][0][m][n][j] * rs, uu = acc[ai][1][m][n][j] * rs; v[n * 4 + j] = g * fast_rcp(1.0f + fast_exp2(-g * LOG2E)) * uu; }
;                 u32x4 w; w.x = pk2(v[0], v[1]); w.y = pk2(v[2], v[3]); w.z = pk2(v[4], v[5]); w.w = pk2(v[6], v[7]);
;                 *(u32x4*)dst = w;
;             }
	v_mul_f32_e32 v69, 0xbfb8aa3b, v64
	v_exp_f32_e32 v69, v69
	s_nop 0
	v_add_f32_e32 v69, 1.0, v69
	v_rcp_f32_e32 v72, v69
	v_pk_mul_f32 v[56:57], v[56:57], v[68:69] op_sel_hi:[1,0]
	v_mul_f32_e32 v69, 0xbfb8aa3b, v65
	v_exp_f32_e32 v69, v69
	s_nop 0
	v_add_f32_e32 v69, 1.0, v69
	v_rcp_f32_e32 v73, v69
	v_pk_mul_f32 v[58:59], v[58:59], v[68:69] op_sel_hi:[1,0]
	v_pk_mul_f32 v[60:61], v[60:61], v[68:69] op_sel_hi:[1,0]
	v_pk_mul_f32 v[52:53], v[52:53], v[68:69] op_sel_hi:[1,0]
	v_pk_mul_f32 v[64:65], v[64:65], v[72:73]
	v_pk_mul_f32 v[54:55], v[54:55], v[68:69] op_sel_hi:[1,0]
	v_pk_mul_f32 v[56:57], v[56:57], v[64:65]
	v_pk_mul_f32 v[64:65], v[66:67], v[68:69] op_sel_hi:[1,0]
	s_nop 0
	v_mul_f32_e32 v66, 0xbfb8aa3b, v64
	v_mul_f32_e32 v67, 0xbfb8aa3b, v65
	v_exp_f32_e32 v66, v66
	v_exp_f32_e32 v67, v67
	v_add_f32_e32 v66, 1.0, v66
	v_add_f32_e32 v67, 1.0, v67
	v_rcp_f32_e32 v66, v66
	v_rcp_f32_e32 v67, v67
	s_nop 0
	v_pk_mul_f32 v[64:65], v[64:65], v[66:67]
	s_nop 0
	v_pk_mul_f32 v[58:59], v[58:59], v[64:65]
	v_mul_f32_e32 v64, 0xbfb8aa3b, v60
	v_mul_f32_e32 v65, 0xbfb8aa3b, v61
	v_exp_f32_e32 v64, v64
	v_exp_f32_e32 v65, v65
	v_add_f32_e32 v64, 1.0, v64
	v_add_f32_e32 v65, 1.0, v65
	v_rcp_f32_e32 v64, v64
	v_rcp_f32_e32 v65, v65
	s_nop 0
	v_pk_mul_f32 v[60:61], v[60:61], v[64:65]
	s_nop 0
	v_pk_mul_f32 v[60:61], v[52:53], v[60:61]
	v_pk_mul_f32 v[52:53], v[62:63], v[68:69] op_sel_hi:[1,0]
	v_lshl_add_u64 v[64:65], v[70:71], 0, v[124:125]
	v_mul_f32_e32 v62, 0xbfb8aa3b, v52
	v_mul_f32_e32 v63, 0xbfb8aa3b, v53
	v_exp_f32_e32 v62, v62
	v_exp_f32_e32 v63, v63
	v_add_f32_e32 v62, 1.0, v62
	v_add_f32_e32 v63, 1.0, v63
	v_rcp_f32_e32 v62, v62
	v_rcp_f32_e32 v63, v63
	s_nop 0
	v_pk_mul_f32 v[52:53], v[52:53], v[62:63]
	s_nop 0
	v_pk_mul_f32 v[62:63], v[54:55], v[52:53]
	v_cvt_pk_bf16_f32 v54, v60, v61
	v_add_u32_e32 v60, 0x90, v142
	v_cvt_pk_bf16_f32 v52, v56, v57
	v_cvt_pk_bf16_f32 v53, v58, v59
	v_cvt_pk_bf16_f32 v55, v62, v63
	global_store_dwordx4 v[64:65], v[52:55], off
	s_nop 1
	v_mov_b32_e32 v52, v223
	v_pk_mul_f32 v[48:49], v[48:49], v[52:53] op_sel_hi:[1,0]
	v_mad_i64_i32 v[54:55], s[0:1], v60, s17, v[140:141]
	v_mul_f32_e32 v53, 0xbfb8aa3b, v48
	v_exp_f32_e32 v53, v53
	s_nop 0
	v_add_f32_e32 v53, 1.0, v53
	v_rcp_f32_e32 v56, v53
	v_pk_mul_f32 v[40:41], v[40:41], v[52:53] op_sel_hi:[1,0]
	v_mul_f32_e32 v53, 0xbfb8aa3b, v49
	v_exp_f32_e32 v53, v53
	s_nop 0
	v_add_f32_e32 v53, 1.0, v53
	v_rcp_f32_e32 v57, v53
	v_pk_mul_f32 v[42:43], v[42:43], v[52:53] op_sel_hi:[1,0]
	v_pk_mul_f32 v[44:45], v[44:45], v[52:53] op_sel_hi:[1,0]
	v_pk_mul_f32 v[36:37], v[36:37], v[52:53] op_sel_hi:[1,0]
	v_pk_mul_f32 v[48:49], v[48:49], v[56:57]
	v_pk_mul_f32 v[38:39], v[38:39], v[52:53] op_sel_hi:[1,0]
	v_pk_mul_f32 v[40:41], v[40:41], v[48:49]
	v_pk_mul_f32 v[48:49], v[50:51], v[52:53] op_sel_hi:[1,0]
	s_nop 0
	v_mul_f32_e32 v50, 0xbfb8aa3b, v48
	v_mul_f32_e32 v51, 0xbfb8aa3b, v49
	v_exp_f32_e32 v50, v50
	v_exp_f32_e32 v51, v51
	v_add_f32_e32 v50, 1.0, v50
	v_add_f32_e32 v51, 1.0, v51
	v_rcp_f32_e32 v50, v50
	v_rcp_f32_e32 v51, v51
	s_nop 0
	v_pk_mul_f32 v[48:49], v[48:49], v[50:51]
	s_nop 0
	v_pk_mul_f32 v[42:43], v[42:43], v[48:49]
	v_mul_f32_e32 v48, 0xbfb8aa3b, v44
	v_mul_f32_e32 v49, 0xbfb8aa3b, v45
	v_exp_f32_e32 v48, v48
	v_exp_f32_e32 v49, v49
	v_add_f32_e32 v48, 1.0, v48
	v_add_f32_e32 v49, 1.0, v49
	v_rcp_f32_e32 v48, v48
	v_rcp_f32_e32 v49, v49
	s_nop 0
	v_pk_mul_f32 v[44:45], v[44:45], v[48:49]
	s_nop 0
	v_pk_mul_f32 v[44:45], v[36:37], v[44:45]
	v_pk_mul_f32 v[36:37], v[46:47], v[52:53] op_sel_hi:[1,0]
	v_lshl_add_u64 v[48:49], v[54:55], 0, v[124:125]
	v_mul_f32_e32 v46, 0xbfb8aa3b, v36
	v_mul_f32_e32 v47, 0xbfb8aa3b, v37
	v_exp_f32_e32 v46, v46
	v_exp_f32_e32 v47, v47
	v_add_f32_e32 v46, 1.0, v46
	v_add_f32_e32 v47, 1.0, v47
	v_rcp_f32_e32 v46, v46
	v_rcp_f32_e32 v47, v47
	s_nop 0
	v_pk_mul_f32 v[36:37], v[36:37], v[46:47]
	s_nop 0
	v_pk_mul_f32 v[46:47], v[38:39], v[36:37]
	v_cvt_pk_bf16_f32 v38, v44, v45
	v_add_u32_e32 v44, 0xa0, v142
	v_cvt_pk_bf16_f32 v36, v40, v41
	v_cvt_pk_bf16_f32 v37, v42, v43
	v_cvt_pk_bf16_f32 v39, v46, v47
	global_store_dwordx4 v[48:49], v[36:39], off
	s_nop 1
	v_mov_b32_e32 v36, v194
	v_pk_mul_f32 v[28:29], v[28:29], v[36:37] op_sel_hi:[1,0]
; __device__ __forceinline__ unsigned pk2(float lo, float hi) { return pg8::cvt_pk_bf16(lo, hi); }
; __device__ __forceinline__ float fast_exp2(float x) { return __builtin_amdgcn_exp2f(x); }
; __device__ __forceinline__ float fast_rcp(float x) { return __builtin_amdgcn_rcpf(x); }
; template <class Epi, class Sched, bool ALIGN_EPI = false, bool SP2 = false>
; __device__ __forceinline__ void gemm_phase(PG8_LAS unsigned char* lds, const Gemm g, const Sched& S, const Epi& E) {
;     ...
;         if constexpr (!Epi::AFTER_DRAIN) { E(acc, cur, wr, wc, fr, fq); S.done(cur); }
;         if (!has_next) break;
;     __device__ __forceinline__ void operator()(const pg8::f32x4 (&acc)[2][2][4][2], const pg8::Unit& u, int wr, int wc, int fr, int fq) const {
;         const int row0 = u.pm * 256 + wr * 64 + fr, col0 = u.pn * 128 + wc * 32 + 8 * fq;
; #pragma unroll
;         for (int ai = 0; ai < 2; ++ai)
; #pragma unroll
;             for (int m = 0; m < 4; ++m) {
;                 const int row = row0 + ai * 128 + m * 16; const float rs = rstd_of(ssq, row);
;                 bf16_t* dst = O + (size_t)row * DFF + col0;
;                 float v[8];
; #pragma unroll
;                 for (int n = 0; n < 2; ++n)
; #pragma unroll
;                     for (int j = 0; j < 4; ++j) { const float g = acc[ai][0][m][n][j] * rs, uu = acc[ai][1][m][n][j] * rs; v[n * 4 + j] = g * fast_rcp(1.0f + fast_exp2(-g * LOG2E)) * uu; }
;                 u32x4 w; w.x = pk2(v[0], v[1]); w.y = pk2(v[2], v[3]); w.z = pk2(v[4], v[5]); w.w = pk2(v[6], v[7]);
;                 *(u32x4*)dst = w;
;             }
	v_mad_i64_i32 v[38:39], s[0:1], v44, s17, v[140:141]
	v_mul_f32_e32 v37, 0xbfb8aa3b, v28
	v_exp_f32_e32 v37, v37
	s_nop 0
	v_add_f32_e32 v37, 1.0, v37
	v_rcp_f32_e32 v40, v37
	v_pk_mul_f32 v[20:21], v[20:21], v[36:37] op_sel_hi:[1,0]
	v_mul_f32_e32 v37, 0xbfb8aa3b, v29
	v_exp_f32_e32 v37, v37
	s_nop 0
	v_add_f32_e32 v37, 1.0, v37
	v_rcp_f32_e32 v41, v37
	v_pk_mul_f32 v[22:23], v[22:23], v[36:37] op_sel_hi:[1,0]
	v_pk_mul_f32 v[24:25], v[24:25], v[36:37] op_sel_hi:[1,0]
	v_pk_mul_f32 v[16:17], v[16:17], v[36:37] op_sel_hi:[1,0]
	v_pk_mul_f32 v[28:29], v[28:29], v[40:41]
	v_pk_mul_f32 v[18:19], v[18:19], v[36:37] op_sel_hi:[1,0]
	v_pk_mul_f32 v[20:21], v[20:21], v[28:29]
	v_pk_mul_f32 v[28:29], v[30:31], v[36:37] op_sel_hi:[1,0]
	s_nop 0
	v_mul_f32_e32 v30, 0xbfb8aa3b, v28
	v_mul_f32_e32 v31, 0xbfb8aa3b, v29
	v_exp_f32_e32 v30, v30
	v_exp_f32_e32 v31, v31
	v_add_f32_e32 v30, 1.0, v30
	v_add_f32_e32 v31, 1.0, v31
	v_rcp_f32_e32 v30, v30
	v_rcp_f32_e32 v31, v31
	s_nop 0
	v_pk_mul_f32 v[28:29], v[28:29], v[30:31]
	s_nop 0
	v_pk_mul_f32 v[22:23], v[22:23], v[28:29]
	v_mul_f32_e32 v28, 0xbfb8aa3b, v24
	v_mul_f32_e32 v29, 0xbfb8aa3b, v25
	v_exp_f32_e32 v28, v28
	v_exp_f32_e32 v29, v29
	v_add_f32_e32 v28, 1.0, v28
	v_add_f32_e32 v29, 1.0, v29
	v_rcp_f32_e32 v28, v28
	v_rcp_f32_e32 v29, v29
	s_nop 0
	v_pk_mul_f32 v[24:25], v[24:25], v[28:29]
	s_nop 0
	v_pk_mul_f32 v[24:25], v[16:17], v[24:25]
	v_pk_mul_f32 v[16:17], v[26:27], v[36:37] op_sel_hi:[1,0]
	v_lshl_add_u64 v[28:29], v[38:39], 0, v[124:125]
	v_mul_f32_e32 v26, 0xbfb8aa3b, v16
	v_mul_f32_e32 v27, 0xbfb8aa3b, v17
	v_exp_f32_e32 v26, v26
	v_exp_f32_e32 v27, v27
	v_add_f32_e32 v26, 1.0, v26
	v_add_f32_e32 v27, 1.0, v27
	v_rcp_f32_e32 v26, v26
	v_rcp_f32_e32 v27, v27
	s_nop 0
	v_pk_mul_f32 v[16:17], v[16:17], v[26:27]
	s_nop 0
	v_pk_mul_f32 v[26:27], v[18:19], v[16:17]
	v_cvt_pk_bf16_f32 v18, v24, v25
	v_add_u32_e32 v24, 0xb0, v142
	v_cvt_pk_bf16_f32 v16, v20, v21
	v_cvt_pk_bf16_f32 v17, v22, v23
	v_cvt_pk_bf16_f32 v19, v26, v27
	global_store_dwordx4 v[28:29], v[16:19], off
	s_nop 1
	v_mov_b32_e32 v16, v195
	v_pk_mul_f32 v[12:13], v[12:13], v[16:17] op_sel_hi:[1,0]
	v_mad_i64_i32 v[18:19], s[0:1], v24, s17, v[140:141]
	v_mul_f32_e32 v17, 0xbfb8aa3b, v12
	v_exp_f32_e32 v17, v17
	s_mov_b64 s[0:1], -1
	s_andn2_b64 vcc, exec, s[38:39]
	v_add_f32_e32 v17, 1.0, v17
	v_rcp_f32_e32 v20, v17
	v_pk_mul_f32 v[4:5], v[4:5], v[16:17] op_sel_hi:[1,0]
	v_mul_f32_e32 v17, 0xbfb8aa3b, v13
	v_exp_f32_e32 v17, v17
	s_nop 0
	v_add_f32_e32 v17, 1.0, v17
	v_rcp_f32_e32 v21, v17
	v_pk_mul_f32 v[6:7], v[6:7], v[16:17] op_sel_hi:[1,0]
	v_pk_mul_f32 v[8:9], v[8:9], v[16:17] op_sel_hi:[1,0]
	v_pk_mul_f32 v[0:1], v[0:1], v[16:17] op_sel_hi:[1,0]
	v_pk_mul_f32 v[12:13], v[12:13], v[20:21]
	v_pk_mul_f32 v[2:3], v[2:3], v[16:17] op_sel_hi:[1,0]
	v_pk_mul_f32 v[4:5], v[4:5], v[12:13]
	v_pk_mul_f32 v[12:13], v[14:15], v[16:17] op_sel_hi:[1,0]
	s_nop 0
	v_mul_f32_e32 v14, 0xbfb8aa3b, v12
	v_mul_f32_e32 v15, 0xbfb8aa3b, v13
	v_exp_f32_e32 v14, v14
	v_exp_f32_e32 v15, v15
	v_add_f32_e32 v14, 1.0, v14
	v_add_f32_e32 v15, 1.0, v15
	v_rcp_f32_e32 v14, v14
	v_rcp_f32_e32 v15, v15
	s_nop 0
	v_pk_mul_f32 v[12:13], v[12:13], v[14:15]
	s_nop 0
	v_pk_mul_f32 v[6:7], v[6:7], v[12:13]
	v_mul_f32_e32 v12, 0xbfb8aa3b, v8
	v_mul_f32_e32 v13, 0xbfb8aa3b, v9
	v_exp_f32_e32 v12, v12
	v_exp_f32_e32 v13, v13
	v_add_f32_e32 v12, 1.0, v12
	v_add_f32_e32 v13, 1.0, v13
	v_rcp_f32_e32 v12, v12
	v_rcp_f32_e32 v13, v13
	s_nop 0
	v_pk_mul_f32 v[8:9], v[8:9], v[12:13]
	s_nop 0
	v_pk_mul_f32 v[8:9], v[0:1], v[8:9]
	v_pk_mul_f32 v[0:1], v[10:11], v[16:17] op_sel_hi:[1,0]
	v_lshl_add_u64 v[12:13], v[18:19], 0, v[124:125]
	v_mul_f32_e32 v10, 0xbfb8aa3b, v0
	v_mul_f32_e32 v11, 0xbfb8aa3b, v1
	v_exp_f32_e32 v10, v10
	v_exp_f32_e32 v11, v11
	v_add_f32_e32 v10, 1.0, v10
	v_add_f32_e32 v11, 1.0, v11
	v_rcp_f32_e32 v10, v10
	v_rcp_f32_e32 v11, v11
	s_nop 0
	v_pk_mul_f32 v[0:1], v[0:1], v[10:11]
	s_nop 0
	v_pk_mul_f32 v[10:11], v[2:3], v[0:1]
	v_cvt_pk_bf16_f32 v0, v4, v5
	v_cvt_pk_bf16_f32 v1, v6, v7
	v_cvt_pk_bf16_f32 v2, v8, v9
	v_cvt_pk_bf16_f32 v3, v10, v11
	global_store_dwordx4 v[12:13], v[0:3], off
	s_cbranch_vccnz .LBB0_619
	s_andn2_b64 vcc, exec, s[4:5]
	s_cbranch_vccnz .LBB0_618
	s_barrier
	s_branch .LBB0_618
